# stack: U-sweep pipelined + topk base+imm addressing and single candidate pass + canonicalize removal + sort/prep flat->ds and next-token prefetch + V sweep vmcnt 11
# speedup vs baseline: 1.0337x; 1.0203x over previous
.LBB0_20:
	v_mov_b32_e32 v119, v0
	s_barrier
	v_writelane_b32 v254, s16, 34
	v_readfirstlane_b32 s0, v119
	s_ashr_i32 s0, s0, 6
	s_lshl_b32 s38, s0, 1
	v_readlane_b32 s1, v254, 60
	v_bfe_u32 v6, v119, 5, 1
	s_add_i32 s40, s38, s1
	v_readlane_b32 s10, v254, 62
	s_lshl_b32 s1, s0, 12
	s_lshl_b32 s0, s0, 4
	s_lshl_b32 s42, s16, 6
	v_lshlrev_b32_e32 v2, 4, v6
	v_mov_b32_e32 v3, v155
	v_readlane_b32 s11, v254, 63
	s_add_i32 s43, s57, s1
	s_ashr_i32 s1, s0, 31
	s_ashr_i32 s20, s42, 31
	v_lshl_add_u64 v[4:5], s[10:11], 0, v[2:3]
	s_lshl_b64 s[10:11], s[0:1], 2
	s_add_u32 s0, s24, s10
	s_addc_u32 s1, s25, s11
	s_add_u32 s14, s26, s10
	s_addc_u32 s15, s27, s11
	s_or_b32 s18, s38, 1
	s_ashr_i32 s19, s18, 31
	s_ashr_i32 s39, s38, 31
	s_lshl_b64 s[18:19], s[18:19], 21
	v_and_b32_e32 v1, 31, v119
	s_lshl_b64 s[16:17], s[38:39], 21
	v_lshl_add_u64 v[64:65], v[4:5], 0, s[18:19]
	v_readlane_b32 s18, v255, 0
	v_lshlrev_b32_e32 v154, 7, v1
	v_lshl_add_u64 v[62:63], v[4:5], 0, s[16:17]
	s_or_b32 s16, s40, 1
	v_readlane_b32 s19, v255, 1
	s_ashr_i32 s41, s40, 31
	s_ashr_i32 s17, s16, 31
	v_lshl_add_u64 v[4:5], s[18:19], 0, v[154:155]
	v_cmp_lt_i32_e32 vcc, v215, v216
	s_lshl_b64 s[10:11], s[40:41], 14
	s_lshl_b64 s[16:17], s[16:17], 14
	v_lshl_add_u64 v[2:3], v[4:5], 0, v[2:3]
	v_lshlrev_b32_e32 v120, 2, v6
	v_cndmask_b32_e32 v7, v214, v215, vcc
	v_lshl_add_u64 v[66:67], v[2:3], 0, s[10:11]
	s_mov_b64 s[10:11], 0x1060
	s_mov_b64 s[18:19], 0x1000
	s_mov_b64 s[30:31], 0x1040
	s_mov_b64 s[34:35], 0x1020
	s_mov_b64 s[36:37], 0x2060
	s_mov_b64 s[38:39], 0x2000
	s_mov_b64 s[40:41], 0x2040
	s_mov_b64 s[44:45], 0x2020
	s_mov_b64 s[46:47], 0x3060
	s_mov_b64 s[48:49], 0x3000
	s_mov_b64 s[50:51], 0x3040
	s_mov_b64 s[52:53], 0x3020
	v_lshl_add_u64 v[90:91], v[2:3], 0, s[16:17]
	v_lshlrev_b32_e32 v121, 2, v7
	v_cmp_eq_u32_e64 s[12:13], 0, v6
	v_or_b32_e32 v122, 1, v120
	v_or_b32_e32 v123, 2, v120
	v_or_b32_e32 v124, 3, v120
	v_or_b32_e32 v125, 8, v120
	v_or_b32_e32 v126, 9, v120
	v_or_b32_e32 v127, 10, v120
	v_or_b32_e32 v128, 11, v120
	v_or_b32_e32 v129, 16, v120
	v_or_b32_e32 v136, 17, v120
	v_or_b32_e32 v137, 18, v120
	v_or_b32_e32 v138, 19, v120
	v_or_b32_e32 v139, 24, v120
	v_or_b32_e32 v140, 25, v120
	v_or_b32_e32 v141, 26, v120
	v_or_b32_e32 v142, 27, v120
	v_or_b32_e32 v143, 32, v120
	v_or_b32_e32 v144, 33, v120
	v_or_b32_e32 v145, 34, v120
	v_or_b32_e32 v146, 35, v120
	v_or_b32_e32 v147, 40, v120
	v_or_b32_e32 v148, 41, v120
	v_or_b32_e32 v149, 42, v120
	v_or_b32_e32 v150, 43, v120
	v_or_b32_e32 v151, 48, v120
	v_or_b32_e32 v152, 49, v120
	v_or_b32_e32 v153, 50, v120
	v_or_b32_e32 v160, 51, v120
	v_or_b32_e32 v161, 56, v120
	v_or_b32_e32 v162, 57, v120
	v_or_b32_e32 v163, 58, v120
	v_or_b32_e32 v164, 59, v120
	v_or_b32_e32 v165, 64, v120
	v_or_b32_e32 v166, 0x41, v120
	v_or_b32_e32 v167, 0x42, v120
	v_or_b32_e32 v168, 0x43, v120
	v_or_b32_e32 v169, 0x48, v120
	v_or_b32_e32 v170, 0x49, v120
	v_or_b32_e32 v171, 0x4a, v120
	v_or_b32_e32 v172, 0x4b, v120
	v_or_b32_e32 v173, 0x50, v120
	v_or_b32_e32 v174, 0x51, v120
	v_or_b32_e32 v175, 0x52, v120
	v_or_b32_e32 v184, 0x53, v120
	v_or_b32_e32 v185, 0x58, v120
	v_or_b32_e32 v186, 0x59, v120
	v_or_b32_e32 v187, 0x5a, v120
	v_or_b32_e32 v188, 0x5b, v120
	v_or_b32_e32 v189, 0x60, v120
	v_or_b32_e32 v190, 0x61, v120
	v_or_b32_e32 v191, 0x62, v120
	v_or_b32_e32 v192, 0x63, v120
	v_or_b32_e32 v193, 0x68, v120
	v_or_b32_e32 v194, 0x69, v120
	v_or_b32_e32 v195, 0x6a, v120
	v_or_b32_e32 v196, 0x6b, v120
	v_or_b32_e32 v197, 0x70, v120
	v_or_b32_e32 v198, 0x71, v120
	v_or_b32_e32 v199, 0x72, v120
	v_or_b32_e32 v200, 0x73, v120
	v_or_b32_e32 v201, 0x78, v120
	v_or_b32_e32 v202, 0x79, v120
	v_or_b32_e32 v203, 0x7a, v120
	v_or_b32_e32 v204, 0x7b, v120
	v_lshl_add_u64 v[68:69], v[66:67], 0, s[18:19]
	v_lshl_add_u64 v[70:71], v[66:67], 0, s[38:39]
	v_lshl_add_u64 v[72:73], v[66:67], 0, s[48:49]
	v_lshl_add_u64 v[92:93], v[90:91], 0, s[18:19]
	v_lshl_add_u64 v[94:95], v[90:91], 0, s[38:39]
	v_lshl_add_u64 v[96:97], v[90:91], 0, s[48:49]
	v_or_b32_e32 v118, s42, v1
	v_mov_b32_e32 v1, s20
	s_mov_b64 s[38:39], -1
	s_mov_b32 s44, 0
	s_branch .LBB0_22

.LBB0_22:
	v_or_b32_e32 v2, s44, v118
	v_mov_b32_e32 v3, v1
	v_lshlrev_b64 v[46:47], 7, v[2:3]
	v_lshl_add_u64 v[2:3], v[62:63], 0, v[46:47]
	global_load_dwordx4 v[30:33], v[2:3], off
	global_load_dwordx4 v[26:29], v[2:3], off offset:32
	global_load_dwordx4 v[22:25], v[2:3], off offset:64
	global_load_dwordx4 v[18:21], v[2:3], off offset:96
	s_nop 0
	global_load_dwordx4 v[2:5], v[66:67], off
	global_load_dwordx4 v[34:37], v[66:67], off offset:32
	global_load_dwordx4 v[38:41], v[66:67], off offset:64
	global_load_dwordx4 v[42:45], v[66:67], off offset:96
	s_waitcnt vmcnt(0)
	v_mfma_f32_32x32x16_bf16 v[2:17], v[2:5], v[30:33], 0
	s_waitcnt vmcnt(2)
	v_mfma_f32_32x32x16_bf16 v[2:17], v[34:37], v[26:29], v[2:17]
	s_waitcnt vmcnt(1)
	v_mfma_f32_32x32x16_bf16 v[2:17], v[38:41], v[22:25], v[2:17]
	s_waitcnt vmcnt(0)
	v_mfma_f32_32x32x16_bf16 v[2:17], v[42:45], v[18:21], v[2:17]
	s_nop 11
	v_and_or_b32 v2, v2, s33, v120
	v_and_or_b32 v3, v3, s33, v122
	v_and_or_b32 v4, v4, s33, v123
	v_and_or_b32 v5, v5, s33, v124
	v_and_or_b32 v6, v6, s33, v125
	v_and_or_b32 v7, v7, s33, v126
	v_and_or_b32 v8, v8, s33, v127
	v_and_or_b32 v9, v9, s33, v128
	v_and_or_b32 v10, v10, s33, v129
	v_and_or_b32 v11, v11, s33, v136
	v_and_or_b32 v12, v12, s33, v137
	v_and_or_b32 v13, v13, s33, v138
	v_and_or_b32 v14, v14, s33, v139
	v_and_or_b32 v15, v15, s33, v140
	v_and_or_b32 v16, v16, s33, v141
	v_and_or_b32 v17, v17, s33, v142
	v_max_f32_e32 v34, v2, v3
	v_min_f32_e32 v35, v4, v5
	v_min_f32_e32 v2, v2, v3
	v_max_f32_e32 v3, v4, v5
	v_max_f32_e32 v37, v6, v7
	v_min_f32_e32 v38, v8, v9
	v_min_f32_e32 v6, v6, v7
	v_max_f32_e32 v7, v8, v9
	v_max_f32_e32 v41, v10, v11
	v_min_f32_e32 v42, v12, v13
	v_min_f32_e32 v10, v10, v11
	v_max_f32_e32 v11, v12, v13
	v_max_f32_e32 v44, v14, v15
	v_min_f32_e32 v45, v16, v17
	v_min_f32_e32 v14, v14, v15
	v_max_f32_e32 v15, v16, v17
	v_max_f32_e32 v36, v34, v35
	v_max_f32_e32 v4, v2, v3
	v_min_f32_e32 v39, v37, v38
	v_min_f32_e32 v8, v6, v7
	v_min_f32_e32 v34, v34, v35
	v_min_f32_e32 v2, v2, v3
	v_max_f32_e32 v35, v37, v38
	v_max_f32_e32 v6, v6, v7
	v_max_f32_e32 v43, v41, v42
	v_max_f32_e32 v12, v10, v11
	v_min_f32_e32 v48, v44, v45
	v_min_f32_e32 v16, v14, v15
	v_min_f32_e32 v41, v41, v42
	v_min_f32_e32 v10, v10, v11
	v_max_f32_e32 v42, v44, v45
	v_max_f32_e32 v14, v14, v15
	v_max_f32_e32 v5, v36, v4
	v_min_f32_e32 v9, v39, v8
	v_max_f32_e32 v3, v34, v2
	v_min_f32_e32 v7, v35, v6
	v_min_f32_e32 v4, v36, v4
	v_max_f32_e32 v8, v39, v8
	v_min_f32_e32 v2, v34, v2
	v_max_f32_e32 v6, v35, v6
	v_max_f32_e32 v13, v43, v12
	v_min_f32_e32 v17, v48, v16
	v_max_f32_e32 v11, v41, v10
	v_min_f32_e32 v15, v42, v14
	v_min_f32_e32 v12, v43, v12
	v_max_f32_e32 v16, v48, v16
	v_min_f32_e32 v10, v41, v10
	v_max_f32_e32 v14, v42, v14
	v_max_f32_e32 v40, v5, v9
	v_max_f32_e32 v37, v3, v7
	v_max_f32_e32 v36, v4, v8
	v_max_f32_e32 v34, v2, v6
	v_min_f32_e32 v49, v13, v17
	v_min_f32_e32 v44, v11, v15
	v_min_f32_e32 v43, v12, v16
	v_min_f32_e32 v41, v10, v14
	v_min_f32_e32 v5, v5, v9
	v_min_f32_e32 v3, v3, v7
	v_min_f32_e32 v4, v4, v8
	v_min_f32_e32 v2, v2, v6
	v_max_f32_e32 v9, v13, v17
	v_max_f32_e32 v11, v11, v15
	v_max_f32_e32 v12, v12, v16
	v_max_f32_e32 v10, v10, v14
	v_max_f32_e32 v38, v40, v37
	v_max_f32_e32 v35, v36, v34
	v_min_f32_e32 v45, v49, v44
	v_min_f32_e32 v42, v43, v41
	v_max_f32_e32 v7, v5, v3
	v_max_f32_e32 v6, v4, v2
	v_min_f32_e32 v13, v9, v11
	v_min_f32_e32 v14, v12, v10
	v_min_f32_e32 v37, v40, v37
	v_min_f32_e32 v34, v36, v34
	v_max_f32_e32 v40, v49, v44
	v_max_f32_e32 v41, v43, v41
	v_min_f32_e32 v3, v5, v3
	v_min_f32_e32 v2, v4, v2
	v_max_f32_e32 v5, v9, v11
	v_max_f32_e32 v9, v12, v10
	v_max_f32_e32 v39, v38, v35
	v_min_f32_e32 v60, v45, v42
	v_max_f32_e32 v8, v7, v6
	v_min_f32_e32 v15, v13, v14
	v_max_f32_e32 v36, v37, v34
	v_min_f32_e32 v43, v40, v41
	v_max_f32_e32 v4, v3, v2
	v_min_f32_e32 v10, v5, v9
	v_min_f32_e32 v54, v39, v60
	v_min_f32_e32 v16, v8, v15
	v_min_f32_e32 v44, v36, v43
	v_min_f32_e32 v11, v4, v10
	v_min_f32_e32 v35, v38, v35
	v_max_f32_e32 v38, v45, v42
	v_min_f32_e32 v6, v7, v6
	v_max_f32_e32 v7, v13, v14
	v_min_f32_e32 v34, v37, v34
	v_max_f32_e32 v37, v40, v41
	v_min_f32_e32 v2, v3, v2
	v_max_f32_e32 v3, v5, v9
	v_min_f32_e32 v17, v54, v16
	v_min_f32_e32 v12, v44, v11
	v_min_f32_e32 v42, v35, v38
	v_min_f32_e32 v13, v6, v7
	v_min_f32_e32 v40, v34, v37
	v_min_f32_e32 v5, v2, v3
	v_min_f32_e32 v48, v17, v12
	v_min_f32_e32 v14, v42, v13
	v_min_f32_e32 v9, v40, v5
	v_max_f32_e32 v51, v17, v12
	v_max_f32_e32 v12, v42, v13
	v_max_f32_e32 v5, v40, v5
	v_min_f32_e32 v49, v14, v9
	v_max_f32_e32 v52, v14, v9
	v_max_f32_e32 v9, v54, v16
	v_max_f32_e32 v11, v44, v11
	v_min_f32_e32 v55, v12, v5
	v_max_f32_e32 v58, v12, v5
	v_max_f32_e32 v12, v35, v38
	v_max_f32_e32 v6, v6, v7
	v_max_f32_e32 v13, v34, v37
	v_max_f32_e32 v2, v2, v3
	v_min_f32_e32 v54, v9, v11
	v_max_f32_e32 v57, v9, v11
	v_max_f32_e32 v5, v39, v60
	v_max_f32_e32 v8, v8, v15
	v_max_f32_e32 v11, v36, v43
	v_max_f32_e32 v4, v4, v10
	v_min_f32_e32 v7, v12, v6
	v_min_f32_e32 v3, v13, v2
	v_min_f32_e32 v9, v5, v8
	v_min_f32_e32 v10, v11, v4
	v_min_f32_e32 v61, v7, v3
	v_max_f32_e32 v206, v7, v3
	v_max_f32_e32 v3, v5, v8
	v_max_f32_e32 v4, v11, v4
	v_max_f32_e32 v5, v12, v6
	v_max_f32_e32 v2, v13, v2
	v_min_f32_e32 v227, v3, v4
	v_min_f32_e32 v228, v5, v2
	v_max_f32_e32 v230, v3, v4
	v_max_f32_e32 v231, v5, v2
	global_load_dwordx4 v[34:37], v[68:69], off offset:96
	global_load_dwordx4 v[38:41], v[68:69], off offset:64
	global_load_dwordx4 v[42:45], v[68:69], off offset:32
	global_load_dwordx4 v[2:5], v[68:69], off
	v_min_f32_e32 v60, v9, v10
	v_max_f32_e32 v205, v9, v10
	s_waitcnt vmcnt(0)
	v_mfma_f32_32x32x16_bf16 v[2:17], v[2:5], v[30:33], 0
	v_min_f32_e32 v50, v48, v49
	v_min_f32_e32 v53, v51, v52
	v_min_f32_e32 v56, v54, v55
	v_min_f32_e32 v59, v57, v58
	v_min_f32_e32 v154, v60, v61
	v_min_f32_e32 v207, v205, v206
	v_min_f32_e32 v229, v227, v228
	v_mfma_f32_32x32x16_bf16 v[2:17], v[42:45], v[26:29], v[2:17]
	v_min_f32_e32 v232, v230, v231
	v_mfma_f32_32x32x16_bf16 v[2:17], v[38:41], v[22:25], v[2:17]
	v_mfma_f32_32x32x16_bf16 v[2:17], v[34:37], v[18:21], v[2:17]
	s_nop 11
	v_and_or_b32 v2, v2, s33, v143
	v_and_or_b32 v3, v3, s33, v144
	v_and_or_b32 v4, v4, s33, v145
	v_and_or_b32 v5, v5, s33, v146
	v_and_or_b32 v6, v6, s33, v147
	v_and_or_b32 v7, v7, s33, v148
	v_and_or_b32 v8, v8, s33, v149
	v_and_or_b32 v9, v9, s33, v150
	v_and_or_b32 v10, v10, s33, v151
	v_and_or_b32 v11, v11, s33, v152
	v_and_or_b32 v12, v12, s33, v153
	v_and_or_b32 v13, v13, s33, v160
	v_and_or_b32 v14, v14, s33, v161
	v_and_or_b32 v15, v15, s33, v162
	v_and_or_b32 v16, v16, s33, v163
	v_and_or_b32 v17, v17, s33, v164
	v_max_f32_e32 v34, v2, v3
	v_min_f32_e32 v35, v4, v5
	v_min_f32_e32 v2, v2, v3
	v_max_f32_e32 v3, v4, v5
	v_max_f32_e32 v37, v6, v7
	v_min_f32_e32 v38, v8, v9
	v_min_f32_e32 v6, v6, v7
	v_max_f32_e32 v7, v8, v9
	v_max_f32_e32 v41, v10, v11
	v_min_f32_e32 v42, v12, v13
	v_min_f32_e32 v10, v10, v11
	v_max_f32_e32 v11, v12, v13
	v_max_f32_e32 v44, v14, v15
	v_min_f32_e32 v45, v16, v17
	v_min_f32_e32 v14, v14, v15
	v_max_f32_e32 v15, v16, v17
	v_max_f32_e32 v36, v34, v35
	v_max_f32_e32 v4, v2, v3
	v_min_f32_e32 v39, v37, v38
	v_min_f32_e32 v8, v6, v7
	v_min_f32_e32 v34, v34, v35
	v_min_f32_e32 v2, v2, v3
	v_max_f32_e32 v35, v37, v38
	v_max_f32_e32 v6, v6, v7
	v_max_f32_e32 v43, v41, v42
	v_max_f32_e32 v12, v10, v11
	v_min_f32_e32 v233, v44, v45
	v_min_f32_e32 v16, v14, v15
	v_min_f32_e32 v41, v41, v42
	v_min_f32_e32 v10, v10, v11
	v_max_f32_e32 v42, v44, v45
	v_max_f32_e32 v14, v14, v15
	v_max_f32_e32 v5, v36, v4
	v_min_f32_e32 v9, v39, v8
	v_max_f32_e32 v3, v34, v2
	v_min_f32_e32 v7, v35, v6
	v_min_f32_e32 v4, v36, v4
	v_max_f32_e32 v8, v39, v8
	v_min_f32_e32 v2, v34, v2
	v_max_f32_e32 v6, v35, v6
	v_max_f32_e32 v13, v43, v12
	v_min_f32_e32 v17, v233, v16
	v_max_f32_e32 v11, v41, v10
	v_min_f32_e32 v15, v42, v14
	v_min_f32_e32 v12, v43, v12
	v_max_f32_e32 v16, v233, v16
	v_min_f32_e32 v10, v41, v10
	v_max_f32_e32 v14, v42, v14
	v_max_f32_e32 v40, v5, v9
	v_max_f32_e32 v37, v3, v7
	v_max_f32_e32 v36, v4, v8
	v_max_f32_e32 v34, v2, v6
	v_min_f32_e32 v234, v13, v17
	v_min_f32_e32 v44, v11, v15
	v_min_f32_e32 v43, v12, v16
	v_min_f32_e32 v41, v10, v14
	v_min_f32_e32 v5, v5, v9
	v_min_f32_e32 v3, v3, v7
	v_min_f32_e32 v4, v4, v8
	v_min_f32_e32 v2, v2, v6
	v_max_f32_e32 v9, v13, v17
	v_max_f32_e32 v11, v11, v15
	v_max_f32_e32 v12, v12, v16
	v_max_f32_e32 v10, v10, v14
	v_max_f32_e32 v38, v40, v37
	v_max_f32_e32 v35, v36, v34
	v_min_f32_e32 v45, v234, v44
	v_min_f32_e32 v42, v43, v41
	v_max_f32_e32 v7, v5, v3
	v_max_f32_e32 v6, v4, v2
	v_min_f32_e32 v13, v9, v11
	v_min_f32_e32 v14, v12, v10
	v_min_f32_e32 v37, v40, v37
	v_min_f32_e32 v34, v36, v34
	v_max_f32_e32 v40, v234, v44
	v_max_f32_e32 v41, v43, v41
	v_min_f32_e32 v3, v5, v3
	v_min_f32_e32 v2, v4, v2
	v_max_f32_e32 v5, v9, v11
	v_max_f32_e32 v9, v12, v10
	v_max_f32_e32 v39, v38, v35
	v_min_f32_e32 v233, v45, v42
	v_max_f32_e32 v8, v7, v6
	v_min_f32_e32 v15, v13, v14
	v_max_f32_e32 v36, v37, v34
	v_min_f32_e32 v43, v40, v41
	v_max_f32_e32 v4, v3, v2
	v_min_f32_e32 v10, v5, v9
	v_min_f32_e32 v235, v39, v233
	v_min_f32_e32 v16, v8, v15
	v_min_f32_e32 v44, v36, v43
	v_min_f32_e32 v11, v4, v10
	v_min_f32_e32 v17, v235, v16
	v_min_f32_e32 v12, v44, v11
	v_min_f32_e32 v35, v38, v35
	v_max_f32_e32 v38, v45, v42
	v_min_f32_e32 v6, v7, v6
	v_max_f32_e32 v7, v13, v14
	v_min_f32_e32 v34, v37, v34
	v_max_f32_e32 v37, v40, v41
	v_min_f32_e32 v2, v3, v2
	v_max_f32_e32 v3, v5, v9
	v_max_f32_e32 v16, v235, v16
	v_max_f32_e32 v11, v44, v11
	v_min_f32_e32 v234, v17, v12
	v_min_f32_e32 v42, v35, v38
	v_min_f32_e32 v13, v6, v7
	v_min_f32_e32 v40, v34, v37
	v_min_f32_e32 v5, v2, v3
	v_max_f32_e32 v12, v17, v12
	v_min_f32_e32 v17, v16, v11
	v_max_f32_e32 v11, v16, v11
	v_max_f32_e32 v16, v39, v233
	v_max_f32_e32 v8, v8, v15
	v_max_f32_e32 v36, v36, v43
	v_max_f32_e32 v4, v4, v10
	v_max_f32_e32 v35, v35, v38
	v_max_f32_e32 v6, v6, v7
	v_max_f32_e32 v34, v34, v37
	v_max_f32_e32 v2, v2, v3
	v_min_f32_e32 v14, v42, v13
	v_min_f32_e32 v9, v40, v5
	v_max_f32_e32 v13, v42, v13
	v_max_f32_e32 v5, v40, v5
	v_min_f32_e32 v15, v16, v8
	v_min_f32_e32 v10, v36, v4
	v_min_f32_e32 v7, v35, v6
	v_min_f32_e32 v3, v34, v2
	v_max_f32_e32 v8, v16, v8
	v_max_f32_e32 v4, v36, v4
	v_max_f32_e32 v6, v35, v6
	v_max_f32_e32 v2, v34, v2
	v_min_f32_e32 v41, v14, v9
	v_max_f32_e32 v9, v14, v9
	v_min_f32_e32 v40, v13, v5
	v_max_f32_e32 v5, v13, v5
	v_min_f32_e32 v39, v15, v10
	v_min_f32_e32 v37, v7, v3
	v_max_f32_e32 v10, v15, v10
	v_max_f32_e32 v3, v7, v3
	v_min_f32_e32 v15, v8, v4
	v_min_f32_e32 v16, v6, v2
	v_max_f32_e32 v4, v8, v4
	v_max_f32_e32 v2, v6, v2
	v_min_f32_e32 v45, v234, v41
	v_min_f32_e32 v14, v12, v9
	v_min_f32_e32 v42, v17, v40
	v_min_f32_e32 v13, v11, v5
	v_min_f32_e32 v38, v39, v37
	v_min_f32_e32 v7, v10, v3
	v_min_f32_e32 v34, v15, v16
	v_min_f32_e32 v6, v4, v2
	v_max3_f32 v8, v230, v231, v45
	v_max3_f32 v35, v232, v234, v41
	v_max3_f32 v14, v227, v228, v14
	v_max3_f32 v9, v229, v12, v9
	v_max3_f32 v12, v205, v206, v42
	v_max3_f32 v17, v207, v17, v40
	v_max3_f32 v13, v60, v61, v13
	v_max3_f32 v5, v154, v11, v5
	v_max3_f32 v11, v57, v58, v38
	v_max3_f32 v36, v59, v39, v37
	v_max3_f32 v7, v54, v55, v7
	v_max3_f32 v3, v56, v10, v3
	v_max3_f32 v10, v51, v52, v34
	v_max3_f32 v15, v53, v15, v16
	v_max3_f32 v6, v48, v49, v6
	v_max3_f32 v2, v50, v4, v2
	v_max_f32_e32 v4, v8, v11
	v_min_f32_e32 v8, v8, v11
	v_max_f32_e32 v11, v35, v36
	v_min_f32_e32 v16, v35, v36
	v_max_f32_e32 v34, v14, v7
	v_min_f32_e32 v7, v14, v7
	v_max_f32_e32 v14, v9, v3
	v_min_f32_e32 v3, v9, v3
	v_max_f32_e32 v9, v12, v10
	v_min_f32_e32 v10, v12, v10
	v_max_f32_e32 v12, v17, v15
	v_min_f32_e32 v15, v17, v15
	v_max_f32_e32 v17, v13, v6
	v_min_f32_e32 v6, v13, v6
	v_max_f32_e32 v13, v5, v2
	v_min_f32_e32 v2, v5, v2
	v_max_f32_e32 v5, v4, v9
	v_min_f32_e32 v4, v4, v9
	v_max_f32_e32 v9, v11, v12
	v_min_f32_e32 v11, v11, v12
	v_max_f32_e32 v12, v34, v17
	v_min_f32_e32 v17, v34, v17
	v_max_f32_e32 v34, v14, v13
	v_min_f32_e32 v13, v14, v13
	v_max_f32_e32 v14, v8, v10
	v_min_f32_e32 v8, v8, v10
	v_max_f32_e32 v10, v16, v15
	v_min_f32_e32 v15, v16, v15
	v_max_f32_e32 v16, v7, v6
	v_min_f32_e32 v6, v7, v6
	v_max_f32_e32 v7, v3, v2
	v_min_f32_e32 v2, v3, v2
	v_max_f32_e32 v52, v5, v12
	v_min_f32_e32 v48, v5, v12
	v_max_f32_e32 v60, v9, v34
	v_min_f32_e32 v56, v9, v34
	v_max_f32_e32 v53, v4, v17
	v_min_f32_e32 v49, v4, v17
	v_max_f32_e32 v205, v15, v2
	v_min_f32_e32 v59, v15, v2
	global_load_dwordx4 v[34:37], v[70:71], off offset:96
	global_load_dwordx4 v[38:41], v[70:71], off offset:64
	global_load_dwordx4 v[42:45], v[70:71], off offset:32
	global_load_dwordx4 v[2:5], v[70:71], off
	v_max_f32_e32 v61, v11, v13
	v_min_f32_e32 v57, v11, v13
	v_max_f32_e32 v54, v14, v16
	v_min_f32_e32 v50, v14, v16
	v_max_f32_e32 v154, v10, v7
	v_min_f32_e32 v58, v10, v7
	v_max_f32_e32 v55, v8, v6
	v_min_f32_e32 v51, v8, v6
	s_waitcnt vmcnt(0)
	v_mfma_f32_32x32x16_bf16 v[2:17], v[2:5], v[30:33], 0
	v_min_f32_e32 v232, v52, v60
	v_min_f32_e32 v231, v48, v56
	v_min_f32_e32 v230, v53, v61
	v_min_f32_e32 v229, v49, v57
	v_min_f32_e32 v228, v54, v154
	v_min_f32_e32 v227, v50, v58
	v_min_f32_e32 v207, v55, v205
	v_mfma_f32_32x32x16_bf16 v[2:17], v[42:45], v[26:29], v[2:17]
	v_min_f32_e32 v206, v51, v59
	v_mfma_f32_32x32x16_bf16 v[2:17], v[38:41], v[22:25], v[2:17]
	v_mfma_f32_32x32x16_bf16 v[2:17], v[34:37], v[18:21], v[2:17]
	s_nop 11
	v_and_or_b32 v2, v2, s33, v165
	v_and_or_b32 v3, v3, s33, v166
	v_and_or_b32 v4, v4, s33, v167
	v_and_or_b32 v5, v5, s33, v168
	v_and_or_b32 v6, v6, s33, v169
	v_and_or_b32 v7, v7, s33, v170
	v_and_or_b32 v8, v8, s33, v171
	v_and_or_b32 v9, v9, s33, v172
	v_and_or_b32 v10, v10, s33, v173
	v_and_or_b32 v11, v11, s33, v174
	v_and_or_b32 v12, v12, s33, v175
	v_and_or_b32 v13, v13, s33, v184
	v_and_or_b32 v14, v14, s33, v185
	v_and_or_b32 v15, v15, s33, v186
	v_and_or_b32 v16, v16, s33, v187
	v_and_or_b32 v17, v17, s33, v188
	v_max_f32_e32 v34, v2, v3
	v_min_f32_e32 v35, v4, v5
	v_min_f32_e32 v2, v2, v3
	v_max_f32_e32 v3, v4, v5
	v_max_f32_e32 v37, v6, v7
	v_min_f32_e32 v38, v8, v9
	v_min_f32_e32 v6, v6, v7
	v_max_f32_e32 v7, v8, v9
	v_max_f32_e32 v41, v10, v11
	v_min_f32_e32 v42, v12, v13
	v_min_f32_e32 v10, v10, v11
	v_max_f32_e32 v11, v12, v13
	v_max_f32_e32 v44, v14, v15
	v_min_f32_e32 v45, v16, v17
	v_min_f32_e32 v14, v14, v15
	v_max_f32_e32 v15, v16, v17
	v_max_f32_e32 v36, v34, v35
	v_max_f32_e32 v4, v2, v3
	v_min_f32_e32 v39, v37, v38
	v_min_f32_e32 v8, v6, v7
	v_min_f32_e32 v34, v34, v35
	v_min_f32_e32 v2, v2, v3
	v_max_f32_e32 v35, v37, v38
	v_max_f32_e32 v6, v6, v7
	v_max_f32_e32 v43, v41, v42
	v_max_f32_e32 v12, v10, v11
	v_min_f32_e32 v233, v44, v45
	v_min_f32_e32 v16, v14, v15
	v_min_f32_e32 v41, v41, v42
	v_min_f32_e32 v10, v10, v11
	v_max_f32_e32 v42, v44, v45
	v_max_f32_e32 v14, v14, v15
	v_max_f32_e32 v5, v36, v4
	v_min_f32_e32 v9, v39, v8
	v_max_f32_e32 v3, v34, v2
	v_min_f32_e32 v7, v35, v6
	v_min_f32_e32 v4, v36, v4
	v_max_f32_e32 v8, v39, v8
	v_min_f32_e32 v2, v34, v2
	v_max_f32_e32 v6, v35, v6
	v_max_f32_e32 v13, v43, v12
	v_min_f32_e32 v17, v233, v16
	v_max_f32_e32 v11, v41, v10
	v_min_f32_e32 v15, v42, v14
	v_min_f32_e32 v12, v43, v12
	v_max_f32_e32 v16, v233, v16
	v_min_f32_e32 v10, v41, v10
	v_max_f32_e32 v14, v42, v14
	v_max_f32_e32 v40, v5, v9
	v_max_f32_e32 v37, v3, v7
	v_max_f32_e32 v36, v4, v8
	v_max_f32_e32 v34, v2, v6
	v_min_f32_e32 v234, v13, v17
	v_min_f32_e32 v44, v11, v15
	v_min_f32_e32 v43, v12, v16
	v_min_f32_e32 v41, v10, v14
	v_min_f32_e32 v5, v5, v9
	v_min_f32_e32 v3, v3, v7
	v_min_f32_e32 v4, v4, v8
	v_min_f32_e32 v2, v2, v6
	v_max_f32_e32 v9, v13, v17
	v_max_f32_e32 v11, v11, v15
	v_max_f32_e32 v12, v12, v16
	v_max_f32_e32 v10, v10, v14
	v_max_f32_e32 v38, v40, v37
	v_max_f32_e32 v35, v36, v34
	v_min_f32_e32 v45, v234, v44
	v_min_f32_e32 v42, v43, v41
	v_max_f32_e32 v7, v5, v3
	v_max_f32_e32 v6, v4, v2
	v_min_f32_e32 v13, v9, v11
	v_min_f32_e32 v14, v12, v10
	v_min_f32_e32 v37, v40, v37
	v_min_f32_e32 v34, v36, v34
	v_max_f32_e32 v40, v234, v44
	v_max_f32_e32 v41, v43, v41
	v_min_f32_e32 v3, v5, v3
	v_min_f32_e32 v2, v4, v2
	v_max_f32_e32 v5, v9, v11
	v_max_f32_e32 v9, v12, v10
	v_max_f32_e32 v39, v38, v35
	v_min_f32_e32 v233, v45, v42
	v_max_f32_e32 v8, v7, v6
	v_min_f32_e32 v15, v13, v14
	v_max_f32_e32 v36, v37, v34
	v_min_f32_e32 v43, v40, v41
	v_max_f32_e32 v4, v3, v2
	v_min_f32_e32 v10, v5, v9
	v_min_f32_e32 v235, v39, v233
	v_min_f32_e32 v16, v8, v15
	v_min_f32_e32 v44, v36, v43
	v_min_f32_e32 v11, v4, v10
	v_min_f32_e32 v17, v235, v16
	v_min_f32_e32 v12, v44, v11
	v_min_f32_e32 v35, v38, v35
	v_max_f32_e32 v38, v45, v42
	v_min_f32_e32 v6, v7, v6
	v_max_f32_e32 v7, v13, v14
	v_min_f32_e32 v34, v37, v34
	v_max_f32_e32 v37, v40, v41
	v_min_f32_e32 v2, v3, v2
	v_max_f32_e32 v3, v5, v9
	v_max_f32_e32 v16, v235, v16
	v_max_f32_e32 v11, v44, v11
	v_min_f32_e32 v234, v17, v12
	v_min_f32_e32 v42, v35, v38
	v_min_f32_e32 v13, v6, v7
	v_min_f32_e32 v40, v34, v37
	v_min_f32_e32 v5, v2, v3
	v_max_f32_e32 v12, v17, v12
	v_min_f32_e32 v17, v16, v11
	v_max_f32_e32 v11, v16, v11
	v_max_f32_e32 v16, v39, v233
	v_max_f32_e32 v8, v8, v15
	v_max_f32_e32 v36, v36, v43
	v_max_f32_e32 v4, v4, v10
	v_max_f32_e32 v35, v35, v38
	v_max_f32_e32 v6, v6, v7
	v_max_f32_e32 v34, v34, v37
	v_max_f32_e32 v2, v2, v3
	v_min_f32_e32 v14, v42, v13
	v_min_f32_e32 v9, v40, v5
	v_max_f32_e32 v13, v42, v13
	v_max_f32_e32 v5, v40, v5
	v_min_f32_e32 v15, v16, v8
	v_min_f32_e32 v10, v36, v4
	v_min_f32_e32 v7, v35, v6
	v_min_f32_e32 v3, v34, v2
	v_max_f32_e32 v8, v16, v8
	v_max_f32_e32 v4, v36, v4
	v_max_f32_e32 v6, v35, v6
	v_max_f32_e32 v2, v34, v2
	v_min_f32_e32 v41, v14, v9
	v_max_f32_e32 v9, v14, v9
	v_min_f32_e32 v40, v13, v5
	v_max_f32_e32 v5, v13, v5
	v_min_f32_e32 v39, v15, v10
	v_min_f32_e32 v37, v7, v3
	v_max_f32_e32 v10, v15, v10
	v_max_f32_e32 v3, v7, v3
	v_min_f32_e32 v15, v8, v4
	v_min_f32_e32 v16, v6, v2
	v_max_f32_e32 v4, v8, v4
	v_max_f32_e32 v2, v6, v2
	v_min_f32_e32 v45, v234, v41
	v_min_f32_e32 v14, v12, v9
	v_min_f32_e32 v42, v17, v40
	v_min_f32_e32 v13, v11, v5
	v_min_f32_e32 v38, v39, v37
	v_min_f32_e32 v7, v10, v3
	v_min_f32_e32 v34, v15, v16
	v_min_f32_e32 v6, v4, v2
	v_max3_f32 v8, v52, v60, v45
	v_max3_f32 v35, v232, v234, v41
	v_max3_f32 v14, v48, v56, v14
	v_max3_f32 v9, v231, v12, v9
	v_max3_f32 v12, v53, v61, v42
	v_max3_f32 v17, v230, v17, v40
	v_max3_f32 v13, v49, v57, v13
	v_max3_f32 v5, v229, v11, v5
	v_max3_f32 v11, v54, v154, v38
	v_max3_f32 v36, v228, v39, v37
	v_max3_f32 v7, v50, v58, v7
	v_max3_f32 v3, v227, v10, v3
	v_max3_f32 v10, v55, v205, v34
	v_max3_f32 v15, v207, v15, v16
	v_max3_f32 v6, v51, v59, v6
	v_max3_f32 v2, v206, v4, v2
	v_max_f32_e32 v4, v8, v11
	v_min_f32_e32 v8, v8, v11
	v_max_f32_e32 v11, v35, v36
	v_min_f32_e32 v16, v35, v36
	v_max_f32_e32 v34, v14, v7
	v_min_f32_e32 v7, v14, v7
	v_max_f32_e32 v14, v9, v3
	v_min_f32_e32 v3, v9, v3
	v_max_f32_e32 v9, v12, v10
	v_min_f32_e32 v10, v12, v10
	v_max_f32_e32 v12, v17, v15
	v_min_f32_e32 v15, v17, v15
	v_max_f32_e32 v17, v13, v6
	v_min_f32_e32 v6, v13, v6
	v_max_f32_e32 v13, v5, v2
	v_min_f32_e32 v2, v5, v2
	v_max_f32_e32 v5, v4, v9
	v_min_f32_e32 v4, v4, v9
	v_max_f32_e32 v9, v11, v12
	v_min_f32_e32 v11, v11, v12
	v_max_f32_e32 v12, v34, v17
	v_min_f32_e32 v17, v34, v17
	v_max_f32_e32 v34, v14, v13
	v_min_f32_e32 v13, v14, v13
	v_max_f32_e32 v14, v8, v10
	v_min_f32_e32 v8, v8, v10
	v_max_f32_e32 v10, v16, v15
	v_min_f32_e32 v15, v16, v15
	v_max_f32_e32 v16, v7, v6
	v_min_f32_e32 v6, v7, v6
	v_max_f32_e32 v7, v3, v2
	v_min_f32_e32 v2, v3, v2
	v_max_f32_e32 v52, v5, v12
	v_min_f32_e32 v48, v5, v12
	v_max_f32_e32 v60, v9, v34
	v_min_f32_e32 v56, v9, v34
	v_max_f32_e32 v53, v4, v17
	v_min_f32_e32 v49, v4, v17
	v_max_f32_e32 v205, v15, v2
	v_min_f32_e32 v59, v15, v2
	global_load_dwordx4 v[34:37], v[72:73], off offset:96
	global_load_dwordx4 v[38:41], v[72:73], off offset:64
	global_load_dwordx4 v[42:45], v[72:73], off offset:32
	global_load_dwordx4 v[2:5], v[72:73], off
	v_max_f32_e32 v61, v11, v13
	v_min_f32_e32 v57, v11, v13
	v_max_f32_e32 v54, v14, v16
	v_min_f32_e32 v50, v14, v16
	v_max_f32_e32 v154, v10, v7
	v_min_f32_e32 v58, v10, v7
	v_max_f32_e32 v55, v8, v6
	v_min_f32_e32 v51, v8, v6
	s_waitcnt vmcnt(0)
	v_mfma_f32_32x32x16_bf16 v[2:17], v[2:5], v[30:33], 0
	v_min_f32_e32 v232, v52, v60
	v_min_f32_e32 v231, v48, v56
	v_min_f32_e32 v230, v53, v61
	v_min_f32_e32 v229, v49, v57
	v_min_f32_e32 v228, v54, v154
	v_min_f32_e32 v227, v50, v58
	v_min_f32_e32 v207, v55, v205
	v_mfma_f32_32x32x16_bf16 v[2:17], v[42:45], v[26:29], v[2:17]
	v_min_f32_e32 v206, v51, v59
	v_mfma_f32_32x32x16_bf16 v[2:17], v[38:41], v[22:25], v[2:17]
	v_mfma_f32_32x32x16_bf16 v[2:17], v[34:37], v[18:21], v[2:17]
	s_nop 11
	v_and_or_b32 v2, v2, s33, v189
	v_and_or_b32 v3, v3, s33, v190
	v_and_or_b32 v4, v4, s33, v191
	v_and_or_b32 v5, v5, s33, v192
	v_and_or_b32 v6, v6, s33, v193
	v_and_or_b32 v7, v7, s33, v194
	v_and_or_b32 v8, v8, s33, v195
	v_and_or_b32 v9, v9, s33, v196
	v_and_or_b32 v10, v10, s33, v197
	v_and_or_b32 v11, v11, s33, v198
	v_and_or_b32 v12, v12, s33, v199
	v_and_or_b32 v13, v13, s33, v200
	v_and_or_b32 v14, v14, s33, v201
	v_and_or_b32 v15, v15, s33, v202
	v_and_or_b32 v16, v16, s33, v203
	v_and_or_b32 v17, v17, s33, v204
	v_max_f32_e32 v18, v2, v3
	v_min_f32_e32 v19, v4, v5
	v_min_f32_e32 v2, v2, v3
	v_max_f32_e32 v3, v4, v5
	v_max_f32_e32 v21, v6, v7
	v_min_f32_e32 v22, v8, v9
	v_min_f32_e32 v6, v6, v7
	v_max_f32_e32 v7, v8, v9
	v_max_f32_e32 v25, v10, v11
	v_min_f32_e32 v26, v12, v13
	v_min_f32_e32 v10, v10, v11
	v_max_f32_e32 v11, v12, v13
	v_max_f32_e32 v28, v14, v15
	v_min_f32_e32 v29, v16, v17
	v_min_f32_e32 v14, v14, v15
	v_max_f32_e32 v15, v16, v17
	v_max_f32_e32 v20, v18, v19
	v_max_f32_e32 v4, v2, v3
	v_min_f32_e32 v23, v21, v22
	v_min_f32_e32 v8, v6, v7
	v_min_f32_e32 v18, v18, v19
	v_min_f32_e32 v2, v2, v3
	v_max_f32_e32 v19, v21, v22
	v_max_f32_e32 v6, v6, v7
	v_max_f32_e32 v27, v25, v26
	v_max_f32_e32 v12, v10, v11
	v_min_f32_e32 v30, v28, v29
	v_min_f32_e32 v16, v14, v15
	v_min_f32_e32 v25, v25, v26
	v_min_f32_e32 v10, v10, v11
	v_max_f32_e32 v26, v28, v29
	v_max_f32_e32 v14, v14, v15
	v_max_f32_e32 v5, v20, v4
	v_min_f32_e32 v9, v23, v8
	v_max_f32_e32 v3, v18, v2
	v_min_f32_e32 v7, v19, v6
	v_min_f32_e32 v4, v20, v4
	v_max_f32_e32 v8, v23, v8
	v_min_f32_e32 v2, v18, v2
	v_max_f32_e32 v6, v19, v6
	v_max_f32_e32 v13, v27, v12
	v_min_f32_e32 v17, v30, v16
	v_max_f32_e32 v11, v25, v10
	v_min_f32_e32 v15, v26, v14
	v_min_f32_e32 v12, v27, v12
	v_max_f32_e32 v16, v30, v16
	v_min_f32_e32 v10, v25, v10
	v_max_f32_e32 v14, v26, v14
	v_max_f32_e32 v24, v5, v9
	v_max_f32_e32 v21, v3, v7
	v_max_f32_e32 v20, v4, v8
	v_max_f32_e32 v18, v2, v6
	v_min_f32_e32 v31, v13, v17
	v_min_f32_e32 v28, v11, v15
	v_min_f32_e32 v27, v12, v16
	v_min_f32_e32 v25, v10, v14
	v_min_f32_e32 v5, v5, v9
	v_min_f32_e32 v3, v3, v7
	v_min_f32_e32 v4, v4, v8
	v_min_f32_e32 v2, v2, v6
	v_max_f32_e32 v9, v13, v17
	v_max_f32_e32 v11, v11, v15
	v_max_f32_e32 v12, v12, v16
	v_max_f32_e32 v10, v10, v14
	v_max_f32_e32 v22, v24, v21
	v_max_f32_e32 v19, v20, v18
	v_min_f32_e32 v29, v31, v28
	v_min_f32_e32 v26, v27, v25
	v_max_f32_e32 v7, v5, v3
	v_max_f32_e32 v6, v4, v2
	v_min_f32_e32 v13, v9, v11
	v_min_f32_e32 v14, v12, v10
	v_min_f32_e32 v21, v24, v21
	v_min_f32_e32 v18, v20, v18
	v_max_f32_e32 v24, v31, v28
	v_max_f32_e32 v25, v27, v25
	v_min_f32_e32 v3, v5, v3
	v_min_f32_e32 v2, v4, v2
	v_max_f32_e32 v5, v9, v11
	v_max_f32_e32 v9, v12, v10
	v_max_f32_e32 v23, v22, v19
	v_min_f32_e32 v30, v29, v26
	v_max_f32_e32 v8, v7, v6
	v_min_f32_e32 v15, v13, v14
	v_max_f32_e32 v20, v21, v18
	v_min_f32_e32 v27, v24, v25
	v_max_f32_e32 v4, v3, v2
	v_min_f32_e32 v10, v5, v9
	v_min_f32_e32 v32, v23, v30
	v_min_f32_e32 v16, v8, v15
	v_min_f32_e32 v28, v20, v27
	v_min_f32_e32 v11, v4, v10
	v_min_f32_e32 v17, v32, v16
	v_min_f32_e32 v12, v28, v11
	v_min_f32_e32 v19, v22, v19
	v_max_f32_e32 v22, v29, v26
	v_min_f32_e32 v6, v7, v6
	v_max_f32_e32 v7, v13, v14
	v_min_f32_e32 v18, v21, v18
	v_max_f32_e32 v21, v24, v25
	v_min_f32_e32 v2, v3, v2
	v_max_f32_e32 v3, v5, v9
	v_max_f32_e32 v16, v32, v16
	v_max_f32_e32 v11, v28, v11
	v_min_f32_e32 v31, v17, v12
	v_min_f32_e32 v26, v19, v22
	v_min_f32_e32 v13, v6, v7
	v_min_f32_e32 v24, v18, v21
	v_min_f32_e32 v5, v2, v3
	v_max_f32_e32 v12, v17, v12
	v_min_f32_e32 v17, v16, v11
	v_max_f32_e32 v11, v16, v11
	v_max_f32_e32 v16, v23, v30
	v_max_f32_e32 v8, v8, v15
	v_max_f32_e32 v20, v20, v27
	v_max_f32_e32 v4, v4, v10
	v_max_f32_e32 v19, v19, v22
	v_max_f32_e32 v6, v6, v7
	v_max_f32_e32 v18, v18, v21
	v_max_f32_e32 v2, v2, v3
	v_min_f32_e32 v14, v26, v13
	v_min_f32_e32 v9, v24, v5
	v_max_f32_e32 v13, v26, v13
	v_max_f32_e32 v5, v24, v5
	v_min_f32_e32 v15, v16, v8
	v_min_f32_e32 v10, v20, v4
	v_min_f32_e32 v7, v19, v6
	v_min_f32_e32 v3, v18, v2
	v_max_f32_e32 v8, v16, v8
	v_max_f32_e32 v4, v20, v4
	v_max_f32_e32 v6, v19, v6
	v_max_f32_e32 v2, v18, v2
	v_min_f32_e32 v25, v14, v9
	v_max_f32_e32 v9, v14, v9
	v_min_f32_e32 v24, v13, v5
	v_max_f32_e32 v5, v13, v5
	v_min_f32_e32 v23, v15, v10
	v_min_f32_e32 v21, v7, v3
	v_max_f32_e32 v10, v15, v10
	v_max_f32_e32 v3, v7, v3
	v_min_f32_e32 v15, v8, v4
	v_min_f32_e32 v16, v6, v2
	v_max_f32_e32 v4, v8, v4
	v_max_f32_e32 v2, v6, v2
	v_min_f32_e32 v29, v31, v25
	v_min_f32_e32 v14, v12, v9
	v_min_f32_e32 v26, v17, v24
	v_min_f32_e32 v13, v11, v5
	v_min_f32_e32 v22, v23, v21
	v_min_f32_e32 v7, v10, v3
	v_min_f32_e32 v18, v15, v16
	v_min_f32_e32 v6, v4, v2
	v_max3_f32 v8, v52, v60, v29
	v_max3_f32 v19, v232, v31, v25
	v_max3_f32 v14, v48, v56, v14
	v_max3_f32 v9, v231, v12, v9
	v_max3_f32 v12, v53, v61, v26
	v_max3_f32 v17, v230, v17, v24
	v_max3_f32 v13, v49, v57, v13
	v_max3_f32 v5, v229, v11, v5
	v_max3_f32 v11, v54, v154, v22
	v_max3_f32 v20, v228, v23, v21
	v_max3_f32 v7, v50, v58, v7
	v_max3_f32 v3, v227, v10, v3
	v_max3_f32 v10, v55, v205, v18
	v_max3_f32 v15, v207, v15, v16
	v_max3_f32 v6, v51, v59, v6
	v_max3_f32 v2, v206, v4, v2
	v_max_f32_e32 v4, v8, v11
	v_min_f32_e32 v8, v8, v11
	v_max_f32_e32 v11, v19, v20
	v_min_f32_e32 v16, v19, v20
	v_max_f32_e32 v18, v14, v7
	v_min_f32_e32 v7, v14, v7
	v_max_f32_e32 v14, v9, v3
	v_min_f32_e32 v3, v9, v3
	v_max_f32_e32 v9, v12, v10
	v_min_f32_e32 v10, v12, v10
	v_max_f32_e32 v12, v17, v15
	v_min_f32_e32 v15, v17, v15
	v_max_f32_e32 v17, v13, v6
	v_min_f32_e32 v6, v13, v6
	v_max_f32_e32 v13, v5, v2
	v_min_f32_e32 v2, v5, v2
	v_max_f32_e32 v5, v4, v9
	v_min_f32_e32 v4, v4, v9
	v_max_f32_e32 v9, v11, v12
	v_min_f32_e32 v11, v11, v12
	v_max_f32_e32 v12, v18, v17
	v_min_f32_e32 v17, v18, v17
	v_max_f32_e32 v18, v14, v13
	v_min_f32_e32 v13, v14, v13
	v_max_f32_e32 v14, v8, v10
	v_min_f32_e32 v8, v8, v10
	v_max_f32_e32 v10, v16, v15
	v_min_f32_e32 v15, v16, v15
	v_max_f32_e32 v16, v7, v6
	v_min_f32_e32 v6, v7, v6
	v_max_f32_e32 v7, v3, v2
	v_min_f32_e32 v2, v3, v2
	v_max_f32_e32 v3, v5, v12
	v_min_f32_e32 v5, v5, v12
	v_max_f32_e32 v12, v9, v18
	v_min_f32_e32 v9, v9, v18
	v_max_f32_e32 v18, v4, v17
	v_min_f32_e32 v4, v4, v17
	v_max_f32_e32 v17, v11, v13
	v_min_f32_e32 v11, v11, v13
	v_max_f32_e32 v13, v14, v16
	v_min_f32_e32 v14, v14, v16
	v_max_f32_e32 v16, v10, v7
	v_min_f32_e32 v7, v10, v7
	v_max_f32_e32 v10, v8, v6
	v_min_f32_e32 v6, v8, v6
	v_max_f32_e32 v8, v15, v2
	v_min_f32_e32 v2, v15, v2
	v_max_f32_e32 v15, v3, v12
	v_min_f32_e32 v3, v3, v12
	v_max_f32_e32 v12, v5, v9
	v_min_f32_e32 v5, v5, v9
	v_max_f32_e32 v9, v18, v17
	v_min_f32_e32 v17, v18, v17
	v_max_f32_e32 v18, v4, v11
	v_min_f32_e32 v4, v4, v11
	v_max_f32_e32 v11, v13, v16
	v_min_f32_e32 v13, v13, v16
	v_max_f32_e32 v16, v14, v7
	v_min_f32_e32 v7, v14, v7
	v_max_f32_e32 v14, v10, v8
	v_min_f32_e32 v8, v10, v8
	v_max_f32_e32 v10, v6, v2
	v_min_f32_e32 v2, v6, v2
	ds_bpermute_b32 v6, v121, v15
	ds_bpermute_b32 v19, v121, v3
	ds_bpermute_b32 v20, v121, v12
	ds_bpermute_b32 v21, v121, v5
	ds_bpermute_b32 v22, v121, v9
	ds_bpermute_b32 v23, v121, v17
	ds_bpermute_b32 v24, v121, v18
	ds_bpermute_b32 v25, v121, v4
	ds_bpermute_b32 v26, v121, v11
	ds_bpermute_b32 v27, v121, v13
	ds_bpermute_b32 v28, v121, v16
	ds_bpermute_b32 v29, v121, v7
	ds_bpermute_b32 v30, v121, v14
	ds_bpermute_b32 v31, v121, v8
	ds_bpermute_b32 v32, v121, v10
	ds_bpermute_b32 v33, v121, v2
	s_waitcnt lgkmcnt(4)
	s_waitcnt lgkmcnt(3)
	s_waitcnt lgkmcnt(2)
	s_waitcnt lgkmcnt(1)
	s_waitcnt lgkmcnt(0)
	v_max_f32_e32 v15, v15, v33
	v_max_f32_e32 v3, v3, v32
	v_max_f32_e32 v12, v12, v31
	v_max_f32_e32 v5, v5, v30
	v_max_f32_e32 v9, v9, v29
	v_max_f32_e32 v17, v17, v28
	v_max_f32_e32 v18, v18, v27
	v_max_f32_e32 v4, v4, v26
	v_max_f32_e32 v11, v11, v25
	v_max_f32_e32 v13, v13, v24
	v_max_f32_e32 v16, v16, v23
	v_max_f32_e32 v7, v7, v22
	v_max_f32_e32 v14, v14, v21
	v_max_f32_e32 v8, v8, v20
	v_max_f32_e32 v10, v10, v19
	v_max_f32_e32 v2, v2, v6
	v_max_f32_e32 v6, v15, v11
	v_min_f32_e32 v11, v15, v11
	v_max_f32_e32 v15, v3, v13
	v_min_f32_e32 v3, v3, v13
	v_max_f32_e32 v13, v12, v16
	v_min_f32_e32 v12, v12, v16
	v_max_f32_e32 v16, v5, v7
	v_min_f32_e32 v5, v5, v7
	v_max_f32_e32 v7, v9, v14
	v_min_f32_e32 v9, v9, v14
	v_max_f32_e32 v14, v17, v8
	v_min_f32_e32 v8, v17, v8
	v_max_f32_e32 v17, v18, v10
	v_min_f32_e32 v10, v18, v10
	v_max_f32_e32 v18, v4, v2
	v_min_f32_e32 v2, v4, v2
	v_max_f32_e32 v4, v6, v7
	v_min_f32_e32 v6, v6, v7
	v_max_f32_e32 v7, v15, v14
	v_min_f32_e32 v14, v15, v14
	v_max_f32_e32 v15, v13, v17
	v_min_f32_e32 v13, v13, v17
	v_max_f32_e32 v17, v16, v18
	v_min_f32_e32 v16, v16, v18
	v_max_f32_e32 v18, v11, v9
	v_min_f32_e32 v9, v11, v9
	v_max_f32_e32 v11, v3, v8
	v_min_f32_e32 v3, v3, v8
	v_max_f32_e32 v8, v12, v10
	v_min_f32_e32 v10, v12, v10
	v_max_f32_e32 v12, v5, v2
	v_min_f32_e32 v2, v5, v2
	v_max_f32_e32 v5, v4, v15
	v_min_f32_e32 v4, v4, v15
	v_max_f32_e32 v15, v7, v17
	v_min_f32_e32 v7, v7, v17
	v_max_f32_e32 v17, v6, v13
	v_min_f32_e32 v6, v6, v13
	v_max_f32_e32 v13, v14, v16
	v_min_f32_e32 v14, v14, v16
	v_max_f32_e32 v16, v18, v8
	v_min_f32_e32 v8, v18, v8
	v_max_f32_e32 v18, v11, v12
	v_min_f32_e32 v11, v11, v12
	v_max_f32_e32 v12, v9, v10
	v_min_f32_e32 v9, v9, v10
	v_max_f32_e32 v10, v3, v2
	v_min_f32_e32 v2, v3, v2
	v_max_f32_e32 v20, v9, v2
	v_min_f32_e32 v21, v9, v2
	v_lshl_add_u64 v[2:3], v[64:65], 0, v[46:47]
	v_max_f32_e32 v30, v5, v15
	v_min_f32_e32 v31, v5, v15
	v_max_f32_e32 v32, v4, v7
	v_min_f32_e32 v33, v4, v7
	global_load_dwordx4 v[46:49], v[2:3], off
	global_load_dwordx4 v[42:45], v[2:3], off offset:32
	global_load_dwordx4 v[38:41], v[2:3], off offset:64
	global_load_dwordx4 v[34:37], v[2:3], off offset:96
	s_nop 0
	global_load_dwordx4 v[2:5], v[90:91], off
	global_load_dwordx4 v[58:61], v[90:91], off offset:32
	global_load_dwordx4 v[54:57], v[90:91], off offset:64
	global_load_dwordx4 v[50:53], v[90:91], off offset:96
	v_max_f32_e32 v26, v17, v13
	v_min_f32_e32 v27, v17, v13
	v_max_f32_e32 v28, v6, v14
	v_min_f32_e32 v29, v6, v14
	v_max_f32_e32 v22, v16, v18
	v_min_f32_e32 v23, v16, v18
	v_max_f32_e32 v24, v8, v11
	v_min_f32_e32 v25, v8, v11
	v_max_f32_e32 v18, v12, v10
	v_min_f32_e32 v19, v12, v10
	s_waitcnt vmcnt(3)
	v_mfma_f32_32x32x16_bf16 v[2:17], v[2:5], v[46:49], 0
	s_waitcnt vmcnt(2)
	v_mfma_f32_32x32x16_bf16 v[2:17], v[58:61], v[42:45], v[2:17]
	s_waitcnt vmcnt(1)
	v_mfma_f32_32x32x16_bf16 v[2:17], v[54:57], v[38:41], v[2:17]
	s_waitcnt vmcnt(0)
	v_mfma_f32_32x32x16_bf16 v[2:17], v[50:53], v[34:37], v[2:17]
	s_nop 11
	v_and_or_b32 v2, v2, s33, v120
	v_and_or_b32 v3, v3, s33, v122
	v_and_or_b32 v4, v4, s33, v123
	v_and_or_b32 v5, v5, s33, v124
	v_and_or_b32 v6, v6, s33, v125
	v_and_or_b32 v7, v7, s33, v126
	v_and_or_b32 v8, v8, s33, v127
	v_and_or_b32 v9, v9, s33, v128
	v_and_or_b32 v10, v10, s33, v129
	v_and_or_b32 v11, v11, s33, v136
	v_and_or_b32 v12, v12, s33, v137
	v_and_or_b32 v13, v13, s33, v138
	v_and_or_b32 v14, v14, s33, v139
	v_and_or_b32 v15, v15, s33, v140
	v_and_or_b32 v16, v16, s33, v141
	v_and_or_b32 v17, v17, s33, v142
	v_max_f32_e32 v50, v2, v3
	v_min_f32_e32 v51, v4, v5
	v_min_f32_e32 v2, v2, v3
	v_max_f32_e32 v3, v4, v5
	v_max_f32_e32 v53, v6, v7
	v_min_f32_e32 v54, v8, v9
	v_min_f32_e32 v6, v6, v7
	v_max_f32_e32 v7, v8, v9
	v_max_f32_e32 v57, v10, v11
	v_min_f32_e32 v58, v12, v13
	v_min_f32_e32 v10, v10, v11
	v_max_f32_e32 v11, v12, v13
	v_max_f32_e32 v60, v14, v15
	v_min_f32_e32 v61, v16, v17
	v_min_f32_e32 v14, v14, v15
	v_max_f32_e32 v15, v16, v17
	v_max_f32_e32 v52, v50, v51
	v_max_f32_e32 v4, v2, v3
	v_min_f32_e32 v55, v53, v54
	v_min_f32_e32 v8, v6, v7
	v_min_f32_e32 v50, v50, v51
	v_min_f32_e32 v2, v2, v3
	v_max_f32_e32 v51, v53, v54
	v_max_f32_e32 v6, v6, v7
	v_max_f32_e32 v59, v57, v58
	v_max_f32_e32 v12, v10, v11
	v_min_f32_e32 v154, v60, v61
	v_min_f32_e32 v16, v14, v15
	v_min_f32_e32 v57, v57, v58
	v_min_f32_e32 v10, v10, v11
	v_max_f32_e32 v58, v60, v61
	v_max_f32_e32 v14, v14, v15
	v_max_f32_e32 v5, v52, v4
	v_min_f32_e32 v9, v55, v8
	v_max_f32_e32 v3, v50, v2
	v_min_f32_e32 v7, v51, v6
	v_min_f32_e32 v4, v52, v4
	v_max_f32_e32 v8, v55, v8
	v_min_f32_e32 v2, v50, v2
	v_max_f32_e32 v6, v51, v6
	v_max_f32_e32 v13, v59, v12
	v_min_f32_e32 v17, v154, v16
	v_max_f32_e32 v11, v57, v10
	v_min_f32_e32 v15, v58, v14
	v_min_f32_e32 v12, v59, v12
	v_max_f32_e32 v16, v154, v16
	v_min_f32_e32 v10, v57, v10
	v_max_f32_e32 v14, v58, v14
	v_max_f32_e32 v56, v5, v9
	v_max_f32_e32 v53, v3, v7
	v_max_f32_e32 v52, v4, v8
	v_max_f32_e32 v50, v2, v6
	v_min_f32_e32 v205, v13, v17
	v_min_f32_e32 v60, v11, v15
	v_min_f32_e32 v59, v12, v16
	v_min_f32_e32 v57, v10, v14
	v_min_f32_e32 v5, v5, v9
	v_min_f32_e32 v3, v3, v7
	v_min_f32_e32 v4, v4, v8
	v_min_f32_e32 v2, v2, v6
	v_max_f32_e32 v9, v13, v17
	v_max_f32_e32 v11, v11, v15
	v_max_f32_e32 v12, v12, v16
	v_max_f32_e32 v10, v10, v14
	v_max_f32_e32 v54, v56, v53
	v_max_f32_e32 v51, v52, v50
	v_min_f32_e32 v61, v205, v60
	v_min_f32_e32 v58, v59, v57
	v_max_f32_e32 v7, v5, v3
	v_max_f32_e32 v6, v4, v2
	v_min_f32_e32 v13, v9, v11
	v_min_f32_e32 v14, v12, v10
	v_min_f32_e32 v53, v56, v53
	v_min_f32_e32 v50, v52, v50
	v_max_f32_e32 v56, v205, v60
	v_max_f32_e32 v57, v59, v57
	v_min_f32_e32 v3, v5, v3
	v_min_f32_e32 v2, v4, v2
	v_max_f32_e32 v5, v9, v11
	v_max_f32_e32 v9, v12, v10
	v_max_f32_e32 v55, v54, v51
	v_min_f32_e32 v235, v61, v58
	v_max_f32_e32 v8, v7, v6
	v_min_f32_e32 v15, v13, v14
	v_max_f32_e32 v52, v53, v50
	v_min_f32_e32 v59, v56, v57
	v_max_f32_e32 v4, v3, v2
	v_min_f32_e32 v10, v5, v9
	v_min_f32_e32 v229, v55, v235
	v_min_f32_e32 v16, v8, v15
	v_min_f32_e32 v60, v52, v59
	v_min_f32_e32 v11, v4, v10
	v_min_f32_e32 v51, v54, v51
	v_max_f32_e32 v54, v61, v58
	v_min_f32_e32 v6, v7, v6
	v_max_f32_e32 v7, v13, v14
	v_min_f32_e32 v50, v53, v50
	v_max_f32_e32 v53, v56, v57
	v_min_f32_e32 v2, v3, v2
	v_max_f32_e32 v3, v5, v9
	v_min_f32_e32 v17, v229, v16
	v_min_f32_e32 v12, v60, v11
	v_min_f32_e32 v58, v51, v54
	v_min_f32_e32 v13, v6, v7
	v_min_f32_e32 v56, v50, v53
	v_min_f32_e32 v5, v2, v3
	v_min_f32_e32 v154, v17, v12
	v_min_f32_e32 v14, v58, v13
	v_min_f32_e32 v9, v56, v5
	v_max_f32_e32 v207, v17, v12
	v_max_f32_e32 v12, v58, v13
	v_max_f32_e32 v5, v56, v5
	v_min_f32_e32 v205, v14, v9
	v_max_f32_e32 v227, v14, v9
	v_max_f32_e32 v9, v229, v16
	v_max_f32_e32 v11, v60, v11
	v_min_f32_e32 v230, v12, v5
	v_max_f32_e32 v233, v12, v5
	v_max_f32_e32 v12, v51, v54
	v_max_f32_e32 v6, v6, v7
	v_max_f32_e32 v13, v50, v53
	v_max_f32_e32 v2, v2, v3
	v_min_f32_e32 v229, v9, v11
	v_max_f32_e32 v232, v9, v11
	v_max_f32_e32 v5, v55, v235
	v_max_f32_e32 v8, v8, v15
	v_max_f32_e32 v11, v52, v59
	v_max_f32_e32 v4, v4, v10
	v_min_f32_e32 v7, v12, v6
	v_min_f32_e32 v3, v13, v2
	v_min_f32_e32 v9, v5, v8
	v_min_f32_e32 v10, v11, v4
	v_min_f32_e32 v236, v7, v3
	v_max_f32_e32 v239, v7, v3
	v_max_f32_e32 v3, v5, v8
	v_max_f32_e32 v4, v11, v4
	v_max_f32_e32 v5, v12, v6
	v_max_f32_e32 v2, v13, v2
	v_min_f32_e32 v241, v3, v4
	v_min_f32_e32 v242, v5, v2
	v_max_f32_e32 v244, v3, v4
	v_max_f32_e32 v245, v5, v2
	global_load_dwordx4 v[50:53], v[92:93], off offset:96
	global_load_dwordx4 v[54:57], v[92:93], off offset:64
	global_load_dwordx4 v[58:61], v[92:93], off offset:32
	global_load_dwordx4 v[2:5], v[92:93], off
	v_min_f32_e32 v235, v9, v10
	v_max_f32_e32 v238, v9, v10
	s_waitcnt vmcnt(0)
	v_mfma_f32_32x32x16_bf16 v[2:17], v[2:5], v[46:49], 0
	v_min_f32_e32 v206, v154, v205
	v_min_f32_e32 v228, v207, v227
	v_min_f32_e32 v231, v229, v230
	v_min_f32_e32 v234, v232, v233
	v_min_f32_e32 v237, v235, v236
	v_min_f32_e32 v240, v238, v239
	v_min_f32_e32 v243, v241, v242
	v_mfma_f32_32x32x16_bf16 v[2:17], v[58:61], v[42:45], v[2:17]
	v_min_f32_e32 v246, v244, v245
	v_mfma_f32_32x32x16_bf16 v[2:17], v[54:57], v[38:41], v[2:17]
	v_mfma_f32_32x32x16_bf16 v[2:17], v[50:53], v[34:37], v[2:17]
	s_nop 11
	v_and_or_b32 v2, v2, s33, v143
	v_and_or_b32 v3, v3, s33, v144
	v_and_or_b32 v4, v4, s33, v145
	v_and_or_b32 v5, v5, s33, v146
	v_and_or_b32 v6, v6, s33, v147
	v_and_or_b32 v7, v7, s33, v148
	v_and_or_b32 v8, v8, s33, v149
	v_and_or_b32 v9, v9, s33, v150
	v_and_or_b32 v10, v10, s33, v151
	v_and_or_b32 v11, v11, s33, v152
	v_and_or_b32 v12, v12, s33, v153
	v_and_or_b32 v13, v13, s33, v160
	v_and_or_b32 v14, v14, s33, v161
	v_and_or_b32 v15, v15, s33, v162
	v_and_or_b32 v16, v16, s33, v163
	v_and_or_b32 v17, v17, s33, v164
	v_max_f32_e32 v50, v2, v3
	v_min_f32_e32 v51, v4, v5
	v_min_f32_e32 v2, v2, v3
	v_max_f32_e32 v3, v4, v5
	v_max_f32_e32 v53, v6, v7
	v_min_f32_e32 v54, v8, v9
	v_min_f32_e32 v6, v6, v7
	v_max_f32_e32 v7, v8, v9
	v_max_f32_e32 v57, v10, v11
	v_min_f32_e32 v58, v12, v13
	v_min_f32_e32 v10, v10, v11
	v_max_f32_e32 v11, v12, v13
	v_max_f32_e32 v60, v14, v15
	v_min_f32_e32 v61, v16, v17
	v_min_f32_e32 v14, v14, v15
	v_max_f32_e32 v15, v16, v17
	v_max_f32_e32 v52, v50, v51
	v_max_f32_e32 v4, v2, v3
	v_min_f32_e32 v55, v53, v54
	v_min_f32_e32 v8, v6, v7
	v_min_f32_e32 v50, v50, v51
	v_min_f32_e32 v2, v2, v3
	v_max_f32_e32 v51, v53, v54
	v_max_f32_e32 v6, v6, v7
	v_max_f32_e32 v59, v57, v58
	v_max_f32_e32 v12, v10, v11
	v_min_f32_e32 v247, v60, v61
	v_min_f32_e32 v16, v14, v15
	v_min_f32_e32 v57, v57, v58
	v_min_f32_e32 v10, v10, v11
	v_max_f32_e32 v58, v60, v61
	v_max_f32_e32 v14, v14, v15
	v_max_f32_e32 v5, v52, v4
	v_min_f32_e32 v9, v55, v8
	v_max_f32_e32 v3, v50, v2
	v_min_f32_e32 v7, v51, v6
	v_min_f32_e32 v4, v52, v4
	v_max_f32_e32 v8, v55, v8
	v_min_f32_e32 v2, v50, v2
	v_max_f32_e32 v6, v51, v6
	v_max_f32_e32 v13, v59, v12
	v_min_f32_e32 v17, v247, v16
	v_max_f32_e32 v11, v57, v10
	v_min_f32_e32 v15, v58, v14
	v_min_f32_e32 v12, v59, v12
	v_max_f32_e32 v16, v247, v16
	v_min_f32_e32 v10, v57, v10
	v_max_f32_e32 v14, v58, v14
	v_max_f32_e32 v56, v5, v9
	v_max_f32_e32 v53, v3, v7
	v_max_f32_e32 v52, v4, v8
	v_max_f32_e32 v50, v2, v6
	v_min_f32_e32 v252, v13, v17
	v_min_f32_e32 v60, v11, v15
	v_min_f32_e32 v59, v12, v16
	v_min_f32_e32 v57, v10, v14
	v_min_f32_e32 v5, v5, v9
	v_min_f32_e32 v3, v3, v7
	v_min_f32_e32 v4, v4, v8
	v_min_f32_e32 v2, v2, v6
	v_max_f32_e32 v9, v13, v17
	v_max_f32_e32 v11, v11, v15
	v_max_f32_e32 v12, v12, v16
	v_max_f32_e32 v10, v10, v14
	v_max_f32_e32 v54, v56, v53
	v_max_f32_e32 v51, v52, v50
	v_min_f32_e32 v61, v252, v60
	v_min_f32_e32 v58, v59, v57
	v_max_f32_e32 v7, v5, v3
	v_max_f32_e32 v6, v4, v2
	v_min_f32_e32 v13, v9, v11
	v_min_f32_e32 v14, v12, v10
	v_min_f32_e32 v53, v56, v53
	v_min_f32_e32 v50, v52, v50
	v_max_f32_e32 v56, v252, v60
	v_max_f32_e32 v57, v59, v57
	v_min_f32_e32 v3, v5, v3
	v_min_f32_e32 v2, v4, v2
	v_max_f32_e32 v5, v9, v11
	v_max_f32_e32 v9, v12, v10
	v_max_f32_e32 v55, v54, v51
	v_min_f32_e32 v247, v61, v58
	v_max_f32_e32 v8, v7, v6
	v_min_f32_e32 v15, v13, v14
	v_max_f32_e32 v52, v53, v50
	v_min_f32_e32 v59, v56, v57
	v_max_f32_e32 v4, v3, v2
	v_min_f32_e32 v10, v5, v9
	v_min_f32_e32 v253, v55, v247
	v_min_f32_e32 v16, v8, v15
	v_min_f32_e32 v60, v52, v59
	v_min_f32_e32 v11, v4, v10
	v_min_f32_e32 v17, v253, v16
	v_min_f32_e32 v12, v60, v11
	v_min_f32_e32 v51, v54, v51
	v_max_f32_e32 v54, v61, v58
	v_min_f32_e32 v6, v7, v6
	v_max_f32_e32 v7, v13, v14
	v_min_f32_e32 v50, v53, v50
	v_max_f32_e32 v53, v56, v57
	v_min_f32_e32 v2, v3, v2
	v_max_f32_e32 v3, v5, v9
	v_max_f32_e32 v16, v253, v16
	v_max_f32_e32 v11, v60, v11
	v_min_f32_e32 v252, v17, v12
	v_min_f32_e32 v58, v51, v54
	v_min_f32_e32 v13, v6, v7
	v_min_f32_e32 v56, v50, v53
	v_min_f32_e32 v5, v2, v3
	v_max_f32_e32 v12, v17, v12
	v_min_f32_e32 v17, v16, v11
	v_max_f32_e32 v11, v16, v11
	v_max_f32_e32 v16, v55, v247
	v_max_f32_e32 v8, v8, v15
	v_max_f32_e32 v52, v52, v59
	v_max_f32_e32 v4, v4, v10
	v_max_f32_e32 v51, v51, v54
	v_max_f32_e32 v6, v6, v7
	v_max_f32_e32 v50, v50, v53
	v_max_f32_e32 v2, v2, v3
	v_min_f32_e32 v14, v58, v13
	v_min_f32_e32 v9, v56, v5
	v_max_f32_e32 v13, v58, v13
	v_max_f32_e32 v5, v56, v5
	v_min_f32_e32 v15, v16, v8
	v_min_f32_e32 v10, v52, v4
	v_min_f32_e32 v7, v51, v6
	v_min_f32_e32 v3, v50, v2
	v_max_f32_e32 v8, v16, v8
	v_max_f32_e32 v4, v52, v4
	v_max_f32_e32 v6, v51, v6
	v_max_f32_e32 v2, v50, v2
	v_min_f32_e32 v57, v14, v9
	v_max_f32_e32 v9, v14, v9
	v_min_f32_e32 v56, v13, v5
	v_max_f32_e32 v5, v13, v5
	v_min_f32_e32 v55, v15, v10
	v_min_f32_e32 v53, v7, v3
	v_max_f32_e32 v10, v15, v10
	v_max_f32_e32 v3, v7, v3
	v_min_f32_e32 v15, v8, v4
	v_min_f32_e32 v16, v6, v2
	v_max_f32_e32 v4, v8, v4
	v_max_f32_e32 v2, v6, v2
	v_min_f32_e32 v61, v252, v57
	v_min_f32_e32 v14, v12, v9
	v_min_f32_e32 v58, v17, v56
	v_min_f32_e32 v13, v11, v5
	v_min_f32_e32 v54, v55, v53
	v_min_f32_e32 v7, v10, v3
	v_min_f32_e32 v50, v15, v16
	v_min_f32_e32 v6, v4, v2
	v_max3_f32 v8, v244, v245, v61
	v_max3_f32 v51, v246, v252, v57
	v_max3_f32 v14, v241, v242, v14
	v_max3_f32 v9, v243, v12, v9
	v_max3_f32 v12, v238, v239, v58
	v_max3_f32 v17, v240, v17, v56
	v_max3_f32 v13, v235, v236, v13
	v_max3_f32 v5, v237, v11, v5
	v_max3_f32 v11, v232, v233, v54
	v_max3_f32 v52, v234, v55, v53
	v_max3_f32 v7, v229, v230, v7
	v_max3_f32 v3, v231, v10, v3
	v_max3_f32 v10, v207, v227, v50
	v_max3_f32 v15, v228, v15, v16
	v_max3_f32 v6, v154, v205, v6
	v_max3_f32 v2, v206, v4, v2
	v_max_f32_e32 v4, v8, v11
	v_min_f32_e32 v8, v8, v11
	v_max_f32_e32 v11, v51, v52
	v_min_f32_e32 v16, v51, v52
	v_max_f32_e32 v50, v14, v7
	v_min_f32_e32 v7, v14, v7
	v_max_f32_e32 v14, v9, v3
	v_min_f32_e32 v3, v9, v3
	v_max_f32_e32 v9, v12, v10
	v_min_f32_e32 v10, v12, v10
	v_max_f32_e32 v12, v17, v15
	v_min_f32_e32 v15, v17, v15
	v_max_f32_e32 v17, v13, v6
	v_min_f32_e32 v6, v13, v6
	v_max_f32_e32 v13, v5, v2
	v_min_f32_e32 v2, v5, v2
	v_max_f32_e32 v5, v4, v9
	v_min_f32_e32 v4, v4, v9
	v_max_f32_e32 v9, v11, v12
	v_min_f32_e32 v11, v11, v12
	v_max_f32_e32 v12, v50, v17
	v_min_f32_e32 v17, v50, v17
	v_max_f32_e32 v50, v14, v13
	v_min_f32_e32 v13, v14, v13
	v_max_f32_e32 v14, v8, v10
	v_min_f32_e32 v8, v8, v10
	v_max_f32_e32 v10, v16, v15
	v_min_f32_e32 v15, v16, v15
	v_max_f32_e32 v16, v7, v6
	v_min_f32_e32 v6, v7, v6
	v_max_f32_e32 v7, v3, v2
	v_min_f32_e32 v2, v3, v2
	v_max_f32_e32 v227, v5, v12
	v_min_f32_e32 v154, v5, v12
	v_max_f32_e32 v235, v9, v50
	v_min_f32_e32 v231, v9, v50
	v_max_f32_e32 v228, v4, v17
	v_min_f32_e32 v205, v4, v17
	v_max_f32_e32 v238, v15, v2
	v_min_f32_e32 v234, v15, v2
	global_load_dwordx4 v[50:53], v[94:95], off offset:96
	global_load_dwordx4 v[54:57], v[94:95], off offset:64
	global_load_dwordx4 v[58:61], v[94:95], off offset:32
	global_load_dwordx4 v[2:5], v[94:95], off
	v_max_f32_e32 v236, v11, v13
	v_min_f32_e32 v232, v11, v13
	v_max_f32_e32 v229, v14, v16
	v_min_f32_e32 v206, v14, v16
	v_max_f32_e32 v237, v10, v7
	v_min_f32_e32 v233, v10, v7
	v_max_f32_e32 v230, v8, v6
	v_min_f32_e32 v207, v8, v6
	s_waitcnt vmcnt(0)
	v_mfma_f32_32x32x16_bf16 v[2:17], v[2:5], v[46:49], 0
	v_min_f32_e32 v246, v227, v235
	v_min_f32_e32 v245, v154, v231
	v_min_f32_e32 v244, v228, v236
	v_min_f32_e32 v243, v205, v232
	v_min_f32_e32 v242, v229, v237
	v_min_f32_e32 v241, v206, v233
	v_min_f32_e32 v240, v230, v238
	v_mfma_f32_32x32x16_bf16 v[2:17], v[58:61], v[42:45], v[2:17]
	v_min_f32_e32 v239, v207, v234
	v_mfma_f32_32x32x16_bf16 v[2:17], v[54:57], v[38:41], v[2:17]
	v_mfma_f32_32x32x16_bf16 v[2:17], v[50:53], v[34:37], v[2:17]
	s_nop 11
	v_and_or_b32 v2, v2, s33, v165
	v_and_or_b32 v3, v3, s33, v166
	v_and_or_b32 v4, v4, s33, v167
	v_and_or_b32 v5, v5, s33, v168
	v_and_or_b32 v6, v6, s33, v169
	v_and_or_b32 v7, v7, s33, v170
	v_and_or_b32 v8, v8, s33, v171
	v_and_or_b32 v9, v9, s33, v172
	v_and_or_b32 v10, v10, s33, v173
	v_and_or_b32 v11, v11, s33, v174
	v_and_or_b32 v12, v12, s33, v175
	v_and_or_b32 v13, v13, s33, v184
	v_and_or_b32 v14, v14, s33, v185
	v_and_or_b32 v15, v15, s33, v186
	v_and_or_b32 v16, v16, s33, v187
	v_and_or_b32 v17, v17, s33, v188
	v_max_f32_e32 v50, v2, v3
	v_min_f32_e32 v51, v4, v5
	v_min_f32_e32 v2, v2, v3
	v_max_f32_e32 v3, v4, v5
	v_max_f32_e32 v53, v6, v7
	v_min_f32_e32 v54, v8, v9
	v_min_f32_e32 v6, v6, v7
	v_max_f32_e32 v7, v8, v9
	v_max_f32_e32 v57, v10, v11
	v_min_f32_e32 v58, v12, v13
	v_min_f32_e32 v10, v10, v11
	v_max_f32_e32 v11, v12, v13
	v_max_f32_e32 v60, v14, v15
	v_min_f32_e32 v61, v16, v17
	v_min_f32_e32 v14, v14, v15
	v_max_f32_e32 v15, v16, v17
	v_max_f32_e32 v52, v50, v51
	v_max_f32_e32 v4, v2, v3
	v_min_f32_e32 v55, v53, v54
	v_min_f32_e32 v8, v6, v7
	v_min_f32_e32 v50, v50, v51
	v_min_f32_e32 v2, v2, v3
	v_max_f32_e32 v51, v53, v54
	v_max_f32_e32 v6, v6, v7
	v_max_f32_e32 v59, v57, v58
	v_max_f32_e32 v12, v10, v11
	v_min_f32_e32 v247, v60, v61
	v_min_f32_e32 v16, v14, v15
	v_min_f32_e32 v57, v57, v58
	v_min_f32_e32 v10, v10, v11
	v_max_f32_e32 v58, v60, v61
	v_max_f32_e32 v14, v14, v15
	v_max_f32_e32 v5, v52, v4
	v_min_f32_e32 v9, v55, v8
	v_max_f32_e32 v3, v50, v2
	v_min_f32_e32 v7, v51, v6
	v_min_f32_e32 v4, v52, v4
	v_max_f32_e32 v8, v55, v8
	v_min_f32_e32 v2, v50, v2
	v_max_f32_e32 v6, v51, v6
	v_max_f32_e32 v13, v59, v12
	v_min_f32_e32 v17, v247, v16
	v_max_f32_e32 v11, v57, v10
	v_min_f32_e32 v15, v58, v14
	v_min_f32_e32 v12, v59, v12
	v_max_f32_e32 v16, v247, v16
	v_min_f32_e32 v10, v57, v10
	v_max_f32_e32 v14, v58, v14
	v_max_f32_e32 v56, v5, v9
	v_max_f32_e32 v53, v3, v7
	v_max_f32_e32 v52, v4, v8
	v_max_f32_e32 v50, v2, v6
	v_min_f32_e32 v252, v13, v17
	v_min_f32_e32 v60, v11, v15
	v_min_f32_e32 v59, v12, v16
	v_min_f32_e32 v57, v10, v14
	v_min_f32_e32 v5, v5, v9
	v_min_f32_e32 v3, v3, v7
	v_min_f32_e32 v4, v4, v8
	v_min_f32_e32 v2, v2, v6
	v_max_f32_e32 v9, v13, v17
	v_max_f32_e32 v11, v11, v15
	v_max_f32_e32 v12, v12, v16
	v_max_f32_e32 v10, v10, v14
	v_max_f32_e32 v54, v56, v53
	v_max_f32_e32 v51, v52, v50
	v_min_f32_e32 v61, v252, v60
	v_min_f32_e32 v58, v59, v57
	v_max_f32_e32 v7, v5, v3
	v_max_f32_e32 v6, v4, v2
	v_min_f32_e32 v13, v9, v11
	v_min_f32_e32 v14, v12, v10
	v_min_f32_e32 v53, v56, v53
	v_min_f32_e32 v50, v52, v50
	v_max_f32_e32 v56, v252, v60
	v_max_f32_e32 v57, v59, v57
	v_min_f32_e32 v3, v5, v3
	v_min_f32_e32 v2, v4, v2
	v_max_f32_e32 v5, v9, v11
	v_max_f32_e32 v9, v12, v10
	v_max_f32_e32 v55, v54, v51
	v_min_f32_e32 v247, v61, v58
	v_max_f32_e32 v8, v7, v6
	v_min_f32_e32 v15, v13, v14
	v_max_f32_e32 v52, v53, v50
	v_min_f32_e32 v59, v56, v57
	v_max_f32_e32 v4, v3, v2
	v_min_f32_e32 v10, v5, v9
	v_min_f32_e32 v253, v55, v247
	v_min_f32_e32 v16, v8, v15
	v_min_f32_e32 v60, v52, v59
	v_min_f32_e32 v11, v4, v10
	v_min_f32_e32 v17, v253, v16
	v_min_f32_e32 v12, v60, v11
	v_min_f32_e32 v51, v54, v51
	v_max_f32_e32 v54, v61, v58
	v_min_f32_e32 v6, v7, v6
	v_max_f32_e32 v7, v13, v14
	v_min_f32_e32 v50, v53, v50
	v_max_f32_e32 v53, v56, v57
	v_min_f32_e32 v2, v3, v2
	v_max_f32_e32 v3, v5, v9
	v_max_f32_e32 v16, v253, v16
	v_max_f32_e32 v11, v60, v11
	v_min_f32_e32 v252, v17, v12
	v_min_f32_e32 v58, v51, v54
	v_min_f32_e32 v13, v6, v7
	v_min_f32_e32 v56, v50, v53
	v_min_f32_e32 v5, v2, v3
	v_max_f32_e32 v12, v17, v12
	v_min_f32_e32 v17, v16, v11
	v_max_f32_e32 v11, v16, v11
	v_max_f32_e32 v16, v55, v247
	v_max_f32_e32 v8, v8, v15
	v_max_f32_e32 v52, v52, v59
	v_max_f32_e32 v4, v4, v10
	v_max_f32_e32 v51, v51, v54
	v_max_f32_e32 v6, v6, v7
	v_max_f32_e32 v50, v50, v53
	v_max_f32_e32 v2, v2, v3
	v_min_f32_e32 v14, v58, v13
	v_min_f32_e32 v9, v56, v5
	v_max_f32_e32 v13, v58, v13
	v_max_f32_e32 v5, v56, v5
	v_min_f32_e32 v15, v16, v8
	v_min_f32_e32 v10, v52, v4
	v_min_f32_e32 v7, v51, v6
	v_min_f32_e32 v3, v50, v2
	v_max_f32_e32 v8, v16, v8
	v_max_f32_e32 v4, v52, v4
	v_max_f32_e32 v6, v51, v6
	v_max_f32_e32 v2, v50, v2
	v_min_f32_e32 v57, v14, v9
	v_max_f32_e32 v9, v14, v9
	v_min_f32_e32 v56, v13, v5
	v_max_f32_e32 v5, v13, v5
	v_min_f32_e32 v55, v15, v10
	v_min_f32_e32 v53, v7, v3
	v_max_f32_e32 v10, v15, v10
	v_max_f32_e32 v3, v7, v3
	v_min_f32_e32 v15, v8, v4
	v_min_f32_e32 v16, v6, v2
	v_max_f32_e32 v4, v8, v4
	v_max_f32_e32 v2, v6, v2
	v_min_f32_e32 v61, v252, v57
	v_min_f32_e32 v14, v12, v9
	v_min_f32_e32 v58, v17, v56
	v_min_f32_e32 v13, v11, v5
	v_min_f32_e32 v54, v55, v53
	v_min_f32_e32 v7, v10, v3
	v_min_f32_e32 v50, v15, v16
	v_min_f32_e32 v6, v4, v2
	v_max3_f32 v8, v227, v235, v61
	v_max3_f32 v51, v246, v252, v57
	v_max3_f32 v14, v154, v231, v14
	v_max3_f32 v9, v245, v12, v9
	v_max3_f32 v12, v228, v236, v58
	v_max3_f32 v17, v244, v17, v56
	v_max3_f32 v13, v205, v232, v13
	v_max3_f32 v5, v243, v11, v5
	v_max3_f32 v11, v229, v237, v54
	v_max3_f32 v52, v242, v55, v53
	v_max3_f32 v7, v206, v233, v7
	v_max3_f32 v3, v241, v10, v3
	v_max3_f32 v10, v230, v238, v50
	v_max3_f32 v15, v240, v15, v16
	v_max3_f32 v6, v207, v234, v6
	v_max3_f32 v2, v239, v4, v2
	v_max_f32_e32 v4, v8, v11
	v_min_f32_e32 v8, v8, v11
	v_max_f32_e32 v11, v51, v52
	v_min_f32_e32 v16, v51, v52
	v_max_f32_e32 v50, v14, v7
	v_min_f32_e32 v7, v14, v7
	v_max_f32_e32 v14, v9, v3
	v_min_f32_e32 v3, v9, v3
	v_max_f32_e32 v9, v12, v10
	v_min_f32_e32 v10, v12, v10
	v_max_f32_e32 v12, v17, v15
	v_min_f32_e32 v15, v17, v15
	v_max_f32_e32 v17, v13, v6
	v_min_f32_e32 v6, v13, v6
	v_max_f32_e32 v13, v5, v2
	v_min_f32_e32 v2, v5, v2
	v_max_f32_e32 v5, v4, v9
	v_min_f32_e32 v4, v4, v9
	v_max_f32_e32 v9, v11, v12
	v_min_f32_e32 v11, v11, v12
	v_max_f32_e32 v12, v50, v17
	v_min_f32_e32 v17, v50, v17
	v_max_f32_e32 v50, v14, v13
	v_min_f32_e32 v13, v14, v13
	v_max_f32_e32 v14, v8, v10
	v_min_f32_e32 v8, v8, v10
	v_max_f32_e32 v10, v16, v15
	v_min_f32_e32 v15, v16, v15
	v_max_f32_e32 v16, v7, v6
	v_min_f32_e32 v6, v7, v6
	v_max_f32_e32 v7, v3, v2
	v_min_f32_e32 v2, v3, v2
	v_max_f32_e32 v227, v5, v12
	v_min_f32_e32 v154, v5, v12
	v_max_f32_e32 v235, v9, v50
	v_min_f32_e32 v231, v9, v50
	v_max_f32_e32 v228, v4, v17
	v_min_f32_e32 v205, v4, v17
	v_max_f32_e32 v238, v15, v2
	v_min_f32_e32 v234, v15, v2
	global_load_dwordx4 v[50:53], v[96:97], off offset:96
	global_load_dwordx4 v[54:57], v[96:97], off offset:64
	global_load_dwordx4 v[58:61], v[96:97], off offset:32
	global_load_dwordx4 v[2:5], v[96:97], off
	v_max_f32_e32 v236, v11, v13
	v_min_f32_e32 v232, v11, v13
	v_max_f32_e32 v229, v14, v16
	v_min_f32_e32 v206, v14, v16
	v_max_f32_e32 v237, v10, v7
	v_min_f32_e32 v233, v10, v7
	v_max_f32_e32 v230, v8, v6
	v_min_f32_e32 v207, v8, v6
	s_waitcnt vmcnt(0)
	v_mfma_f32_32x32x16_bf16 v[2:17], v[2:5], v[46:49], 0
	v_min_f32_e32 v246, v227, v235
	v_min_f32_e32 v245, v154, v231
	v_min_f32_e32 v244, v228, v236
	v_min_f32_e32 v243, v205, v232
	v_min_f32_e32 v242, v229, v237
	v_min_f32_e32 v241, v206, v233
	v_min_f32_e32 v240, v230, v238
	v_mfma_f32_32x32x16_bf16 v[2:17], v[58:61], v[42:45], v[2:17]
	v_min_f32_e32 v239, v207, v234
	v_mfma_f32_32x32x16_bf16 v[2:17], v[54:57], v[38:41], v[2:17]
	v_mfma_f32_32x32x16_bf16 v[2:17], v[50:53], v[34:37], v[2:17]
	s_nop 11
	v_and_or_b32 v2, v2, s33, v189
	v_and_or_b32 v3, v3, s33, v190
	v_and_or_b32 v4, v4, s33, v191
	v_and_or_b32 v5, v5, s33, v192
	v_and_or_b32 v6, v6, s33, v193
	v_and_or_b32 v7, v7, s33, v194
	v_and_or_b32 v8, v8, s33, v195
	v_and_or_b32 v9, v9, s33, v196
	v_and_or_b32 v10, v10, s33, v197
	v_and_or_b32 v11, v11, s33, v198
	v_and_or_b32 v12, v12, s33, v199
	v_and_or_b32 v13, v13, s33, v200
	v_and_or_b32 v14, v14, s33, v201
	v_and_or_b32 v15, v15, s33, v202
	v_and_or_b32 v16, v16, s33, v203
	v_and_or_b32 v17, v17, s33, v204
	v_max_f32_e32 v34, v2, v3
	v_min_f32_e32 v35, v4, v5
	v_min_f32_e32 v2, v2, v3
	v_max_f32_e32 v3, v4, v5
	v_max_f32_e32 v37, v6, v7
	v_min_f32_e32 v38, v8, v9
	v_min_f32_e32 v6, v6, v7
	v_max_f32_e32 v7, v8, v9
	v_max_f32_e32 v41, v10, v11
	v_min_f32_e32 v42, v12, v13
	v_min_f32_e32 v10, v10, v11
	v_max_f32_e32 v11, v12, v13
	v_max_f32_e32 v44, v14, v15
	v_min_f32_e32 v45, v16, v17
	v_min_f32_e32 v14, v14, v15
	v_max_f32_e32 v15, v16, v17
	v_max_f32_e32 v36, v34, v35
	v_max_f32_e32 v4, v2, v3
	v_min_f32_e32 v39, v37, v38
	v_min_f32_e32 v8, v6, v7
	v_min_f32_e32 v34, v34, v35
	v_min_f32_e32 v2, v2, v3
	v_max_f32_e32 v35, v37, v38
	v_max_f32_e32 v6, v6, v7
	v_max_f32_e32 v43, v41, v42
	v_max_f32_e32 v12, v10, v11
	v_min_f32_e32 v46, v44, v45
	v_min_f32_e32 v16, v14, v15
	v_min_f32_e32 v41, v41, v42
	v_min_f32_e32 v10, v10, v11
	v_max_f32_e32 v42, v44, v45
	v_max_f32_e32 v14, v14, v15
	v_max_f32_e32 v5, v36, v4
	v_min_f32_e32 v9, v39, v8
	v_max_f32_e32 v3, v34, v2
	v_min_f32_e32 v7, v35, v6
	v_min_f32_e32 v4, v36, v4
	v_max_f32_e32 v8, v39, v8
	v_min_f32_e32 v2, v34, v2
	v_max_f32_e32 v6, v35, v6
	v_max_f32_e32 v13, v43, v12
	v_min_f32_e32 v17, v46, v16
	v_max_f32_e32 v11, v41, v10
	v_min_f32_e32 v15, v42, v14
	v_min_f32_e32 v12, v43, v12
	v_max_f32_e32 v16, v46, v16
	v_min_f32_e32 v10, v41, v10
	v_max_f32_e32 v14, v42, v14
	v_max_f32_e32 v40, v5, v9
	v_max_f32_e32 v37, v3, v7
	v_max_f32_e32 v36, v4, v8
	v_max_f32_e32 v34, v2, v6
	v_min_f32_e32 v47, v13, v17
	v_min_f32_e32 v44, v11, v15
	v_min_f32_e32 v43, v12, v16
	v_min_f32_e32 v41, v10, v14
	v_min_f32_e32 v5, v5, v9
	v_min_f32_e32 v3, v3, v7
	v_min_f32_e32 v4, v4, v8
	v_min_f32_e32 v2, v2, v6
	v_max_f32_e32 v9, v13, v17
	v_max_f32_e32 v11, v11, v15
	v_max_f32_e32 v12, v12, v16
	v_max_f32_e32 v10, v10, v14
	v_max_f32_e32 v38, v40, v37
	v_max_f32_e32 v35, v36, v34
	v_min_f32_e32 v45, v47, v44
	v_min_f32_e32 v42, v43, v41
	v_max_f32_e32 v7, v5, v3
	v_max_f32_e32 v6, v4, v2
	v_min_f32_e32 v13, v9, v11
	v_min_f32_e32 v14, v12, v10
	v_min_f32_e32 v37, v40, v37
	v_min_f32_e32 v34, v36, v34
	v_max_f32_e32 v40, v47, v44
	v_max_f32_e32 v41, v43, v41
	v_min_f32_e32 v3, v5, v3
	v_min_f32_e32 v2, v4, v2
	v_max_f32_e32 v5, v9, v11
	v_max_f32_e32 v9, v12, v10
	v_max_f32_e32 v39, v38, v35
	v_min_f32_e32 v46, v45, v42
	v_max_f32_e32 v8, v7, v6
	v_min_f32_e32 v15, v13, v14
	v_max_f32_e32 v36, v37, v34
	v_min_f32_e32 v43, v40, v41
	v_max_f32_e32 v4, v3, v2
	v_min_f32_e32 v10, v5, v9
	v_min_f32_e32 v48, v39, v46
	v_min_f32_e32 v16, v8, v15
	v_min_f32_e32 v44, v36, v43
	v_min_f32_e32 v11, v4, v10
	v_min_f32_e32 v17, v48, v16
	v_min_f32_e32 v12, v44, v11
	v_min_f32_e32 v35, v38, v35
	v_max_f32_e32 v38, v45, v42
	v_min_f32_e32 v6, v7, v6
	v_max_f32_e32 v7, v13, v14
	v_min_f32_e32 v34, v37, v34
	v_max_f32_e32 v37, v40, v41
	v_min_f32_e32 v2, v3, v2
	v_max_f32_e32 v3, v5, v9
	v_max_f32_e32 v16, v48, v16
	v_max_f32_e32 v11, v44, v11
	v_min_f32_e32 v47, v17, v12
	v_min_f32_e32 v42, v35, v38
	v_min_f32_e32 v13, v6, v7
	v_min_f32_e32 v40, v34, v37
	v_min_f32_e32 v5, v2, v3
	v_max_f32_e32 v12, v17, v12
	v_min_f32_e32 v17, v16, v11
	v_max_f32_e32 v11, v16, v11
	v_max_f32_e32 v16, v39, v46
	v_max_f32_e32 v8, v8, v15
	v_max_f32_e32 v36, v36, v43
	v_max_f32_e32 v4, v4, v10
	v_max_f32_e32 v35, v35, v38
	v_max_f32_e32 v6, v6, v7
	v_max_f32_e32 v34, v34, v37
	v_max_f32_e32 v2, v2, v3
	v_min_f32_e32 v14, v42, v13
	v_min_f32_e32 v9, v40, v5
	v_max_f32_e32 v13, v42, v13
	v_max_f32_e32 v5, v40, v5
	v_min_f32_e32 v15, v16, v8
	v_min_f32_e32 v10, v36, v4
	v_min_f32_e32 v7, v35, v6
	v_min_f32_e32 v3, v34, v2
	v_max_f32_e32 v8, v16, v8
	v_max_f32_e32 v4, v36, v4
	v_max_f32_e32 v6, v35, v6
	v_max_f32_e32 v2, v34, v2
	v_min_f32_e32 v41, v14, v9
	v_max_f32_e32 v9, v14, v9
	v_min_f32_e32 v40, v13, v5
	v_max_f32_e32 v5, v13, v5
	v_min_f32_e32 v39, v15, v10
	v_min_f32_e32 v37, v7, v3
	v_max_f32_e32 v10, v15, v10
	v_max_f32_e32 v3, v7, v3
	v_min_f32_e32 v15, v8, v4
	v_min_f32_e32 v16, v6, v2
	v_max_f32_e32 v4, v8, v4
	v_max_f32_e32 v2, v6, v2
	v_min_f32_e32 v45, v47, v41
	v_min_f32_e32 v14, v12, v9
	v_min_f32_e32 v42, v17, v40
	v_min_f32_e32 v13, v11, v5
	v_min_f32_e32 v38, v39, v37
	v_min_f32_e32 v7, v10, v3
	v_min_f32_e32 v34, v15, v16
	v_min_f32_e32 v6, v4, v2
	v_max3_f32 v8, v227, v235, v45
	v_max3_f32 v35, v246, v47, v41
	v_max3_f32 v14, v154, v231, v14
	v_max3_f32 v9, v245, v12, v9
	v_max3_f32 v12, v228, v236, v42
	v_max3_f32 v17, v244, v17, v40
	v_max3_f32 v13, v205, v232, v13
	v_max3_f32 v5, v243, v11, v5
	v_max3_f32 v11, v229, v237, v38
	v_max3_f32 v36, v242, v39, v37
	v_max3_f32 v7, v206, v233, v7
	v_max3_f32 v3, v241, v10, v3
	v_max3_f32 v10, v230, v238, v34
	v_max3_f32 v15, v240, v15, v16
	v_max3_f32 v6, v207, v234, v6
	v_max3_f32 v2, v239, v4, v2
	v_max_f32_e32 v4, v8, v11
	v_min_f32_e32 v8, v8, v11
	v_max_f32_e32 v11, v35, v36
	v_min_f32_e32 v16, v35, v36
	v_max_f32_e32 v34, v14, v7
	v_min_f32_e32 v7, v14, v7
	v_max_f32_e32 v14, v9, v3
	v_min_f32_e32 v3, v9, v3
	v_max_f32_e32 v9, v12, v10
	v_min_f32_e32 v10, v12, v10
	v_max_f32_e32 v12, v17, v15
	v_min_f32_e32 v15, v17, v15
	v_max_f32_e32 v17, v13, v6
	v_min_f32_e32 v6, v13, v6
	v_max_f32_e32 v13, v5, v2
	v_min_f32_e32 v2, v5, v2
	v_max_f32_e32 v5, v4, v9
	v_min_f32_e32 v4, v4, v9
	v_max_f32_e32 v9, v11, v12
	v_min_f32_e32 v11, v11, v12
	v_max_f32_e32 v12, v34, v17
	v_min_f32_e32 v17, v34, v17
	v_max_f32_e32 v34, v14, v13
	v_min_f32_e32 v13, v14, v13
	v_max_f32_e32 v14, v8, v10
	v_min_f32_e32 v8, v8, v10
	v_max_f32_e32 v10, v16, v15
	v_min_f32_e32 v15, v16, v15
	v_max_f32_e32 v16, v7, v6
	v_min_f32_e32 v6, v7, v6
	v_max_f32_e32 v7, v3, v2
	v_min_f32_e32 v2, v3, v2
	v_max_f32_e32 v3, v5, v12
	v_min_f32_e32 v5, v5, v12
	v_max_f32_e32 v12, v9, v34
	v_min_f32_e32 v9, v9, v34
	v_max_f32_e32 v34, v4, v17
	v_min_f32_e32 v4, v4, v17
	v_max_f32_e32 v17, v11, v13
	v_min_f32_e32 v11, v11, v13
	v_max_f32_e32 v13, v14, v16
	v_min_f32_e32 v14, v14, v16
	v_max_f32_e32 v16, v10, v7
	v_min_f32_e32 v7, v10, v7
	v_max_f32_e32 v10, v8, v6
	v_min_f32_e32 v6, v8, v6
	v_max_f32_e32 v8, v15, v2
	v_min_f32_e32 v2, v15, v2
	v_max_f32_e32 v15, v3, v12
	v_min_f32_e32 v3, v3, v12
	v_max_f32_e32 v12, v5, v9
	v_min_f32_e32 v5, v5, v9
	v_max_f32_e32 v9, v34, v17
	v_min_f32_e32 v17, v34, v17
	v_max_f32_e32 v34, v4, v11
	v_min_f32_e32 v4, v4, v11
	v_max_f32_e32 v11, v13, v16
	v_min_f32_e32 v13, v13, v16
	v_max_f32_e32 v16, v14, v7
	v_min_f32_e32 v7, v14, v7
	v_max_f32_e32 v14, v10, v8
	v_min_f32_e32 v8, v10, v8
	v_max_f32_e32 v10, v6, v2
	v_min_f32_e32 v2, v6, v2
	ds_bpermute_b32 v6, v121, v15
	ds_bpermute_b32 v35, v121, v3
	ds_bpermute_b32 v36, v121, v12
	ds_bpermute_b32 v37, v121, v5
	ds_bpermute_b32 v38, v121, v9
	ds_bpermute_b32 v39, v121, v17
	ds_bpermute_b32 v40, v121, v34
	ds_bpermute_b32 v41, v121, v4
	ds_bpermute_b32 v42, v121, v11
	ds_bpermute_b32 v43, v121, v13
	ds_bpermute_b32 v44, v121, v16
	ds_bpermute_b32 v45, v121, v7
	ds_bpermute_b32 v46, v121, v14
	ds_bpermute_b32 v47, v121, v8
	ds_bpermute_b32 v48, v121, v10
	ds_bpermute_b32 v49, v121, v2
	s_waitcnt lgkmcnt(4)
	s_waitcnt lgkmcnt(3)
	s_waitcnt lgkmcnt(2)
	s_waitcnt lgkmcnt(1)
	s_waitcnt lgkmcnt(0)
	v_max_f32_e32 v15, v15, v49
	v_max_f32_e32 v3, v3, v48
	v_max_f32_e32 v12, v12, v47
	v_max_f32_e32 v5, v5, v46
	v_max_f32_e32 v9, v9, v45
	v_max_f32_e32 v17, v17, v44
	v_max_f32_e32 v34, v34, v43
	v_max_f32_e32 v4, v4, v42
	v_max_f32_e32 v11, v11, v41
	v_max_f32_e32 v13, v13, v40
	v_max_f32_e32 v16, v16, v39
	v_max_f32_e32 v7, v7, v38
	v_max_f32_e32 v14, v14, v37
	v_max_f32_e32 v8, v8, v36
	v_max_f32_e32 v10, v10, v35
	v_max_f32_e32 v2, v2, v6
	v_max_f32_e32 v6, v15, v11
	v_min_f32_e32 v11, v15, v11
	v_max_f32_e32 v15, v3, v13
	v_min_f32_e32 v3, v3, v13
	v_max_f32_e32 v13, v12, v16
	v_min_f32_e32 v12, v12, v16
	v_max_f32_e32 v16, v5, v7
	v_min_f32_e32 v5, v5, v7
	v_max_f32_e32 v7, v9, v14
	v_min_f32_e32 v9, v9, v14
	v_max_f32_e32 v14, v17, v8
	v_min_f32_e32 v8, v17, v8
	v_max_f32_e32 v17, v34, v10
	v_min_f32_e32 v10, v34, v10
	v_max_f32_e32 v34, v4, v2
	v_min_f32_e32 v2, v4, v2
	v_max_f32_e32 v4, v6, v7
	v_min_f32_e32 v6, v6, v7
	v_max_f32_e32 v7, v15, v14
	v_min_f32_e32 v14, v15, v14
	v_max_f32_e32 v15, v13, v17
	v_min_f32_e32 v13, v13, v17
	v_max_f32_e32 v17, v16, v34
	v_min_f32_e32 v16, v16, v34
	v_max_f32_e32 v34, v11, v9
	v_min_f32_e32 v9, v11, v9
	v_max_f32_e32 v11, v3, v8
	v_min_f32_e32 v3, v3, v8
	v_max_f32_e32 v8, v12, v10
	v_min_f32_e32 v10, v12, v10
	v_max_f32_e32 v12, v5, v2
	v_max_f32_e32 v36, v34, v8
	v_min_f32_e32 v8, v34, v8
	v_max_f32_e32 v34, v11, v12
	v_min_f32_e32 v37, v11, v12
	v_max_f32_e32 v38, v9, v10
	v_min_f32_e32 v9, v9, v10
	v_max_f32_e32 v10, v36, v34
	v_min_f32_e32 v11, v36, v34
	v_mov_b32_e32 v34, v119
	v_min_f32_e32 v2, v5, v2
	v_max_f32_e32 v5, v4, v15
	v_min_f32_e32 v15, v4, v15
	v_max_f32_e32 v4, v7, v17
	v_min_f32_e32 v7, v7, v17
	v_max_f32_e32 v17, v6, v13
	v_min_f32_e32 v6, v6, v13
	v_max_f32_e32 v13, v14, v16
	v_min_f32_e32 v35, v14, v16
	v_max_f32_e32 v39, v3, v2
	v_min_f32_e32 v40, v3, v2
	v_and_b32_e32 v34, 31, v34
	v_max_f32_e32 v2, v5, v4
	v_min_f32_e32 v3, v5, v4
	v_max_f32_e32 v4, v15, v7
	v_min_f32_e32 v5, v15, v7
	v_max_f32_e32 v14, v17, v13
	v_min_f32_e32 v15, v17, v13
	v_max_f32_e32 v16, v6, v35
	v_min_f32_e32 v17, v6, v35
	v_max_f32_e32 v12, v8, v37
	v_min_f32_e32 v13, v8, v37
	v_max_f32_e32 v6, v38, v39
	v_min_f32_e32 v7, v38, v39
	v_max_f32_e32 v8, v9, v40
	v_min_f32_e32 v9, v9, v40
	v_lshl_add_u32 v36, v34, 7, s43
	s_lshl_b32 s10, s44, 10
	v_add_u32_e32 v36, s10, v36
	s_and_saveexec_b64 s[40:41], s[12:13]
	s_cbranch_execz .LBB0_24
	ds_write_b128 v36, v[30:33]
	ds_write_b128 v36, v[2:5] offset:64
	ds_write_b128 v36, v[26:29] offset:16
	ds_write_b128 v36, v[14:17] offset:80
	ds_write_b128 v36, v[22:25] offset:32
	ds_write_b128 v36, v[10:13] offset:96
	ds_write_b128 v36, v[18:21] offset:48
	ds_write_b128 v36, v[6:9] offset:112
.LBB0_24:
	s_or_b64 exec, exec, s[40:41]
	s_waitcnt lgkmcnt(0)
	s_cmp_eq_u32 s44, 0
	s_cbranch_scc0 .Ltk_merge
	v_mov_b32_e32 v74, v2
	v_mov_b32_e32 v75, v3
	v_mov_b32_e32 v76, v4
	v_mov_b32_e32 v77, v5
	v_mov_b32_e32 v78, v6
	v_mov_b32_e32 v79, v7
	v_mov_b32_e32 v80, v8
	v_mov_b32_e32 v81, v9
	v_mov_b32_e32 v82, v10
	v_mov_b32_e32 v83, v11
	v_mov_b32_e32 v84, v12
	v_mov_b32_e32 v85, v13
	v_mov_b32_e32 v86, v14
	v_mov_b32_e32 v87, v15
	v_mov_b32_e32 v88, v16
	v_mov_b32_e32 v89, v17
	v_mov_b32_e32 v98, v18
	v_mov_b32_e32 v99, v19
	v_mov_b32_e32 v100, v20
	v_mov_b32_e32 v101, v21
	v_mov_b32_e32 v102, v22
	v_mov_b32_e32 v103, v23
	v_mov_b32_e32 v104, v24
	v_mov_b32_e32 v105, v25
	v_mov_b32_e32 v106, v26
	v_mov_b32_e32 v107, v27
	v_mov_b32_e32 v108, v28
	v_mov_b32_e32 v109, v29
	v_mov_b32_e32 v110, v30
	v_mov_b32_e32 v111, v31
	v_mov_b32_e32 v112, v32
	v_mov_b32_e32 v113, v33
	s_mov_b64 s[40:41], exec
	s_branch .LBB0_21
.Ltk_merge:
	s_mov_b64 s[40:41], exec
	s_mov_b64 exec, s[12:13]
	v_mov_b32_e32 v2, v74
	v_mov_b32_e32 v3, v75
	v_mov_b32_e32 v4, v76
	v_mov_b32_e32 v5, v77
	v_mov_b32_e32 v6, v78
	v_mov_b32_e32 v7, v79
	v_mov_b32_e32 v8, v80
	v_mov_b32_e32 v9, v81
	v_mov_b32_e32 v10, v82
	v_mov_b32_e32 v11, v83
	v_mov_b32_e32 v12, v84
	v_mov_b32_e32 v13, v85
	v_mov_b32_e32 v14, v86
	v_mov_b32_e32 v15, v87
	v_mov_b32_e32 v16, v88
	v_mov_b32_e32 v17, v89
	v_mov_b32_e32 v18, v98
	v_mov_b32_e32 v19, v99
	v_mov_b32_e32 v20, v100
	v_mov_b32_e32 v21, v101
	v_mov_b32_e32 v22, v102
	v_mov_b32_e32 v23, v103
	v_mov_b32_e32 v24, v104
	v_mov_b32_e32 v25, v105
	v_mov_b32_e32 v26, v106
	v_mov_b32_e32 v27, v107
	v_mov_b32_e32 v28, v108
	v_mov_b32_e32 v29, v109
	v_mov_b32_e32 v30, v110
	v_mov_b32_e32 v31, v111
	v_mov_b32_e32 v32, v112
	v_mov_b32_e32 v33, v113
	v_add_u32_e32 v36, 0xffff8000, v36
	s_mov_b64 exec, s[40:41]
	v_and_b32_e32 v34, 63, v119
	v_and_b32_e32 v45, 0xffffff80, v30
	v_and_b32_e32 v6, 0xffffff80, v6
	v_add_f32_e32 v6, v45, v6
	v_and_or_b32 v57, v6, s78, 12
	v_and_b32_e32 v6, 0xffffff80, v7
	v_add_f32_e32 v6, v45, v6
	v_and_or_b32 v58, v6, s78, 13
	v_and_b32_e32 v6, 0xffffff80, v8
	v_add_f32_e32 v6, v45, v6
	v_and_or_b32 v59, v6, s78, 14
	v_and_b32_e32 v6, 0xffffff80, v9
	v_and_b32_e32 v3, 0xffffff80, v3
	v_add_f32_e32 v6, v45, v6
	v_and_b32_e32 v61, 0xffffff80, v31
	v_and_b32_e32 v4, 0xffffff80, v4
	v_and_or_b32 v60, v6, s78, 15
	v_add_f32_e32 v6, v61, v3
	v_and_b32_e32 v5, 0xffffff80, v5
	v_and_or_b32 v154, v6, s78, 17
	v_add_f32_e32 v6, v61, v4
	v_and_b32_e32 v14, 0xffffff80, v14
	v_and_or_b32 v205, v6, s78, 18
	v_add_f32_e32 v6, v61, v5
	v_and_b32_e32 v15, 0xffffff80, v15
	v_and_or_b32 v206, v6, s78, 19
	v_add_f32_e32 v6, v61, v14
	v_add_f32_e32 v30, v45, v3
	v_and_b32_e32 v16, 0xffffff80, v16
	v_and_or_b32 v207, v6, s78, 20
	v_add_f32_e32 v6, v61, v15
	v_and_or_b32 v46, v30, s78, 1
	v_add_f32_e32 v30, v45, v4
	v_and_b32_e32 v17, 0xffffff80, v17
	v_and_or_b32 v44, v6, s78, 21
	v_add_f32_e32 v6, v61, v16
	v_and_or_b32 v47, v30, s78, 2
	v_add_f32_e32 v30, v45, v5
	v_and_or_b32 v43, v6, s78, 22
	v_add_f32_e32 v6, v61, v17
	v_and_b32_e32 v41, 0xffffff80, v32
	v_and_or_b32 v48, v30, s78, 3
	v_add_f32_e32 v30, v45, v14
	v_and_or_b32 v42, v6, s78, 23
	v_add_f32_e32 v6, v41, v3
	v_and_or_b32 v49, v30, s78, 4
	v_add_f32_e32 v30, v45, v15
	v_and_or_b32 v40, v6, s78, 33
	v_add_f32_e32 v6, v41, v4
	v_and_or_b32 v50, v30, s78, 5
	v_add_f32_e32 v30, v45, v16
	v_and_or_b32 v39, v6, s78, 34
	v_add_f32_e32 v6, v41, v5
	v_and_or_b32 v51, v30, s78, 6
	v_add_f32_e32 v30, v45, v17
	v_and_or_b32 v38, v6, s78, 35
	v_add_f32_e32 v6, v41, v14
	v_and_b32_e32 v35, 0xffffff80, v33
	v_and_or_b32 v52, v30, s78, 7
	v_and_b32_e32 v10, 0xffffff80, v10
	v_and_or_b32 v37, v6, s78, 36
	v_add_f32_e32 v6, v35, v3
	v_and_b32_e32 v30, 0xffffff80, v26
	v_add_f32_e32 v10, v45, v10
	v_and_or_b32 v33, v6, s78, 49
	v_add_f32_e32 v6, v35, v4
	v_add_f32_e32 v4, v30, v4
	v_and_or_b32 v53, v10, s78, 8
	v_and_b32_e32 v10, 0xffffff80, v11
	v_and_b32_e32 v4, 0xffffff00, v4
	v_and_b32_e32 v16, 0xffffff80, v27
	v_add_f32_e32 v10, v45, v10
	v_or_b32_e32 v17, 0x42, v4
	v_add_f32_e32 v4, v16, v3
	v_and_or_b32 v54, v10, s78, 9
	v_and_b32_e32 v10, 0xffffff80, v12
	v_add_f32_e32 v5, v35, v5
	v_and_b32_e32 v4, 0xffffff00, v4
	v_and_b32_e32 v14, 0xffffff80, v28
	v_and_b32_e32 v12, 0xffffff80, v29
	v_and_or_b32 v31, v5, s78, 51
	v_add_f32_e32 v5, v30, v3
	v_or_b32_e32 v15, 0x51, v4
	v_add_f32_e32 v4, v14, v3
	v_add_f32_e32 v3, v12, v3
	v_and_b32_e32 v3, 0xffffff00, v3
	v_or_b32_e32 v11, 0x71, v3
	v_and_b32_e32 v3, 0xffffff80, v2
	v_and_or_b32 v32, v6, s78, 50
	v_and_b32_e32 v6, 0xffffff80, v18
	v_add_f32_e32 v18, v3, v45
	v_and_b32_e32 v18, 0xffffff00, v18
	v_add_f32_e32 v10, v45, v10
	v_and_b32_e32 v5, 0xffffff00, v5
	v_and_b32_e32 v4, 0xffffff00, v4
	v_and_or_b32 v55, v10, s78, 10
	v_and_b32_e32 v10, 0xffffff80, v13
	v_or_b32_e32 v26, 0x41, v5
	v_or_b32_e32 v13, 0x61, v4
	v_and_b32_e32 v5, 0xffffff80, v19
	v_and_b32_e32 v4, 0xffffff80, v20
	v_min_f32_e32 v19, 0xff61b1e6, v18
	v_max_f32_e32 v18, 0xff61b1e6, v18
	v_max_f32_e32 v20, v46, v46
	v_add_f32_e32 v10, v45, v10
	v_and_b32_e32 v2, 0xffffff80, v21
	v_max_f32_e32 v19, 0xff61b1e6, v19
	v_min_f32_e32 v21, v18, v20
	v_and_or_b32 v56, v10, s78, 11
	v_and_b32_e32 v10, 0xffffff80, v22
	v_min_f32_e32 v22, v19, v21
	v_max_f32_e32 v18, v18, v20
	v_max_f32_e32 v20, v47, v47
	v_max_f32_e32 v22, v19, v22
	v_max_f32_e32 v19, v19, v21
	v_min_f32_e32 v21, v18, v20
	v_and_b32_e32 v9, 0xffffff80, v23
	v_min_f32_e32 v23, v19, v21
	v_max_f32_e32 v18, v18, v20
	v_max_f32_e32 v20, v48, v48
	v_and_b32_e32 v8, 0xffffff80, v24
	v_min_f32_e32 v24, v22, v23
	v_max_f32_e32 v19, v19, v21
	v_min_f32_e32 v21, v18, v20
	v_max_f32_e32 v24, v22, v24
	v_max_f32_e32 v22, v22, v23
	v_min_f32_e32 v23, v19, v21
	v_max_f32_e32 v18, v18, v20
	v_max_f32_e32 v20, v49, v49
	v_and_b32_e32 v7, 0xffffff80, v25
	v_min_f32_e32 v25, v22, v23
	v_max_f32_e32 v19, v19, v21
	v_min_f32_e32 v21, v18, v20
	v_min_f32_e32 v27, v24, v25
	v_max_f32_e32 v22, v22, v23
	v_min_f32_e32 v23, v19, v21
	v_max_f32_e32 v18, v18, v20
	v_max_f32_e32 v20, v50, v50
	v_max_f32_e32 v27, v24, v27
	v_max_f32_e32 v24, v24, v25
	v_min_f32_e32 v25, v22, v23
	v_max_f32_e32 v19, v19, v21
	v_min_f32_e32 v21, v18, v20
	v_min_f32_e32 v28, v24, v25
	v_max_f32_e32 v22, v22, v23
	v_min_f32_e32 v23, v19, v21
	v_max_f32_e32 v18, v18, v20
	v_max_f32_e32 v20, v51, v51
	v_min_f32_e32 v29, v27, v28
	v_max_f32_e32 v24, v24, v25
	v_min_f32_e32 v25, v22, v23
	v_max_f32_e32 v19, v19, v21
	v_min_f32_e32 v21, v18, v20
	v_max_f32_e32 v29, v27, v29
	v_max_f32_e32 v27, v27, v28
	v_min_f32_e32 v28, v24, v25
	v_max_f32_e32 v22, v22, v23
	v_min_f32_e32 v23, v19, v21
	v_max_f32_e32 v18, v18, v20
	v_max_f32_e32 v20, v52, v52
	v_min_f32_e32 v45, v27, v28
	v_max_f32_e32 v24, v24, v25
	v_min_f32_e32 v25, v22, v23
	v_max_f32_e32 v19, v19, v21
	v_min_f32_e32 v21, v18, v20
	v_min_f32_e32 v46, v29, v45
	v_max_f32_e32 v27, v27, v28
	v_min_f32_e32 v28, v24, v25
	v_max_f32_e32 v22, v22, v23
	v_min_f32_e32 v23, v19, v21
	v_max_f32_e32 v18, v18, v20
	v_max_f32_e32 v20, v53, v53
	v_max_f32_e32 v46, v29, v46
	v_max_f32_e32 v29, v29, v45
	v_min_f32_e32 v45, v27, v28
	v_max_f32_e32 v24, v24, v25
	v_min_f32_e32 v25, v22, v23
	v_max_f32_e32 v19, v19, v21
	v_min_f32_e32 v21, v18, v20
	v_min_f32_e32 v47, v29, v45
	v_max_f32_e32 v27, v27, v28
	v_min_f32_e32 v28, v24, v25
	v_max_f32_e32 v22, v22, v23
	v_min_f32_e32 v23, v19, v21
	v_max_f32_e32 v18, v18, v20
	v_max_f32_e32 v20, v54, v54
	v_min_f32_e32 v48, v46, v47
	v_max_f32_e32 v29, v29, v45
	v_min_f32_e32 v45, v27, v28
	v_max_f32_e32 v24, v24, v25
	v_min_f32_e32 v25, v22, v23
	v_max_f32_e32 v19, v19, v21
	v_min_f32_e32 v21, v18, v20
	v_max_f32_e32 v18, v18, v20
	v_max_f32_e32 v20, v55, v55
	v_max_f32_e32 v48, v46, v48
	v_max_f32_e32 v46, v46, v47
	v_min_f32_e32 v47, v29, v45
	v_max_f32_e32 v27, v27, v28
	v_min_f32_e32 v28, v24, v25
	v_max_f32_e32 v22, v22, v23
	v_min_f32_e32 v23, v19, v21
	v_max_f32_e32 v19, v19, v21
	v_min_f32_e32 v21, v18, v20
	v_max_f32_e32 v18, v18, v20
	v_max_f32_e32 v20, v56, v56
	v_min_f32_e32 v49, v46, v47
	v_max_f32_e32 v29, v29, v45
	v_min_f32_e32 v45, v27, v28
	v_max_f32_e32 v24, v24, v25
	v_min_f32_e32 v25, v22, v23
	v_max_f32_e32 v22, v22, v23
	v_min_f32_e32 v23, v19, v21
	v_max_f32_e32 v19, v19, v21
	v_min_f32_e32 v21, v18, v20
	v_max_f32_e32 v18, v18, v20
	v_max_f32_e32 v20, v57, v57
	v_min_f32_e32 v50, v48, v49
	v_max_f32_e32 v46, v46, v47
	v_min_f32_e32 v47, v29, v45
	v_max_f32_e32 v27, v27, v28
	v_min_f32_e32 v28, v24, v25
	v_max_f32_e32 v24, v24, v25
	v_min_f32_e32 v25, v22, v23
	v_max_f32_e32 v22, v22, v23
	v_min_f32_e32 v23, v19, v21
	v_max_f32_e32 v19, v19, v21
	v_min_f32_e32 v21, v18, v20
	v_max_f32_e32 v18, v18, v20
	v_max_f32_e32 v20, v58, v58
	v_max_f32_e32 v50, v48, v50
	v_max_f32_e32 v48, v48, v49
	v_min_f32_e32 v49, v46, v47
	v_max_f32_e32 v29, v29, v45
	v_min_f32_e32 v45, v27, v28
	v_max_f32_e32 v27, v27, v28
	v_min_f32_e32 v28, v24, v25
	v_max_f32_e32 v24, v24, v25
	v_min_f32_e32 v25, v22, v23
	v_max_f32_e32 v22, v22, v23
	v_min_f32_e32 v23, v19, v21
	v_max_f32_e32 v19, v19, v21
	v_min_f32_e32 v21, v18, v20
	v_max_f32_e32 v18, v18, v20
	v_max_f32_e32 v20, v59, v59
	v_min_f32_e32 v51, v48, v49
	v_max_f32_e32 v46, v46, v47
	v_min_f32_e32 v47, v29, v45
	v_max_f32_e32 v29, v29, v45
	v_min_f32_e32 v45, v27, v28
	v_max_f32_e32 v27, v27, v28
	v_min_f32_e32 v28, v24, v25
	v_max_f32_e32 v24, v24, v25
	v_min_f32_e32 v25, v22, v23
	v_max_f32_e32 v22, v22, v23
	v_min_f32_e32 v23, v19, v21
	v_max_f32_e32 v19, v19, v21
	v_min_f32_e32 v21, v18, v20
	v_max_f32_e32 v18, v18, v20
	v_max_f32_e32 v20, v60, v60
	v_min_f32_e32 v52, v50, v51
	v_max_f32_e32 v48, v48, v49
	v_min_f32_e32 v49, v46, v47
	v_max_f32_e32 v46, v46, v47
	v_min_f32_e32 v47, v29, v45
	v_max_f32_e32 v29, v29, v45
	v_min_f32_e32 v45, v27, v28
	v_max_f32_e32 v27, v27, v28
	v_min_f32_e32 v28, v24, v25
	v_max_f32_e32 v24, v24, v25
	v_min_f32_e32 v25, v22, v23
	v_max_f32_e32 v22, v22, v23
	v_min_f32_e32 v23, v19, v21
	v_max_f32_e32 v19, v19, v21
	v_min_f32_e32 v21, v18, v20
	v_max_f32_e32 v18, v18, v20
	v_add_f32_e32 v20, v3, v61
	v_max_f32_e32 v52, v50, v52
	v_max_f32_e32 v50, v50, v51
	v_min_f32_e32 v51, v48, v49
	v_and_or_b32 v20, v20, s78, 16
	v_min_f32_e32 v53, v50, v51
	v_max_f32_e32 v48, v48, v49
	v_min_f32_e32 v49, v46, v47
	v_min_f32_e32 v54, v52, v53
	v_max_f32_e32 v50, v50, v51
	v_min_f32_e32 v51, v48, v49
	v_max_f32_e32 v46, v46, v47
	v_min_f32_e32 v47, v29, v45
	v_max_f32_e32 v29, v29, v45
	v_min_f32_e32 v45, v27, v28
	v_max_f32_e32 v27, v27, v28
	v_min_f32_e32 v28, v24, v25
	v_max_f32_e32 v24, v24, v25
	v_min_f32_e32 v25, v22, v23
	v_max_f32_e32 v22, v22, v23
	v_min_f32_e32 v23, v19, v21
	v_max_f32_e32 v19, v19, v21
	v_min_f32_e32 v21, v18, v20
	v_max_f32_e32 v18, v18, v20
	v_max_f32_e32 v20, v154, v154
	v_max_f32_e32 v54, v52, v54
	v_max_f32_e32 v52, v52, v53
	v_min_f32_e32 v53, v50, v51
	v_max_f32_e32 v48, v48, v49
	v_min_f32_e32 v49, v46, v47
	v_max_f32_e32 v46, v46, v47
	v_min_f32_e32 v47, v29, v45
	v_max_f32_e32 v29, v29, v45
	v_min_f32_e32 v45, v27, v28
	v_max_f32_e32 v27, v27, v28
	v_min_f32_e32 v28, v24, v25
	v_max_f32_e32 v24, v24, v25
	v_min_f32_e32 v25, v22, v23
	v_max_f32_e32 v22, v22, v23
	v_min_f32_e32 v23, v19, v21
	v_max_f32_e32 v19, v19, v21
	v_min_f32_e32 v21, v18, v20
	v_max_f32_e32 v18, v18, v20
	v_max_f32_e32 v20, v205, v205
	v_min_f32_e32 v55, v52, v53
	v_max_f32_e32 v50, v50, v51
	v_min_f32_e32 v51, v48, v49
	v_max_f32_e32 v48, v48, v49
	v_min_f32_e32 v49, v46, v47
	v_max_f32_e32 v46, v46, v47
	v_min_f32_e32 v47, v29, v45
	v_max_f32_e32 v29, v29, v45
	v_min_f32_e32 v45, v27, v28
	v_max_f32_e32 v27, v27, v28
	v_min_f32_e32 v28, v24, v25
	v_max_f32_e32 v24, v24, v25
	v_min_f32_e32 v25, v22, v23
	v_max_f32_e32 v22, v22, v23
	v_min_f32_e32 v23, v19, v21
	v_max_f32_e32 v19, v19, v21
	v_min_f32_e32 v21, v18, v20
	v_max_f32_e32 v18, v18, v20
	v_max_f32_e32 v20, v206, v206
	v_min_f32_e32 v227, v54, v55
	v_max_f32_e32 v52, v52, v53
	v_min_f32_e32 v53, v50, v51
	v_max_f32_e32 v50, v50, v51
	v_min_f32_e32 v51, v48, v49
	v_max_f32_e32 v48, v48, v49
	v_min_f32_e32 v49, v46, v47
	v_max_f32_e32 v46, v46, v47
	v_min_f32_e32 v47, v29, v45
	v_max_f32_e32 v29, v29, v45
	v_min_f32_e32 v45, v27, v28
	v_max_f32_e32 v27, v27, v28
	v_min_f32_e32 v28, v24, v25
	v_max_f32_e32 v24, v24, v25
	v_min_f32_e32 v25, v22, v23
	v_max_f32_e32 v22, v22, v23
	v_min_f32_e32 v23, v19, v21
	v_max_f32_e32 v19, v19, v21
	v_min_f32_e32 v21, v18, v20
	v_max_f32_e32 v18, v18, v20
	v_max_f32_e32 v20, v207, v207
	v_max_f32_e32 v227, v54, v227
	v_max_f32_e32 v54, v54, v55
	v_min_f32_e32 v55, v52, v53
	v_max_f32_e32 v52, v52, v53
	v_min_f32_e32 v53, v50, v51
	v_max_f32_e32 v50, v50, v51
	v_min_f32_e32 v51, v48, v49
	v_max_f32_e32 v48, v48, v49
	v_min_f32_e32 v49, v46, v47
	v_max_f32_e32 v46, v46, v47
	v_min_f32_e32 v47, v29, v45
	v_max_f32_e32 v29, v29, v45
	v_min_f32_e32 v45, v27, v28
	v_max_f32_e32 v27, v27, v28
	v_min_f32_e32 v28, v24, v25
	v_max_f32_e32 v24, v24, v25
	v_min_f32_e32 v25, v22, v23
	v_max_f32_e32 v22, v22, v23
	v_min_f32_e32 v23, v19, v21
	v_max_f32_e32 v19, v19, v21
	v_min_f32_e32 v21, v18, v20
	v_max_f32_e32 v18, v18, v20
	v_max_f32_e32 v20, v44, v44
	v_min_f32_e32 v56, v54, v55
	v_max_f32_e32 v54, v54, v55
	v_min_f32_e32 v55, v52, v53
	v_max_f32_e32 v52, v52, v53
	v_min_f32_e32 v53, v50, v51
	v_max_f32_e32 v50, v50, v51
	v_min_f32_e32 v51, v48, v49
	v_max_f32_e32 v48, v48, v49
	v_min_f32_e32 v49, v46, v47
	v_max_f32_e32 v46, v46, v47
	v_min_f32_e32 v47, v29, v45
	v_max_f32_e32 v29, v29, v45
	v_min_f32_e32 v45, v27, v28
	v_max_f32_e32 v27, v27, v28
	v_min_f32_e32 v28, v24, v25
	v_max_f32_e32 v24, v24, v25
	v_min_f32_e32 v25, v22, v23
	v_max_f32_e32 v22, v22, v23
	v_min_f32_e32 v23, v19, v21
	v_max_f32_e32 v19, v19, v21
	v_min_f32_e32 v21, v18, v20
	v_max_f32_e32 v18, v18, v20
	v_max_f32_e32 v20, v43, v43
	v_min_f32_e32 v228, v227, v56
	v_max_f32_e32 v56, v227, v56
	v_min_f32_e32 v57, v54, v55
	v_max_f32_e32 v54, v54, v55
	v_min_f32_e32 v55, v52, v53
	v_max_f32_e32 v52, v52, v53
	v_min_f32_e32 v53, v50, v51
	v_max_f32_e32 v50, v50, v51
	v_min_f32_e32 v51, v48, v49
	v_max_f32_e32 v48, v48, v49
	v_min_f32_e32 v49, v46, v47
	v_max_f32_e32 v46, v46, v47
	v_min_f32_e32 v47, v29, v45
	v_max_f32_e32 v29, v29, v45
	v_min_f32_e32 v45, v27, v28
	v_max_f32_e32 v27, v27, v28
	v_min_f32_e32 v28, v24, v25
	v_max_f32_e32 v24, v24, v25
	v_min_f32_e32 v25, v22, v23
	v_max_f32_e32 v22, v22, v23
	v_min_f32_e32 v23, v19, v21
	v_max_f32_e32 v19, v19, v21
	v_min_f32_e32 v21, v18, v20
	v_max_f32_e32 v18, v18, v20
	v_max_f32_e32 v20, v42, v42
	v_max_f32_e32 v228, v227, v228
	v_min_f32_e32 v227, v56, v57
	v_max_f32_e32 v56, v56, v57
	v_min_f32_e32 v57, v54, v55
	v_max_f32_e32 v54, v54, v55
	v_min_f32_e32 v55, v52, v53
	v_max_f32_e32 v52, v52, v53
	v_min_f32_e32 v53, v50, v51
	v_max_f32_e32 v50, v50, v51
	v_min_f32_e32 v51, v48, v49
	v_max_f32_e32 v48, v48, v49
	v_min_f32_e32 v49, v46, v47
	v_max_f32_e32 v46, v46, v47
	v_min_f32_e32 v47, v29, v45
	v_max_f32_e32 v29, v29, v45
	v_min_f32_e32 v45, v27, v28
	v_max_f32_e32 v27, v27, v28
	v_min_f32_e32 v28, v24, v25
	v_max_f32_e32 v24, v24, v25
	v_min_f32_e32 v25, v22, v23
	v_max_f32_e32 v22, v22, v23
	v_min_f32_e32 v23, v19, v21
	v_max_f32_e32 v19, v19, v21
	v_min_f32_e32 v21, v18, v20
	v_max_f32_e32 v18, v18, v20
	v_add_f32_e32 v20, v3, v41
	v_and_or_b32 v20, v20, s78, 32
	v_min_f32_e32 v58, v56, v57
	v_max_f32_e32 v56, v56, v57
	v_min_f32_e32 v57, v54, v55
	v_max_f32_e32 v54, v54, v55
	v_min_f32_e32 v55, v52, v53
	v_max_f32_e32 v52, v52, v53
	v_min_f32_e32 v53, v50, v51
	v_max_f32_e32 v50, v50, v51
	v_min_f32_e32 v51, v48, v49
	v_max_f32_e32 v48, v48, v49
	v_min_f32_e32 v49, v46, v47
	v_max_f32_e32 v46, v46, v47
	v_min_f32_e32 v47, v29, v45
	v_max_f32_e32 v29, v29, v45
	v_min_f32_e32 v45, v27, v28
	v_max_f32_e32 v27, v27, v28
	v_min_f32_e32 v28, v24, v25
	v_max_f32_e32 v24, v24, v25
	v_min_f32_e32 v25, v22, v23
	v_max_f32_e32 v22, v22, v23
	v_min_f32_e32 v23, v19, v21
	v_max_f32_e32 v19, v19, v21
	v_min_f32_e32 v21, v18, v20
	v_max_f32_e32 v18, v18, v20
	v_max_f32_e32 v20, v40, v40
	v_min_f32_e32 v44, v27, v28
	v_max_f32_e32 v27, v27, v28
	v_min_f32_e32 v28, v24, v25
	v_max_f32_e32 v24, v24, v25
	v_min_f32_e32 v25, v22, v23
	v_max_f32_e32 v22, v22, v23
	v_min_f32_e32 v23, v19, v21
	v_max_f32_e32 v19, v19, v21
	v_min_f32_e32 v21, v18, v20
	v_max_f32_e32 v18, v18, v20
	v_max_f32_e32 v20, v39, v39
	v_min_f32_e32 v43, v27, v28
	v_max_f32_e32 v27, v27, v28
	v_min_f32_e32 v28, v24, v25
	v_max_f32_e32 v24, v24, v25
	v_min_f32_e32 v25, v22, v23
	v_max_f32_e32 v22, v22, v23
	v_min_f32_e32 v23, v19, v21
	v_max_f32_e32 v19, v19, v21
	v_min_f32_e32 v21, v18, v20
	v_max_f32_e32 v18, v18, v20
	v_max_f32_e32 v20, v38, v38
	v_min_f32_e32 v42, v27, v28
	v_max_f32_e32 v27, v27, v28
	v_min_f32_e32 v28, v24, v25
	v_max_f32_e32 v24, v24, v25
	v_min_f32_e32 v25, v22, v23
	v_max_f32_e32 v22, v22, v23
	v_min_f32_e32 v23, v19, v21
	v_max_f32_e32 v19, v19, v21
	v_min_f32_e32 v21, v18, v20
	v_max_f32_e32 v18, v18, v20
	v_max_f32_e32 v20, v37, v37
	v_min_f32_e32 v229, v228, v227
	v_max_f32_e32 v227, v228, v227
	v_min_f32_e32 v41, v27, v28
	v_max_f32_e32 v27, v27, v28
	v_min_f32_e32 v28, v24, v25
	v_max_f32_e32 v24, v24, v25
	v_min_f32_e32 v25, v22, v23
	v_max_f32_e32 v22, v22, v23
	v_min_f32_e32 v23, v19, v21
	v_max_f32_e32 v19, v19, v21
	v_min_f32_e32 v21, v18, v20
	v_max_f32_e32 v18, v18, v20
	v_add_f32_e32 v20, v3, v35
	v_max_f32_e32 v229, v228, v229
	v_min_f32_e32 v228, v227, v58
	v_max_f32_e32 v58, v227, v58
	v_min_f32_e32 v59, v56, v57
	v_max_f32_e32 v56, v56, v57
	v_min_f32_e32 v57, v54, v55
	v_max_f32_e32 v54, v54, v55
	v_min_f32_e32 v55, v52, v53
	v_max_f32_e32 v52, v52, v53
	v_min_f32_e32 v53, v50, v51
	v_max_f32_e32 v50, v50, v51
	v_min_f32_e32 v51, v48, v49
	v_max_f32_e32 v48, v48, v49
	v_min_f32_e32 v49, v46, v47
	v_max_f32_e32 v46, v46, v47
	v_min_f32_e32 v47, v29, v45
	v_max_f32_e32 v29, v29, v45
	v_and_or_b32 v20, v20, s78, 48
	v_min_f32_e32 v230, v229, v228
	v_max_f32_e32 v228, v229, v228
	v_min_f32_e32 v227, v58, v59
	v_max_f32_e32 v58, v58, v59
	v_min_f32_e32 v59, v56, v57
	v_max_f32_e32 v56, v56, v57
	v_min_f32_e32 v57, v54, v55
	v_max_f32_e32 v54, v54, v55
	v_min_f32_e32 v55, v52, v53
	v_max_f32_e32 v52, v52, v53
	v_min_f32_e32 v53, v50, v51
	v_max_f32_e32 v50, v50, v51
	v_min_f32_e32 v51, v48, v49
	v_max_f32_e32 v48, v48, v49
	v_min_f32_e32 v49, v46, v47
	v_max_f32_e32 v46, v46, v47
	v_min_f32_e32 v45, v29, v44
	v_max_f32_e32 v29, v29, v44
	v_max_f32_e32 v230, v229, v230
	v_min_f32_e32 v229, v228, v227
	v_max_f32_e32 v227, v228, v227
	v_min_f32_e32 v60, v58, v59
	v_max_f32_e32 v58, v58, v59
	v_min_f32_e32 v59, v56, v57
	v_max_f32_e32 v56, v56, v57
	v_min_f32_e32 v57, v54, v55
	v_max_f32_e32 v54, v54, v55
	v_min_f32_e32 v55, v52, v53
	v_max_f32_e32 v52, v52, v53
	v_min_f32_e32 v53, v50, v51
	v_max_f32_e32 v50, v50, v51
	v_min_f32_e32 v51, v48, v49
	v_max_f32_e32 v48, v48, v49
	v_min_f32_e32 v47, v46, v45
	v_max_f32_e32 v45, v46, v45
	v_min_f32_e32 v44, v29, v43
	v_max_f32_e32 v29, v29, v43
	v_min_f32_e32 v40, v27, v28
	v_max_f32_e32 v27, v27, v28
	v_min_f32_e32 v28, v24, v25
	v_max_f32_e32 v24, v24, v25
	v_min_f32_e32 v25, v22, v23
	v_max_f32_e32 v22, v22, v23
	v_min_f32_e32 v23, v19, v21
	v_max_f32_e32 v19, v19, v21
	v_min_f32_e32 v21, v18, v20
	v_max_f32_e32 v18, v18, v20
	v_max_f32_e32 v20, v33, v33
	v_min_f32_e32 v231, v230, v229
	v_max_f32_e32 v229, v230, v229
	v_min_f32_e32 v228, v227, v60
	v_max_f32_e32 v60, v227, v60
	v_min_f32_e32 v61, v58, v59
	v_max_f32_e32 v58, v58, v59
	v_min_f32_e32 v59, v56, v57
	v_max_f32_e32 v56, v56, v57
	v_min_f32_e32 v57, v54, v55
	v_max_f32_e32 v54, v54, v55
	v_min_f32_e32 v55, v52, v53
	v_max_f32_e32 v52, v52, v53
	v_min_f32_e32 v53, v50, v51
	v_max_f32_e32 v50, v50, v51
	v_min_f32_e32 v49, v48, v47
	v_max_f32_e32 v47, v48, v47
	v_min_f32_e32 v46, v45, v44
	v_max_f32_e32 v44, v45, v44
	v_min_f32_e32 v43, v29, v42
	v_max_f32_e32 v29, v29, v42
	v_min_f32_e32 v39, v27, v28
	v_max_f32_e32 v27, v27, v28
	v_min_f32_e32 v28, v24, v25
	v_max_f32_e32 v24, v24, v25
	v_min_f32_e32 v25, v22, v23
	v_max_f32_e32 v22, v22, v23
	v_min_f32_e32 v23, v19, v21
	v_max_f32_e32 v19, v19, v21
	v_min_f32_e32 v21, v18, v20
	v_max_f32_e32 v18, v18, v20
	v_max_f32_e32 v20, v32, v32
	v_min_f32_e32 v232, v229, v228
	v_max_f32_e32 v228, v229, v228
	v_min_f32_e32 v227, v60, v61
	v_max_f32_e32 v60, v60, v61
	v_min_f32_e32 v61, v58, v59
	v_max_f32_e32 v58, v58, v59
	v_min_f32_e32 v59, v56, v57
	v_max_f32_e32 v56, v56, v57
	v_min_f32_e32 v57, v54, v55
	v_max_f32_e32 v54, v54, v55
	v_min_f32_e32 v55, v52, v53
	v_max_f32_e32 v52, v52, v53
	v_min_f32_e32 v51, v50, v49
	v_max_f32_e32 v49, v50, v49
	v_min_f32_e32 v48, v47, v46
	v_max_f32_e32 v46, v47, v46
	v_min_f32_e32 v45, v44, v43
	v_max_f32_e32 v43, v44, v43
	v_min_f32_e32 v42, v29, v41
	v_max_f32_e32 v29, v29, v41
	v_min_f32_e32 v38, v27, v28
	v_max_f32_e32 v27, v27, v28
	v_min_f32_e32 v28, v24, v25
	v_max_f32_e32 v24, v24, v25
	v_min_f32_e32 v25, v22, v23
	v_max_f32_e32 v22, v22, v23
	v_min_f32_e32 v23, v19, v21
	v_max_f32_e32 v19, v19, v21
	v_min_f32_e32 v21, v18, v20
	v_max_f32_e32 v18, v18, v20
	v_max_f32_e32 v20, v31, v31
	v_min_f32_e32 v229, v228, v227
	v_max_f32_e32 v227, v228, v227
	v_min_f32_e32 v154, v60, v61
	v_max_f32_e32 v60, v60, v61
	v_min_f32_e32 v61, v58, v59
	v_max_f32_e32 v58, v58, v59
	v_min_f32_e32 v59, v56, v57
	v_max_f32_e32 v56, v56, v57
	v_min_f32_e32 v57, v54, v55
	v_max_f32_e32 v54, v54, v55
	v_min_f32_e32 v53, v52, v51
	v_max_f32_e32 v51, v52, v51
	v_min_f32_e32 v50, v49, v48
	v_max_f32_e32 v48, v49, v48
	v_min_f32_e32 v47, v46, v45
	v_max_f32_e32 v45, v46, v45
	v_min_f32_e32 v44, v43, v42
	v_max_f32_e32 v42, v43, v42
	v_min_f32_e32 v41, v29, v40
	v_max_f32_e32 v29, v29, v40
	v_min_f32_e32 v37, v27, v28
	v_max_f32_e32 v27, v27, v28
	v_min_f32_e32 v28, v24, v25
	v_max_f32_e32 v24, v24, v25
	v_min_f32_e32 v25, v22, v23
	v_max_f32_e32 v22, v22, v23
	v_min_f32_e32 v23, v19, v21
	v_max_f32_e32 v19, v19, v21
	v_min_f32_e32 v21, v18, v20
	v_max_f32_e32 v18, v18, v20
	v_add_f32_e32 v20, v3, v30
	v_min_f32_e32 v228, v227, v154
	v_max_f32_e32 v154, v227, v154
	v_min_f32_e32 v205, v60, v61
	v_max_f32_e32 v60, v60, v61
	v_min_f32_e32 v61, v58, v59
	v_max_f32_e32 v58, v58, v59
	v_min_f32_e32 v59, v56, v57
	v_max_f32_e32 v56, v56, v57
	v_min_f32_e32 v55, v54, v53
	v_max_f32_e32 v53, v54, v53
	v_min_f32_e32 v52, v51, v50
	v_max_f32_e32 v50, v51, v50
	v_min_f32_e32 v49, v48, v47
	v_max_f32_e32 v47, v48, v47
	v_min_f32_e32 v46, v45, v44
	v_max_f32_e32 v44, v45, v44
	v_min_f32_e32 v43, v42, v41
	v_max_f32_e32 v41, v42, v41
	v_min_f32_e32 v40, v29, v39
	v_max_f32_e32 v29, v29, v39
	v_and_or_b32 v20, v20, s78, 64
	v_min_f32_e32 v227, v154, v205
	v_max_f32_e32 v154, v154, v205
	v_min_f32_e32 v205, v60, v61
	v_max_f32_e32 v60, v60, v61
	v_min_f32_e32 v61, v58, v59
	v_max_f32_e32 v58, v58, v59
	v_min_f32_e32 v57, v56, v55
	v_max_f32_e32 v55, v56, v55
	v_min_f32_e32 v54, v53, v52
	v_max_f32_e32 v52, v53, v52
	v_min_f32_e32 v51, v50, v49
	v_max_f32_e32 v49, v50, v49
	v_min_f32_e32 v48, v47, v46
	v_max_f32_e32 v46, v47, v46
	v_min_f32_e32 v45, v44, v43
	v_max_f32_e32 v43, v44, v43
	v_min_f32_e32 v42, v41, v40
	v_max_f32_e32 v40, v41, v40
	v_min_f32_e32 v39, v29, v38
	v_max_f32_e32 v29, v29, v38
	v_add_f32_e32 v16, v3, v16
	v_min_f32_e32 v206, v154, v205
	v_max_f32_e32 v154, v154, v205
	v_min_f32_e32 v205, v60, v61
	v_max_f32_e32 v60, v60, v61
	v_min_f32_e32 v59, v58, v57
	v_max_f32_e32 v57, v58, v57
	v_min_f32_e32 v56, v55, v54
	v_max_f32_e32 v54, v55, v54
	v_min_f32_e32 v53, v52, v51
	v_max_f32_e32 v51, v52, v51
	v_min_f32_e32 v50, v49, v48
	v_max_f32_e32 v48, v49, v48
	v_min_f32_e32 v47, v46, v45
	v_max_f32_e32 v45, v46, v45
	v_min_f32_e32 v44, v43, v42
	v_max_f32_e32 v42, v43, v42
	v_min_f32_e32 v41, v40, v39
	v_max_f32_e32 v39, v40, v39
	v_min_f32_e32 v38, v29, v37
	v_max_f32_e32 v29, v29, v37
	v_min_f32_e32 v35, v27, v28
	v_max_f32_e32 v27, v27, v28
	v_min_f32_e32 v28, v24, v25
	v_max_f32_e32 v24, v24, v25
	v_min_f32_e32 v25, v22, v23
	v_max_f32_e32 v22, v22, v23
	v_min_f32_e32 v23, v19, v21
	v_max_f32_e32 v19, v19, v21
	v_min_f32_e32 v21, v18, v20
	v_max_f32_e32 v18, v18, v20
	v_max_f32_e32 v20, v26, v26
	v_and_b32_e32 v16, 0xffffff00, v16
	v_min_f32_e32 v207, v154, v205
	v_max_f32_e32 v154, v154, v205
	v_min_f32_e32 v61, v60, v59
	v_max_f32_e32 v59, v60, v59
	v_min_f32_e32 v58, v57, v56
	v_max_f32_e32 v56, v57, v56
	v_min_f32_e32 v55, v54, v53
	v_max_f32_e32 v53, v54, v53
	v_min_f32_e32 v52, v51, v50
	v_max_f32_e32 v50, v51, v50
	v_min_f32_e32 v49, v48, v47
	v_max_f32_e32 v47, v48, v47
	v_min_f32_e32 v46, v45, v44
	v_max_f32_e32 v44, v45, v44
	v_min_f32_e32 v43, v42, v41
	v_max_f32_e32 v41, v42, v41
	v_min_f32_e32 v40, v39, v38
	v_max_f32_e32 v38, v39, v38
	v_min_f32_e32 v37, v29, v35
	v_max_f32_e32 v29, v29, v35
	v_min_f32_e32 v33, v27, v28
	v_max_f32_e32 v27, v27, v28
	v_min_f32_e32 v28, v24, v25
	v_max_f32_e32 v24, v24, v25
	v_min_f32_e32 v25, v22, v23
	v_max_f32_e32 v22, v22, v23
	v_min_f32_e32 v23, v19, v21
	v_max_f32_e32 v19, v19, v21
	v_min_f32_e32 v21, v18, v20
	v_max_f32_e32 v18, v18, v20
	v_or_b32_e32 v16, 0x50, v16
	v_add_f32_e32 v14, v3, v14
	v_min_f32_e32 v205, v154, v61
	v_max_f32_e32 v61, v154, v61
	v_min_f32_e32 v60, v59, v58
	v_max_f32_e32 v58, v59, v58
	v_min_f32_e32 v57, v56, v55
	v_max_f32_e32 v55, v56, v55
	v_min_f32_e32 v54, v53, v52
	v_max_f32_e32 v52, v53, v52
	v_min_f32_e32 v51, v50, v49
	v_max_f32_e32 v49, v50, v49
	v_min_f32_e32 v48, v47, v46
	v_max_f32_e32 v46, v47, v46
	v_min_f32_e32 v45, v44, v43
	v_max_f32_e32 v43, v44, v43
	v_min_f32_e32 v42, v41, v40
	v_max_f32_e32 v40, v41, v40
	v_min_f32_e32 v39, v38, v37
	v_max_f32_e32 v37, v38, v37
	v_min_f32_e32 v35, v29, v33
	v_max_f32_e32 v29, v29, v33
	v_min_f32_e32 v32, v27, v28
	v_max_f32_e32 v27, v27, v28
	v_min_f32_e32 v28, v24, v25
	v_max_f32_e32 v24, v24, v25
	v_min_f32_e32 v25, v22, v23
	v_max_f32_e32 v22, v22, v23
	v_min_f32_e32 v23, v19, v21
	v_max_f32_e32 v19, v19, v21
	v_min_f32_e32 v20, v18, v17
	v_max_f32_e32 v17, v18, v17
	v_and_b32_e32 v14, 0xffffff00, v14
	v_min_f32_e32 v154, v61, v60
	v_max_f32_e32 v60, v61, v60
	v_min_f32_e32 v59, v58, v57
	v_max_f32_e32 v57, v58, v57
	v_min_f32_e32 v56, v55, v54
	v_max_f32_e32 v54, v55, v54
	v_min_f32_e32 v53, v52, v51
	v_max_f32_e32 v51, v52, v51
	v_min_f32_e32 v50, v49, v48
	v_max_f32_e32 v48, v49, v48
	v_min_f32_e32 v47, v46, v45
	v_max_f32_e32 v45, v46, v45
	v_min_f32_e32 v44, v43, v42
	v_max_f32_e32 v42, v43, v42
	v_min_f32_e32 v41, v40, v39
	v_max_f32_e32 v39, v40, v39
	v_min_f32_e32 v38, v37, v35
	v_max_f32_e32 v35, v37, v35
	v_min_f32_e32 v33, v29, v32
	v_max_f32_e32 v29, v29, v32
	v_min_f32_e32 v31, v27, v28
	v_max_f32_e32 v27, v27, v28
	v_min_f32_e32 v28, v24, v25
	v_max_f32_e32 v24, v24, v25
	v_min_f32_e32 v25, v22, v23
	v_max_f32_e32 v22, v22, v23
	v_min_f32_e32 v21, v19, v20
	v_max_f32_e32 v19, v19, v20
	v_min_f32_e32 v18, v17, v16
	v_max_f32_e32 v16, v17, v16
	v_or_b32_e32 v14, 0x60, v14
	v_add_f32_e32 v12, v3, v12
	v_min_f32_e32 v61, v60, v59
	v_max_f32_e32 v59, v60, v59
	v_min_f32_e32 v58, v57, v56
	v_max_f32_e32 v56, v57, v56
	v_min_f32_e32 v55, v54, v53
	v_max_f32_e32 v53, v54, v53
	v_min_f32_e32 v52, v51, v50
	v_max_f32_e32 v50, v51, v50
	v_min_f32_e32 v49, v48, v47
	v_max_f32_e32 v47, v48, v47
	v_min_f32_e32 v46, v45, v44
	v_max_f32_e32 v44, v45, v44
	v_min_f32_e32 v43, v42, v41
	v_max_f32_e32 v41, v42, v41
	v_min_f32_e32 v40, v39, v38
	v_max_f32_e32 v38, v39, v38
	v_min_f32_e32 v37, v35, v33
	v_max_f32_e32 v33, v35, v33
	v_min_f32_e32 v32, v29, v31
	v_max_f32_e32 v29, v29, v31
	v_min_f32_e32 v30, v27, v28
	v_max_f32_e32 v27, v27, v28
	v_min_f32_e32 v26, v24, v25
	v_max_f32_e32 v24, v24, v25
	v_min_f32_e32 v23, v22, v21
	v_max_f32_e32 v21, v22, v21
	v_min_f32_e32 v20, v19, v18
	v_max_f32_e32 v18, v19, v18
	v_min_f32_e32 v17, v16, v15
	v_max_f32_e32 v15, v16, v15
	v_and_b32_e32 v12, 0xffffff00, v12
	v_min_f32_e32 v60, v59, v58
	v_max_f32_e32 v58, v59, v58
	v_min_f32_e32 v57, v56, v55
	v_max_f32_e32 v55, v56, v55
	v_min_f32_e32 v54, v53, v52
	v_max_f32_e32 v52, v53, v52
	v_min_f32_e32 v51, v50, v49
	v_max_f32_e32 v49, v50, v49
	v_min_f32_e32 v48, v47, v46
	v_max_f32_e32 v46, v47, v46
	v_min_f32_e32 v45, v44, v43
	v_max_f32_e32 v43, v44, v43
	v_min_f32_e32 v42, v41, v40
	v_max_f32_e32 v40, v41, v40
	v_min_f32_e32 v39, v38, v37
	v_max_f32_e32 v37, v38, v37
	v_min_f32_e32 v35, v33, v32
	v_max_f32_e32 v32, v33, v32
	v_min_f32_e32 v31, v29, v30
	v_max_f32_e32 v29, v29, v30
	v_min_f32_e32 v28, v27, v26
	v_max_f32_e32 v26, v27, v26
	v_min_f32_e32 v25, v24, v23
	v_max_f32_e32 v23, v24, v23
	v_min_f32_e32 v22, v21, v20
	v_max_f32_e32 v20, v21, v20
	v_min_f32_e32 v19, v18, v17
	v_max_f32_e32 v17, v18, v17
	v_min_f32_e32 v16, v15, v14
	v_max_f32_e32 v14, v15, v14
	v_or_b32_e32 v12, 0x70, v12
	v_add_f32_e32 v10, v3, v10
	v_min_f32_e32 v59, v58, v57
	v_max_f32_e32 v57, v58, v57
	v_min_f32_e32 v56, v55, v54
	v_max_f32_e32 v54, v55, v54
	v_min_f32_e32 v53, v52, v51
	v_max_f32_e32 v51, v52, v51
	v_min_f32_e32 v50, v49, v48
	v_max_f32_e32 v48, v49, v48
	v_min_f32_e32 v47, v46, v45
	v_max_f32_e32 v45, v46, v45
	v_min_f32_e32 v44, v43, v42
	v_max_f32_e32 v42, v43, v42
	v_min_f32_e32 v41, v40, v39
	v_max_f32_e32 v39, v40, v39
	v_min_f32_e32 v38, v37, v35
	v_max_f32_e32 v35, v37, v35
	v_min_f32_e32 v33, v32, v31
	v_max_f32_e32 v31, v32, v31
	v_min_f32_e32 v30, v29, v28
	v_max_f32_e32 v28, v29, v28
	v_min_f32_e32 v27, v26, v25
	v_max_f32_e32 v25, v26, v25
	v_min_f32_e32 v24, v23, v22
	v_max_f32_e32 v22, v23, v22
	v_min_f32_e32 v21, v20, v19
	v_max_f32_e32 v19, v20, v19
	v_min_f32_e32 v18, v17, v16
	v_max_f32_e32 v16, v17, v16
	v_min_f32_e32 v15, v14, v13
	v_max_f32_e32 v13, v14, v13
	v_and_b32_e32 v10, 0xffffff00, v10
	v_add_f32_e32 v9, v3, v9
	v_min_f32_e32 v58, v57, v56
	v_max_f32_e32 v56, v57, v56
	v_min_f32_e32 v55, v54, v53
	v_max_f32_e32 v53, v54, v53
	v_min_f32_e32 v52, v51, v50
	v_max_f32_e32 v50, v51, v50
	v_min_f32_e32 v49, v48, v47
	v_max_f32_e32 v47, v48, v47
	v_min_f32_e32 v46, v45, v44
	v_max_f32_e32 v44, v45, v44
	v_min_f32_e32 v43, v42, v41
	v_max_f32_e32 v41, v42, v41
	v_min_f32_e32 v40, v39, v38
	v_max_f32_e32 v38, v39, v38
	v_min_f32_e32 v37, v35, v33
	v_max_f32_e32 v33, v35, v33
	v_min_f32_e32 v32, v31, v30
	v_max_f32_e32 v30, v31, v30
	v_min_f32_e32 v29, v28, v27
	v_max_f32_e32 v27, v28, v27
	v_min_f32_e32 v26, v25, v24
	v_max_f32_e32 v24, v25, v24
	v_min_f32_e32 v23, v22, v21
	v_max_f32_e32 v21, v22, v21
	v_min_f32_e32 v20, v19, v18
	v_max_f32_e32 v18, v19, v18
	v_min_f32_e32 v17, v16, v15
	v_max_f32_e32 v15, v16, v15
	v_min_f32_e32 v14, v13, v12
	v_max_f32_e32 v12, v13, v12
	v_or_b32_e32 v10, 0x80, v10
	v_and_b32_e32 v9, 0xffffff00, v9
	v_add_f32_e32 v8, v3, v8
	v_min_f32_e32 v57, v56, v55
	v_max_f32_e32 v55, v56, v55
	v_min_f32_e32 v54, v53, v52
	v_max_f32_e32 v52, v53, v52
	v_min_f32_e32 v51, v50, v49
	v_max_f32_e32 v49, v50, v49
	v_min_f32_e32 v48, v47, v46
	v_max_f32_e32 v46, v47, v46
	v_min_f32_e32 v45, v44, v43
	v_max_f32_e32 v43, v44, v43
	v_min_f32_e32 v42, v41, v40
	v_max_f32_e32 v40, v41, v40
	v_min_f32_e32 v39, v38, v37
	v_max_f32_e32 v37, v38, v37
	v_min_f32_e32 v35, v33, v32
	v_max_f32_e32 v32, v33, v32
	v_min_f32_e32 v31, v30, v29
	v_max_f32_e32 v29, v30, v29
	v_min_f32_e32 v28, v27, v26
	v_max_f32_e32 v26, v27, v26
	v_min_f32_e32 v25, v24, v23
	v_max_f32_e32 v23, v24, v23
	v_min_f32_e32 v22, v21, v20
	v_max_f32_e32 v20, v21, v20
	v_min_f32_e32 v19, v18, v17
	v_max_f32_e32 v17, v18, v17
	v_min_f32_e32 v16, v15, v14
	v_max_f32_e32 v14, v15, v14
	v_min_f32_e32 v13, v12, v11
	v_max_f32_e32 v11, v12, v11
	v_or_b32_e32 v9, 0x90, v9
	v_and_b32_e32 v8, 0xffffff00, v8
	v_add_f32_e32 v7, v3, v7
	v_min_f32_e32 v56, v55, v54
	v_max_f32_e32 v54, v55, v54
	v_min_f32_e32 v53, v52, v51
	v_max_f32_e32 v51, v52, v51
	v_min_f32_e32 v50, v49, v48
	v_max_f32_e32 v48, v49, v48
	v_min_f32_e32 v47, v46, v45
	v_max_f32_e32 v45, v46, v45
	v_min_f32_e32 v44, v43, v42
	v_max_f32_e32 v42, v43, v42
	v_min_f32_e32 v41, v40, v39
	v_max_f32_e32 v39, v40, v39
	v_min_f32_e32 v38, v37, v35
	v_max_f32_e32 v35, v37, v35
	v_min_f32_e32 v33, v32, v31
	v_max_f32_e32 v31, v32, v31
	v_min_f32_e32 v30, v29, v28
	v_max_f32_e32 v28, v29, v28
	v_min_f32_e32 v27, v26, v25
	v_max_f32_e32 v25, v26, v25
	v_min_f32_e32 v24, v23, v22
	v_max_f32_e32 v22, v23, v22
	v_min_f32_e32 v21, v20, v19
	v_max_f32_e32 v19, v20, v19
	v_min_f32_e32 v18, v17, v16
	v_max_f32_e32 v16, v17, v16
	v_min_f32_e32 v15, v14, v13
	v_max_f32_e32 v13, v14, v13
	v_min_f32_e32 v12, v11, v10
	v_max_f32_e32 v10, v11, v10
	v_or_b32_e32 v8, 0xa0, v8
	v_and_b32_e32 v7, 0xffffff00, v7
	v_add_f32_e32 v6, v3, v6
	v_min_f32_e32 v55, v54, v53
	v_max_f32_e32 v53, v54, v53
	v_min_f32_e32 v52, v51, v50
	v_max_f32_e32 v50, v51, v50
	v_min_f32_e32 v49, v48, v47
	v_max_f32_e32 v47, v48, v47
	v_min_f32_e32 v46, v45, v44
	v_max_f32_e32 v44, v45, v44
	v_min_f32_e32 v43, v42, v41
	v_max_f32_e32 v41, v42, v41
	v_min_f32_e32 v40, v39, v38
	v_max_f32_e32 v38, v39, v38
	v_min_f32_e32 v37, v35, v33
	v_max_f32_e32 v33, v35, v33
	v_min_f32_e32 v32, v31, v30
	v_max_f32_e32 v30, v31, v30
	v_min_f32_e32 v29, v28, v27
	v_max_f32_e32 v27, v28, v27
	v_min_f32_e32 v26, v25, v24
	v_max_f32_e32 v24, v25, v24
	v_min_f32_e32 v23, v22, v21
	v_max_f32_e32 v21, v22, v21
	v_min_f32_e32 v20, v19, v18
	v_max_f32_e32 v18, v19, v18
	v_min_f32_e32 v17, v16, v15
	v_max_f32_e32 v15, v16, v15
	v_min_f32_e32 v14, v13, v12
	v_max_f32_e32 v12, v13, v12
	v_min_f32_e32 v11, v10, v9
	v_max_f32_e32 v9, v10, v9
	v_or_b32_e32 v7, 0xb0, v7
	v_and_b32_e32 v6, 0xffffff00, v6
	v_add_f32_e32 v5, v3, v5
	v_min_f32_e32 v54, v53, v52
	v_max_f32_e32 v52, v53, v52
	v_min_f32_e32 v51, v50, v49
	v_max_f32_e32 v49, v50, v49
	v_min_f32_e32 v48, v47, v46
	v_max_f32_e32 v46, v47, v46
	v_min_f32_e32 v45, v44, v43
	v_max_f32_e32 v43, v44, v43
	v_min_f32_e32 v42, v41, v40
	v_max_f32_e32 v40, v41, v40
	v_min_f32_e32 v39, v38, v37
	v_max_f32_e32 v37, v38, v37
	v_min_f32_e32 v35, v33, v32
	v_max_f32_e32 v32, v33, v32
	v_min_f32_e32 v31, v30, v29
	v_max_f32_e32 v29, v30, v29
	v_min_f32_e32 v28, v27, v26
	v_max_f32_e32 v26, v27, v26
	v_min_f32_e32 v25, v24, v23
	v_max_f32_e32 v23, v24, v23
	v_min_f32_e32 v22, v21, v20
	v_max_f32_e32 v20, v21, v20
	v_min_f32_e32 v19, v18, v17
	v_max_f32_e32 v17, v18, v17
	v_min_f32_e32 v16, v15, v14
	v_max_f32_e32 v14, v15, v14
	v_min_f32_e32 v13, v12, v11
	v_max_f32_e32 v11, v12, v11
	v_min_f32_e32 v10, v9, v8
	v_max_f32_e32 v8, v9, v8
	v_or_b32_e32 v6, 0xc0, v6
	v_and_b32_e32 v5, 0xffffff00, v5
	v_max3_f32 v230, v230, v231, v232
	v_min_f32_e32 v53, v52, v51
	v_max_f32_e32 v51, v52, v51
	v_min_f32_e32 v50, v49, v48
	v_max_f32_e32 v48, v49, v48
	v_min_f32_e32 v47, v46, v45
	v_max_f32_e32 v45, v46, v45
	v_min_f32_e32 v44, v43, v42
	v_max_f32_e32 v42, v43, v42
	v_min_f32_e32 v41, v40, v39
	v_max_f32_e32 v39, v40, v39
	v_min_f32_e32 v38, v37, v35
	v_max_f32_e32 v35, v37, v35
	v_min_f32_e32 v33, v32, v31
	v_max_f32_e32 v31, v32, v31
	v_min_f32_e32 v30, v29, v28
	v_max_f32_e32 v28, v29, v28
	v_min_f32_e32 v27, v26, v25
	v_max_f32_e32 v25, v26, v25
	v_min_f32_e32 v24, v23, v22
	v_max_f32_e32 v22, v23, v22
	v_min_f32_e32 v21, v20, v19
	v_max_f32_e32 v19, v20, v19
	v_min_f32_e32 v18, v17, v16
	v_max_f32_e32 v16, v17, v16
	v_min_f32_e32 v15, v14, v13
	v_max_f32_e32 v13, v14, v13
	v_min_f32_e32 v12, v11, v10
	v_max_f32_e32 v10, v11, v10
	v_min_f32_e32 v9, v8, v7
	v_max_f32_e32 v7, v8, v7
	v_or_b32_e32 v5, 0xd0, v5
	v_max3_f32 v228, v230, v229, v228
	v_min_f32_e32 v52, v51, v50
	v_max_f32_e32 v50, v51, v50
	v_min_f32_e32 v49, v48, v47
	v_max_f32_e32 v47, v48, v47
	v_min_f32_e32 v46, v45, v44
	v_max_f32_e32 v44, v45, v44
	v_min_f32_e32 v43, v42, v41
	v_max_f32_e32 v41, v42, v41
	v_min_f32_e32 v40, v39, v38
	v_max_f32_e32 v38, v39, v38
	v_min_f32_e32 v37, v35, v33
	v_max_f32_e32 v33, v35, v33
	v_min_f32_e32 v32, v31, v30
	v_max_f32_e32 v30, v31, v30
	v_min_f32_e32 v29, v28, v27
	v_max_f32_e32 v27, v28, v27
	v_min_f32_e32 v26, v25, v24
	v_max_f32_e32 v24, v25, v24
	v_min_f32_e32 v23, v22, v21
	v_max_f32_e32 v21, v22, v21
	v_min_f32_e32 v20, v19, v18
	v_max_f32_e32 v18, v19, v18
	v_min_f32_e32 v17, v16, v15
	v_max_f32_e32 v15, v16, v15
	v_min_f32_e32 v14, v13, v12
	v_max_f32_e32 v12, v13, v12
	v_min_f32_e32 v11, v10, v9
	v_max_f32_e32 v9, v10, v9
	v_min_f32_e32 v8, v7, v6
	v_max_f32_e32 v6, v7, v6
	v_max3_f32 v206, v228, v227, v206
	v_min_f32_e32 v51, v50, v49
	v_max_f32_e32 v49, v50, v49
	v_min_f32_e32 v48, v47, v46
	v_max_f32_e32 v46, v47, v46
	v_min_f32_e32 v45, v44, v43
	v_max_f32_e32 v43, v44, v43
	v_min_f32_e32 v42, v41, v40
	v_max_f32_e32 v40, v41, v40
	v_min_f32_e32 v39, v38, v37
	v_max_f32_e32 v37, v38, v37
	v_min_f32_e32 v35, v33, v32
	v_max_f32_e32 v32, v33, v32
	v_min_f32_e32 v31, v30, v29
	v_max_f32_e32 v29, v30, v29
	v_min_f32_e32 v28, v27, v26
	v_max_f32_e32 v26, v27, v26
	v_min_f32_e32 v25, v24, v23
	v_max_f32_e32 v23, v24, v23
	v_min_f32_e32 v22, v21, v20
	v_max_f32_e32 v20, v21, v20
	v_min_f32_e32 v19, v18, v17
	v_max_f32_e32 v17, v18, v17
	v_min_f32_e32 v16, v15, v14
	v_max_f32_e32 v14, v15, v14
	v_min_f32_e32 v13, v12, v11
	v_max_f32_e32 v11, v12, v11
	v_min_f32_e32 v10, v9, v8
	v_max_f32_e32 v8, v9, v8
	v_min_f32_e32 v7, v6, v5
	v_add_f32_e32 v4, v3, v4
	v_max3_f32 v205, v206, v207, v205
	v_min_f32_e32 v50, v49, v48
	v_max_f32_e32 v48, v49, v48
	v_min_f32_e32 v47, v46, v45
	v_max_f32_e32 v45, v46, v45
	v_min_f32_e32 v44, v43, v42
	v_max_f32_e32 v42, v43, v42
	v_min_f32_e32 v41, v40, v39
	v_max_f32_e32 v39, v40, v39
	v_min_f32_e32 v38, v37, v35
	v_max_f32_e32 v35, v37, v35
	v_min_f32_e32 v33, v32, v31
	v_max_f32_e32 v31, v32, v31
	v_min_f32_e32 v30, v29, v28
	v_max_f32_e32 v28, v29, v28
	v_min_f32_e32 v27, v26, v25
	v_max_f32_e32 v25, v26, v25
	v_min_f32_e32 v24, v23, v22
	v_max_f32_e32 v22, v23, v22
	v_min_f32_e32 v21, v20, v19
	v_max_f32_e32 v19, v20, v19
	v_min_f32_e32 v18, v17, v16
	v_max_f32_e32 v16, v17, v16
	v_min_f32_e32 v15, v14, v13
	v_max_f32_e32 v13, v14, v13
	v_min_f32_e32 v12, v11, v10
	v_max_f32_e32 v10, v11, v10
	v_min_f32_e32 v9, v8, v7
	v_and_b32_e32 v4, 0xffffff00, v4
	v_max3_f32 v61, v205, v154, v61
	v_min_f32_e32 v49, v48, v47
	v_max_f32_e32 v47, v48, v47
	v_min_f32_e32 v46, v45, v44
	v_max_f32_e32 v44, v45, v44
	v_min_f32_e32 v43, v42, v41
	v_max_f32_e32 v41, v42, v41
	v_min_f32_e32 v40, v39, v38
	v_max_f32_e32 v38, v39, v38
	v_min_f32_e32 v37, v35, v33
	v_max_f32_e32 v33, v35, v33
	v_min_f32_e32 v32, v31, v30
	v_max_f32_e32 v30, v31, v30
	v_min_f32_e32 v29, v28, v27
	v_max_f32_e32 v27, v28, v27
	v_min_f32_e32 v26, v25, v24
	v_max_f32_e32 v24, v25, v24
	v_min_f32_e32 v23, v22, v21
	v_max_f32_e32 v21, v22, v21
	v_min_f32_e32 v20, v19, v18
	v_max_f32_e32 v18, v19, v18
	v_min_f32_e32 v17, v16, v15
	v_max_f32_e32 v15, v16, v15
	v_min_f32_e32 v14, v13, v12
	v_max_f32_e32 v12, v13, v12
	v_min_f32_e32 v11, v10, v9
	v_or_b32_e32 v4, 0xe0, v4
	v_max3_f32 v59, v61, v60, v59
	v_min_f32_e32 v48, v47, v46
	v_max_f32_e32 v46, v47, v46
	v_min_f32_e32 v45, v44, v43
	v_max_f32_e32 v43, v44, v43
	v_min_f32_e32 v42, v41, v40
	v_max_f32_e32 v40, v41, v40
	v_min_f32_e32 v39, v38, v37
	v_max_f32_e32 v37, v38, v37
	v_min_f32_e32 v35, v33, v32
	v_max_f32_e32 v32, v33, v32
	v_min_f32_e32 v31, v30, v29
	v_max_f32_e32 v29, v30, v29
	v_min_f32_e32 v28, v27, v26
	v_max_f32_e32 v26, v27, v26
	v_min_f32_e32 v25, v24, v23
	v_max_f32_e32 v23, v24, v23
	v_min_f32_e32 v22, v21, v20
	v_max_f32_e32 v20, v21, v20
	v_min_f32_e32 v19, v18, v17
	v_max_f32_e32 v17, v18, v17
	v_min_f32_e32 v16, v15, v14
	v_max_f32_e32 v14, v15, v14
	v_min_f32_e32 v13, v12, v11
	v_max_f32_e32 v5, v6, v5
	v_max3_f32 v57, v59, v58, v57
	v_min_f32_e32 v47, v46, v45
	v_max_f32_e32 v45, v46, v45
	v_min_f32_e32 v44, v43, v42
	v_max_f32_e32 v42, v43, v42
	v_min_f32_e32 v41, v40, v39
	v_max_f32_e32 v39, v40, v39
	v_min_f32_e32 v38, v37, v35
	v_max_f32_e32 v35, v37, v35
	v_min_f32_e32 v33, v32, v31
	v_max_f32_e32 v31, v32, v31
	v_min_f32_e32 v30, v29, v28
	v_max_f32_e32 v28, v29, v28
	v_min_f32_e32 v27, v26, v25
	v_max_f32_e32 v25, v26, v25
	v_min_f32_e32 v24, v23, v22
	v_max_f32_e32 v22, v23, v22
	v_min_f32_e32 v21, v20, v19
	v_max_f32_e32 v19, v20, v19
	v_min_f32_e32 v18, v17, v16
	v_max_f32_e32 v16, v17, v16
	v_min_f32_e32 v15, v14, v13
	v_max_f32_e32 v7, v8, v7
	v_min_f32_e32 v6, v5, v4
	v_max3_f32 v55, v57, v56, v55
	v_min_f32_e32 v46, v45, v44
	v_max_f32_e32 v44, v45, v44
	v_min_f32_e32 v43, v42, v41
	v_max_f32_e32 v41, v42, v41
	v_min_f32_e32 v40, v39, v38
	v_max_f32_e32 v38, v39, v38
	v_min_f32_e32 v37, v35, v33
	v_max_f32_e32 v33, v35, v33
	v_min_f32_e32 v32, v31, v30
	v_max_f32_e32 v30, v31, v30
	v_min_f32_e32 v29, v28, v27
	v_max_f32_e32 v27, v28, v27
	v_min_f32_e32 v26, v25, v24
	v_max_f32_e32 v24, v25, v24
	v_min_f32_e32 v23, v22, v21
	v_max_f32_e32 v21, v22, v21
	v_min_f32_e32 v20, v19, v18
	v_max_f32_e32 v18, v19, v18
	v_min_f32_e32 v17, v16, v15
	v_max_f32_e32 v9, v10, v9
	v_min_f32_e32 v8, v7, v6
	v_max3_f32 v53, v55, v54, v53
	v_min_f32_e32 v45, v44, v43
	v_max_f32_e32 v43, v44, v43
	v_min_f32_e32 v42, v41, v40
	v_max_f32_e32 v40, v41, v40
	v_min_f32_e32 v39, v38, v37
	v_max_f32_e32 v37, v38, v37
	v_min_f32_e32 v35, v33, v32
	v_max_f32_e32 v32, v33, v32
	v_min_f32_e32 v31, v30, v29
	v_max_f32_e32 v29, v30, v29
	v_min_f32_e32 v28, v27, v26
	v_max_f32_e32 v26, v27, v26
	v_min_f32_e32 v25, v24, v23
	v_max_f32_e32 v23, v24, v23
	v_min_f32_e32 v22, v21, v20
	v_max_f32_e32 v20, v21, v20
	v_min_f32_e32 v19, v18, v17
	v_max_f32_e32 v11, v12, v11
	v_min_f32_e32 v10, v9, v8
	v_max3_f32 v51, v53, v52, v51
	v_min_f32_e32 v44, v43, v42
	v_max_f32_e32 v42, v43, v42
	v_min_f32_e32 v41, v40, v39
	v_max_f32_e32 v39, v40, v39
	v_min_f32_e32 v38, v37, v35
	v_max_f32_e32 v35, v37, v35
	v_min_f32_e32 v33, v32, v31
	v_max_f32_e32 v31, v32, v31
	v_min_f32_e32 v30, v29, v28
	v_max_f32_e32 v28, v29, v28
	v_min_f32_e32 v27, v26, v25
	v_max_f32_e32 v25, v26, v25
	v_min_f32_e32 v24, v23, v22
	v_max_f32_e32 v22, v23, v22
	v_min_f32_e32 v21, v20, v19
	v_max_f32_e32 v13, v14, v13
	v_min_f32_e32 v12, v11, v10
	v_max3_f32 v49, v51, v50, v49
	v_min_f32_e32 v43, v42, v41
	v_max_f32_e32 v41, v42, v41
	v_min_f32_e32 v40, v39, v38
	v_max_f32_e32 v38, v39, v38
	v_min_f32_e32 v37, v35, v33
	v_max_f32_e32 v33, v35, v33
	v_min_f32_e32 v32, v31, v30
	v_max_f32_e32 v30, v31, v30
	v_min_f32_e32 v29, v28, v27
	v_max_f32_e32 v27, v28, v27
	v_min_f32_e32 v26, v25, v24
	v_max_f32_e32 v24, v25, v24
	v_min_f32_e32 v23, v22, v21
	v_max_f32_e32 v15, v16, v15
	v_min_f32_e32 v14, v13, v12
	v_max3_f32 v47, v49, v48, v47
	v_min_f32_e32 v42, v41, v40
	v_max_f32_e32 v40, v41, v40
	v_min_f32_e32 v39, v38, v37
	v_max_f32_e32 v37, v38, v37
	v_min_f32_e32 v35, v33, v32
	v_max_f32_e32 v32, v33, v32
	v_min_f32_e32 v31, v30, v29
	v_max_f32_e32 v29, v30, v29
	v_min_f32_e32 v28, v27, v26
	v_max_f32_e32 v26, v27, v26
	v_min_f32_e32 v25, v24, v23
	v_max_f32_e32 v17, v18, v17
	v_min_f32_e32 v16, v15, v14
	v_pk_add_f32 v[2:3], v[2:3], v[2:3] op_sel:[1,0] op_sel_hi:[0,1]
	v_max3_f32 v45, v47, v46, v45
	v_min_f32_e32 v41, v40, v39
	v_max_f32_e32 v39, v40, v39
	v_min_f32_e32 v38, v37, v35
	v_max_f32_e32 v35, v37, v35
	v_min_f32_e32 v33, v32, v31
	v_max_f32_e32 v31, v32, v31
	v_min_f32_e32 v30, v29, v28
	v_max_f32_e32 v28, v29, v28
	v_min_f32_e32 v27, v26, v25
	v_max_f32_e32 v19, v20, v19
	v_min_f32_e32 v18, v17, v16
	v_and_b32_e32 v2, 0xffffff00, v2
	v_max3_f32 v43, v45, v44, v43
	v_min_f32_e32 v40, v39, v38
	v_max_f32_e32 v38, v39, v38
	v_min_f32_e32 v37, v35, v33
	v_max_f32_e32 v33, v35, v33
	v_min_f32_e32 v32, v31, v30
	v_max_f32_e32 v30, v31, v30
	v_min_f32_e32 v29, v28, v27
	v_max_f32_e32 v21, v22, v21
	v_min_f32_e32 v20, v19, v18
	v_or_b32_e32 v2, 0xf0, v2
	v_max3_f32 v41, v43, v42, v41
	v_min_f32_e32 v39, v38, v37
	v_max_f32_e32 v37, v38, v37
	v_min_f32_e32 v35, v33, v32
	v_max_f32_e32 v32, v33, v32
	v_min_f32_e32 v31, v30, v29
	v_max_f32_e32 v23, v24, v23
	v_min_f32_e32 v22, v21, v20
	v_max_f32_e32 v4, v5, v4
	v_max3_f32 v39, v41, v40, v39
	v_min_f32_e32 v38, v37, v35
	v_max_f32_e32 v35, v37, v35
	v_min_f32_e32 v33, v32, v31
	v_max_f32_e32 v25, v26, v25
	v_min_f32_e32 v24, v23, v22
	v_max_f32_e32 v6, v7, v6
	v_max_f32_e32 v41, v4, v2
	v_min_f32_e32 v2, v4, v2
	v_min_f32_e32 v37, v35, v33
	v_max_f32_e32 v27, v28, v27
	v_min_f32_e32 v26, v25, v24
	v_max_f32_e32 v8, v9, v8
	v_max_f32_e32 v40, v6, v2
	v_min_f32_e32 v2, v6, v2
	v_max3_f32 v42, v39, v38, v37
	v_max_f32_e32 v29, v30, v29
	v_min_f32_e32 v28, v27, v26
	v_max_f32_e32 v10, v11, v10
	v_max_f32_e32 v39, v8, v2
	v_min_f32_e32 v2, v8, v2
	v_max_f32_e32 v31, v32, v31
	v_min_f32_e32 v30, v29, v28
	v_max_f32_e32 v12, v13, v12
	v_max_f32_e32 v38, v10, v2
	v_min_f32_e32 v2, v10, v2
	v_max_f32_e32 v33, v35, v33
	v_min_f32_e32 v32, v31, v30
	v_max_f32_e32 v14, v15, v14
	v_max_f32_e32 v37, v12, v2
	v_min_f32_e32 v2, v12, v2
	v_min_f32_e32 v35, v33, v32
	v_max_f32_e32 v43, v33, v32
	v_max_f32_e32 v16, v17, v16
	v_max_f32_e32 v33, v14, v2
	v_min_f32_e32 v2, v14, v2
	v_max_f32_e32 v18, v19, v18
	v_max_f32_e32 v32, v16, v2
	v_min_f32_e32 v2, v16, v2
	v_max_f32_e32 v44, v31, v30
	v_max_f32_e32 v20, v21, v20
	v_max_f32_e32 v31, v18, v2
	v_min_f32_e32 v2, v18, v2
	v_max_f32_e32 v22, v23, v22
	v_max_f32_e32 v30, v20, v2
	v_min_f32_e32 v2, v20, v2
	v_max_f32_e32 v45, v29, v28
	v_max_f32_e32 v24, v25, v24
	v_max_f32_e32 v29, v22, v2
	v_min_f32_e32 v2, v22, v2
	v_max_f32_e32 v26, v27, v26
	v_max_f32_e32 v28, v24, v2
	v_min_f32_e32 v2, v24, v2
	v_max_f32_e32 v27, v26, v2
	v_min_f32_e32 v2, v26, v2
	v_max_f32_e32 v26, v45, v2
	v_min_f32_e32 v2, v45, v2
	v_max_f32_e32 v25, v44, v2
	v_min_f32_e32 v2, v44, v2
	v_max_f32_e32 v24, v43, v2
	v_min_f32_e32 v2, v43, v2
	v_and_b32_e32 v17, 0xffffff00, v41
	v_max3_f32 v19, v42, v35, v2
	v_sub_f32_e32 v2, v17, v17
	v_mul_f32_e32 v6, 0x3fb8aa3b, v2
	v_fma_f32 v7, v2, s79, -v6
	v_rndne_f32_e32 v22, v6
	v_fmac_f32_e32 v7, 0x32a5705f, v2
	v_sub_f32_e32 v6, v6, v22
	v_add_f32_e32 v6, v6, v7
	v_exp_f32_e32 v6, v6
	v_cvt_i32_f32_e32 v7, v22
	v_and_b32_e32 v3, 0xffffff00, v40
	v_cmp_ngt_f32_e32 vcc, s80, v2
	v_sub_f32_e32 v3, v3, v17
	v_ldexp_f32 v6, v6, v7
	v_cndmask_b32_e32 v6, 0, v6, vcc
	v_cmp_nlt_f32_e32 vcc, s81, v2
	v_and_b32_e32 v4, 0xffffff00, v39
	v_sub_f32_e32 v4, v4, v17
	v_cndmask_b32_e32 v2, v217, v6, vcc
	v_mul_f32_e32 v6, 0x3fb8aa3b, v3
	v_fma_f32 v7, v3, s79, -v6
	v_rndne_f32_e32 v22, v6
	v_fmac_f32_e32 v7, 0x32a5705f, v3
	v_sub_f32_e32 v6, v6, v22
	v_add_f32_e32 v6, v6, v7
	v_exp_f32_e32 v6, v6
	v_cvt_i32_f32_e32 v7, v22
	v_cmp_ngt_f32_e32 vcc, s80, v3
	v_and_b32_e32 v5, 0xffffff00, v38
	v_sub_f32_e32 v5, v5, v17
	v_ldexp_f32 v6, v6, v7
	v_cndmask_b32_e32 v6, 0, v6, vcc
	v_cmp_nlt_f32_e32 vcc, s81, v3
	v_and_b32_e32 v8, 0xffffff00, v37
	v_and_b32_e32 v9, 0xffffff00, v33
	v_cndmask_b32_e32 v3, v217, v6, vcc
	v_mul_f32_e32 v6, 0x3fb8aa3b, v4
	v_fma_f32 v22, v4, s79, -v6
	v_rndne_f32_e32 v23, v6
	v_fmac_f32_e32 v22, 0x32a5705f, v4
	v_sub_f32_e32 v6, v6, v23
	v_add_f32_e32 v6, v6, v22
	v_exp_f32_e32 v6, v6
	v_cvt_i32_f32_e32 v22, v23
	v_cmp_ngt_f32_e32 vcc, s80, v4
	v_add_f32_e32 v7, v2, v3
	v_and_b32_e32 v10, 0xffffff00, v32
	v_ldexp_f32 v6, v6, v22
	v_cndmask_b32_e32 v6, 0, v6, vcc
	v_cmp_nlt_f32_e32 vcc, s81, v4
	v_and_b32_e32 v11, 0xffffff00, v31
	v_and_b32_e32 v12, 0xffffff00, v30
	v_cndmask_b32_e32 v6, v217, v6, vcc
	v_add_f32_e32 v4, v7, v6
	v_mul_f32_e32 v7, 0x3fb8aa3b, v5
	v_fma_f32 v22, v5, s79, -v7
	v_rndne_f32_e32 v23, v7
	v_fmac_f32_e32 v22, 0x32a5705f, v5
	v_sub_f32_e32 v7, v7, v23
	v_add_f32_e32 v7, v7, v22
	v_exp_f32_e32 v7, v7
	v_cvt_i32_f32_e32 v22, v23
	v_cmp_ngt_f32_e32 vcc, s80, v5
	v_and_b32_e32 v14, 0xffffff00, v29
	v_and_b32_e32 v15, 0xffffff00, v28
	v_ldexp_f32 v7, v7, v22
	v_cndmask_b32_e32 v7, 0, v7, vcc
	v_cmp_nlt_f32_e32 vcc, s81, v5
	v_and_b32_e32 v20, 0xffffff00, v27
	v_and_b32_e32 v21, 0xffffff00, v26
	v_cndmask_b32_e32 v7, v217, v7, vcc
	v_add_f32_e32 v5, v4, v7
	v_sub_f32_e32 v4, v8, v17
	v_mul_f32_e32 v8, 0x3fb8aa3b, v4
	v_fma_f32 v22, v4, s79, -v8
	v_rndne_f32_e32 v23, v8
	v_fmac_f32_e32 v22, 0x32a5705f, v4
	v_sub_f32_e32 v8, v8, v23
	v_add_f32_e32 v8, v8, v22
	v_exp_f32_e32 v8, v8
	v_cvt_i32_f32_e32 v22, v23
	v_cmp_ngt_f32_e32 vcc, s80, v4
	v_and_b32_e32 v13, 0xffffff00, v25
	v_sub_f32_e32 v13, v13, v17
	v_ldexp_f32 v8, v8, v22
	v_cndmask_b32_e32 v8, 0, v8, vcc
	v_cmp_nlt_f32_e32 vcc, s81, v4
	v_and_b32_e32 v16, 0xffffff00, v24
	v_sub_f32_e32 v16, v16, v17
	v_cndmask_b32_e32 v4, v217, v8, vcc
	v_add_f32_e32 v8, v5, v4
	v_sub_f32_e32 v5, v9, v17
	v_mul_f32_e32 v9, 0x3fb8aa3b, v5
	v_fma_f32 v22, v5, s79, -v9
	v_rndne_f32_e32 v23, v9
	v_fmac_f32_e32 v22, 0x32a5705f, v5
	v_sub_f32_e32 v9, v9, v23
	v_add_f32_e32 v9, v9, v22
	v_exp_f32_e32 v9, v9
	v_cvt_i32_f32_e32 v22, v23
	v_cmp_ngt_f32_e32 vcc, s80, v5
	v_and_b32_e32 v18, 0xffffff00, v19
	s_mov_b32 s10, s42
	v_ldexp_f32 v9, v9, v22
	v_cndmask_b32_e32 v9, 0, v9, vcc
	v_cmp_nlt_f32_e32 vcc, s81, v5
	v_or_b32_e32 v34, s10, v34
	v_lshrrev_b32_e32 v42, 2, v39
	v_cndmask_b32_e32 v5, v217, v9, vcc
	v_sub_f32_e32 v9, v10, v17
	v_mul_f32_e32 v10, 0x3fb8aa3b, v9
	v_fma_f32 v22, v9, s79, -v10
	v_rndne_f32_e32 v23, v10
	v_fmac_f32_e32 v22, 0x32a5705f, v9
	v_sub_f32_e32 v10, v10, v23
	v_add_f32_e32 v10, v10, v22
	v_exp_f32_e32 v10, v10
	v_cvt_i32_f32_e32 v22, v23
	v_cmp_ngt_f32_e32 vcc, s80, v9
	v_add_f32_e32 v8, v8, v5
	v_and_b32_e32 v39, 15, v39
	v_ldexp_f32 v10, v10, v22
	v_cndmask_b32_e32 v10, 0, v10, vcc
	v_cmp_nlt_f32_e32 vcc, s81, v9
	v_sub_f32_e32 v9, v11, v17
	v_mul_f32_e32 v11, 0x3fb8aa3b, v9
	v_fma_f32 v22, v9, s79, -v11
	v_rndne_f32_e32 v23, v11
	v_fmac_f32_e32 v22, 0x32a5705f, v9
	v_sub_f32_e32 v11, v11, v23
	v_add_f32_e32 v11, v11, v22
	v_exp_f32_e32 v11, v11
	v_cvt_i32_f32_e32 v22, v23
	v_cndmask_b32_e32 v10, v217, v10, vcc
	v_cmp_ngt_f32_e32 vcc, s80, v9
	v_add_f32_e32 v8, v8, v10
	v_ldexp_f32 v11, v11, v22
	v_cndmask_b32_e32 v11, 0, v11, vcc
	v_cmp_nlt_f32_e32 vcc, s81, v9
	v_lshl_add_u32 v39, v39, 2, v36
	ds_read_b32 v43, v39 offset:64
	v_cndmask_b32_e32 v11, v217, v11, vcc
	v_add_f32_e32 v9, v8, v11
	v_sub_f32_e32 v8, v12, v17
	v_mul_f32_e32 v12, 0x3fb8aa3b, v8
	v_fma_f32 v22, v8, s79, -v12
	v_rndne_f32_e32 v23, v12
	v_fmac_f32_e32 v22, 0x32a5705f, v8
	v_sub_f32_e32 v12, v12, v23
	v_add_f32_e32 v12, v12, v22
	v_exp_f32_e32 v12, v12
	v_cvt_i32_f32_e32 v22, v23
	v_cmp_ngt_f32_e32 vcc, s80, v8
	v_lshrrev_b32_e32 v39, 2, v38
	v_and_b32_e32 v42, 60, v42
	v_ldexp_f32 v12, v12, v22
	v_cndmask_b32_e32 v12, 0, v12, vcc
	v_cmp_nlt_f32_e32 vcc, s81, v8
	v_and_b32_e32 v39, 60, v39
	v_add_u32_e32 v42, v36, v42
	v_cndmask_b32_e32 v8, v217, v12, vcc
	v_add_f32_e32 v12, v9, v8
	v_sub_f32_e32 v9, v14, v17
	v_mul_f32_e32 v14, 0x3fb8aa3b, v9
	v_fma_f32 v22, v9, s79, -v14
	v_rndne_f32_e32 v23, v14
	v_fmac_f32_e32 v22, 0x32a5705f, v9
	v_sub_f32_e32 v14, v14, v23
	v_add_f32_e32 v14, v14, v22
	v_exp_f32_e32 v14, v14
	v_cvt_i32_f32_e32 v22, v23
	v_cmp_ngt_f32_e32 vcc, s80, v9
	v_add_u32_e32 v39, v36, v39
	v_and_b32_e32 v38, 15, v38
	v_ldexp_f32 v14, v14, v22
	v_cndmask_b32_e32 v14, 0, v14, vcc
	v_cmp_nlt_f32_e32 vcc, s81, v9
	ds_read_b32 v42, v42
	ds_read_b32 v44, v39
	v_cndmask_b32_e32 v9, v217, v14, vcc
	v_sub_f32_e32 v14, v15, v17
	v_mul_f32_e32 v15, 0x3fb8aa3b, v14
	v_fma_f32 v22, v14, s79, -v15
	v_rndne_f32_e32 v23, v15
	v_fmac_f32_e32 v22, 0x32a5705f, v14
	v_sub_f32_e32 v15, v15, v23
	v_add_f32_e32 v15, v15, v22
	v_exp_f32_e32 v15, v15
	v_cvt_i32_f32_e32 v22, v23
	v_cmp_ngt_f32_e32 vcc, s80, v14
	v_add_f32_e32 v12, v12, v9
	v_lshl_add_u32 v38, v38, 2, v36
	v_ldexp_f32 v15, v15, v22
	v_cndmask_b32_e32 v15, 0, v15, vcc
	v_cmp_nlt_f32_e32 vcc, s81, v14
	ds_read_b32 v45, v38 offset:64
	s_nop 0
	v_cndmask_b32_e32 v14, v217, v15, vcc
	v_sub_f32_e32 v15, v20, v17
	v_mul_f32_e32 v20, 0x3fb8aa3b, v15
	v_fma_f32 v22, v15, s79, -v20
	v_rndne_f32_e32 v23, v20
	v_fmac_f32_e32 v22, 0x32a5705f, v15
	v_sub_f32_e32 v20, v20, v23
	v_add_f32_e32 v20, v20, v22
	v_exp_f32_e32 v20, v20
	v_cvt_i32_f32_e32 v22, v23
	v_cmp_ngt_f32_e32 vcc, s80, v15
	v_add_f32_e32 v12, v12, v14
	v_ldexp_f32 v20, v20, v22
	v_cndmask_b32_e32 v20, 0, v20, vcc
	v_cmp_nlt_f32_e32 vcc, s81, v15
	s_nop 1
	v_cndmask_b32_e32 v15, v217, v20, vcc
	v_add_f32_e32 v20, v12, v15
	v_sub_f32_e32 v12, v21, v17
	v_mul_f32_e32 v21, 0x3fb8aa3b, v12
	v_fma_f32 v22, v12, s79, -v21
	v_rndne_f32_e32 v23, v21
	v_fmac_f32_e32 v22, 0x32a5705f, v12
	v_sub_f32_e32 v21, v21, v23
	v_add_f32_e32 v21, v21, v22
	v_exp_f32_e32 v21, v21
	v_cvt_i32_f32_e32 v22, v23
	v_cmp_ngt_f32_e32 vcc, s80, v12
	v_sub_f32_e32 v17, v18, v17
	v_mul_f32_e32 v18, 0x3fb8aa3b, v17
	v_ldexp_f32 v21, v21, v22
	v_cndmask_b32_e32 v21, 0, v21, vcc
	v_cmp_nlt_f32_e32 vcc, s81, v12
	s_nop 1
	v_cndmask_b32_e32 v12, v217, v21, vcc
	v_mul_f32_e32 v21, 0x3fb8aa3b, v13
	v_fma_f32 v22, v13, s79, -v21
	v_rndne_f32_e32 v23, v21
	v_fmac_f32_e32 v22, 0x32a5705f, v13
	v_sub_f32_e32 v21, v21, v23
	v_add_f32_e32 v21, v21, v22
	v_exp_f32_e32 v21, v21
	v_cvt_i32_f32_e32 v22, v23
	v_cmp_ngt_f32_e32 vcc, s80, v13
	v_add_f32_e32 v20, v20, v12
	v_ldexp_f32 v21, v21, v22
	v_cndmask_b32_e32 v21, 0, v21, vcc
	v_cmp_nlt_f32_e32 vcc, s81, v13
	s_nop 1
	v_cndmask_b32_e32 v13, v217, v21, vcc
	v_mul_f32_e32 v21, 0x3fb8aa3b, v16
	v_fma_f32 v22, v16, s79, -v21
	v_rndne_f32_e32 v23, v21
	v_fmac_f32_e32 v22, 0x32a5705f, v16
	v_sub_f32_e32 v21, v21, v23
	v_add_f32_e32 v21, v21, v22
	v_exp_f32_e32 v21, v21
	v_cvt_i32_f32_e32 v22, v23
	v_cmp_ngt_f32_e32 vcc, s80, v16
	v_add_f32_e32 v20, v20, v13
	v_ldexp_f32 v21, v21, v22
	v_cndmask_b32_e32 v21, 0, v21, vcc
	v_cmp_nlt_f32_e32 vcc, s81, v16
	v_rndne_f32_e32 v22, v18
	s_nop 0
	v_cndmask_b32_e32 v16, v217, v21, vcc
	v_fma_f32 v21, v17, s79, -v18
	v_fmac_f32_e32 v21, 0x32a5705f, v17
	v_sub_f32_e32 v18, v18, v22
	v_add_f32_e32 v18, v18, v21
	v_exp_f32_e32 v18, v18
	v_cvt_i32_f32_e32 v21, v22
	v_cmp_ngt_f32_e32 vcc, s80, v17
	v_add_f32_e32 v20, v20, v16
	v_ldexp_f32 v18, v18, v21
	v_cndmask_b32_e32 v18, 0, v18, vcc
	v_cmp_nlt_f32_e32 vcc, s81, v17
	s_nop 1
	v_cndmask_b32_e32 v17, v217, v18, vcc
	v_add_f32_e32 v18, v20, v17
	v_div_scale_f32 v20, s[10:11], v18, v18, 1.0
	v_rcp_f32_e32 v21, v20
	s_nop 0
	v_fma_f32 v22, -v20, v21, 1.0
	v_fmac_f32_e32 v21, v22, v21
	v_div_scale_f32 v22, vcc, 1.0, v18, 1.0
	v_mul_f32_e32 v23, v22, v21
	v_fma_f32 v35, -v20, v23, v22
	v_fmac_f32_e32 v23, v35, v21
	v_fma_f32 v20, -v20, v23, v22
	v_div_fmas_f32 v20, v20, v21, v23
	v_ashrrev_i32_e32 v35, 31, v34
	v_div_fixup_f32 v18, v20, v18, 1.0
	v_lshlrev_b64 v[20:21], 9, v[34:35]
	v_lshrrev_b32_e32 v34, 2, v41
	v_and_b32_e32 v35, 15, v41
	v_lshrrev_b32_e32 v41, 2, v40
	v_and_b32_e32 v41, 60, v41
	v_add_u32_e32 v41, v36, v41
	v_and_b32_e32 v34, 60, v34
	ds_read_b32 v41, v41
	v_add_u32_e32 v34, v36, v34
	v_and_b32_e32 v40, 15, v40
	ds_read_b32 v34, v34
	v_lshl_add_u32 v35, v35, 2, v36
	v_lshl_add_u32 v40, v40, 2, v36
	ds_read_b32 v35, v35 offset:64
	ds_read_b32 v40, v40 offset:64
	s_waitcnt lgkmcnt(3)
	v_lshlrev_b32_e32 v39, 7, v41
	s_waitcnt lgkmcnt(2)
	v_lshlrev_b32_e32 v34, 7, v34
	v_and_b32_e32 v39, 0x3f80, v39
	s_waitcnt lgkmcnt(1)
	v_and_b32_e32 v35, 0x7f, v35
	s_waitcnt lgkmcnt(0)
	v_and_b32_e32 v38, 0x7f, v40
	v_and_b32_e32 v34, 0x3f80, v34
	v_lshlrev_b32_e32 v40, 7, v44
	v_lshlrev_b32_e32 v41, 7, v42
	v_or_b32_e32 v39, v39, v38
	v_or_b32_e32 v38, v34, v35
	v_and_b32_e32 v34, 0x7f, v45
	v_and_b32_e32 v35, 0x7f, v43
	v_and_b32_e32 v40, 0x3f80, v40
	v_and_b32_e32 v42, 0x3f80, v41
	v_lshl_add_u64 v[22:23], s[0:1], 0, v[20:21]
	v_or_b32_e32 v41, v40, v34
	v_or_b32_e32 v40, v42, v35
	global_store_dwordx4 v[22:23], v[38:41], off
	v_lshl_add_u64 v[20:21], s[14:15], 0, v[20:21]
	v_pk_mul_f32 v[4:5], v[4:5], v[18:19] op_sel_hi:[1,0]
	v_pk_mul_f32 v[40:41], v[6:7], v[18:19] op_sel_hi:[1,0]
	v_pk_mul_f32 v[38:39], v[2:3], v[18:19] op_sel_hi:[1,0]
	v_lshrrev_b32_e32 v2, 2, v37
	v_lshrrev_b32_e32 v6, 2, v33
	v_and_b32_e32 v7, 15, v33
	v_lshrrev_b32_e32 v33, 2, v32
	v_and_b32_e32 v32, 15, v32
	v_and_b32_e32 v2, 60, v2
	v_and_b32_e32 v3, 15, v37
	v_and_b32_e32 v6, 60, v6
	v_lshl_add_u32 v32, v32, 2, v36
	v_add_u32_e32 v2, v36, v2
	v_lshl_add_u32 v3, v3, 2, v36
	v_add_u32_e32 v6, v36, v6
	ds_read_b32 v35, v32 offset:64
	v_lshrrev_b32_e32 v32, 2, v31
	ds_read_b32 v2, v2
	ds_read_b32 v3, v3 offset:64
	ds_read_b32 v6, v6
	v_lshl_add_u32 v7, v7, 2, v36
	v_and_b32_e32 v33, 60, v33
	v_and_b32_e32 v32, 60, v32
	ds_read_b32 v7, v7 offset:64
	v_add_u32_e32 v33, v36, v33
	v_add_u32_e32 v32, v36, v32
	v_and_b32_e32 v31, 15, v31
	ds_read_b32 v34, v33
	ds_read_b32 v37, v32
	v_lshl_add_u32 v31, v31, 2, v36
	ds_read_b32 v31, v31 offset:64
	s_waitcnt lgkmcnt(4)
	v_lshlrev_b32_e32 v6, 7, v6
	s_waitcnt lgkmcnt(3)
	v_and_b32_e32 v7, 0x7f, v7
	v_lshlrev_b32_e32 v2, 7, v2
	v_and_b32_e32 v6, 0x3f80, v6
	v_and_b32_e32 v3, 0x7f, v3
	v_and_b32_e32 v2, 0x3f80, v2
	v_or_b32_e32 v33, v6, v7
	s_waitcnt lgkmcnt(1)
	v_lshlrev_b32_e32 v6, 7, v37
	v_lshlrev_b32_e32 v7, 7, v34
	v_or_b32_e32 v32, v2, v3
	s_waitcnt lgkmcnt(0)
	v_and_b32_e32 v2, 0x7f, v31
	v_and_b32_e32 v3, 0x7f, v35
	v_and_b32_e32 v6, 0x3f80, v6
	v_and_b32_e32 v7, 0x3f80, v7
	v_or_b32_e32 v35, v6, v2
	v_or_b32_e32 v34, v7, v3
	v_pk_mul_f32 v[6:7], v[10:11], v[18:19] op_sel_hi:[1,0]
	global_store_dwordx4 v[20:21], v[4:7], off offset:16
	v_lshrrev_b32_e32 v2, 2, v30
	v_and_b32_e32 v2, 60, v2
	v_lshrrev_b32_e32 v4, 2, v29
	v_and_b32_e32 v3, 15, v30
	v_and_b32_e32 v4, 60, v4
	v_add_u32_e32 v2, v36, v2
	v_lshl_add_u32 v3, v3, 2, v36
	v_add_u32_e32 v4, v36, v4
	v_and_b32_e32 v5, 15, v29
	v_lshrrev_b32_e32 v6, 2, v28
	v_lshrrev_b32_e32 v10, 2, v27
	ds_read_b32 v2, v2
	ds_read_b32 v3, v3 offset:64
	ds_read_b32 v4, v4
	v_lshl_add_u32 v5, v5, 2, v36
	v_and_b32_e32 v6, 60, v6
	v_and_b32_e32 v7, 15, v28
	v_and_b32_e32 v10, 60, v10
	ds_read_b32 v5, v5 offset:64
	v_add_u32_e32 v6, v36, v6
	v_lshl_add_u32 v7, v7, 2, v36
	v_add_u32_e32 v10, v36, v10
	v_and_b32_e32 v11, 15, v27
	ds_read_b32 v6, v6
	ds_read_b32 v7, v7 offset:64
	ds_read_b32 v10, v10
	v_lshl_add_u32 v11, v11, 2, v36
	ds_read_b32 v11, v11 offset:64
	s_waitcnt lgkmcnt(6)
	v_and_b32_e32 v27, 0x7f, v3
	s_waitcnt lgkmcnt(5)
	v_lshlrev_b32_e32 v3, 7, v4
	s_waitcnt lgkmcnt(4)
	v_and_b32_e32 v5, 0x7f, v5
	v_and_b32_e32 v3, 0x3f80, v3
	v_lshlrev_b32_e32 v2, 7, v2
	v_or_b32_e32 v3, v3, v5
	s_waitcnt lgkmcnt(1)
	v_lshlrev_b32_e32 v5, 7, v10
	v_lshlrev_b32_e32 v6, 7, v6
	v_and_b32_e32 v2, 0x3f80, v2
	s_waitcnt lgkmcnt(0)
	v_and_b32_e32 v4, 0x7f, v11
	v_and_b32_e32 v7, 0x7f, v7
	v_and_b32_e32 v5, 0x3f80, v5
	v_and_b32_e32 v6, 0x3f80, v6
	v_or_b32_e32 v2, v2, v27
	v_or_b32_e32 v5, v5, v4
	v_or_b32_e32 v4, v6, v7
	global_store_dwordx4 v[22:23], v[2:5], off offset:32
	v_lshrrev_b32_e32 v6, 2, v24
	v_and_b32_e32 v6, 60, v6
	v_pk_mul_f32 v[4:5], v[14:15], v[18:19] op_sel_hi:[1,0]
	v_pk_mul_f32 v[2:3], v[8:9], v[18:19] op_sel_hi:[1,0]
	global_store_dwordx4 v[20:21], v[2:5], off offset:32
	v_lshrrev_b32_e32 v8, 2, v19
	v_and_b32_e32 v7, 15, v24
	v_lshrrev_b32_e32 v2, 2, v26
	v_lshrrev_b32_e32 v4, 2, v25
	v_and_b32_e32 v2, 60, v2
	v_and_b32_e32 v3, 15, v26
	v_and_b32_e32 v4, 60, v4
	v_add_u32_e32 v2, v36, v2
	v_lshl_add_u32 v3, v3, 2, v36
	v_add_u32_e32 v4, v36, v4
	v_and_b32_e32 v5, 15, v25
	ds_read_b32 v2, v2
	ds_read_b32 v3, v3 offset:64
	ds_read_b32 v4, v4
	v_lshl_add_u32 v5, v5, 2, v36
	v_and_b32_e32 v8, 60, v8
	ds_read_b32 v5, v5 offset:64
	v_add_u32_e32 v6, v36, v6
	v_lshl_add_u32 v7, v7, 2, v36
	v_add_u32_e32 v8, v36, v8
	v_and_b32_e32 v9, 15, v19
	ds_read_b32 v6, v6
	ds_read_b32 v7, v7 offset:64
	ds_read_b32 v8, v8
	v_lshl_add_u32 v9, v9, 2, v36
	ds_read_b32 v9, v9 offset:64
	s_waitcnt lgkmcnt(6)
	v_and_b32_e32 v10, 0x7f, v3
	s_waitcnt lgkmcnt(5)
	v_lshlrev_b32_e32 v3, 7, v4
	s_waitcnt lgkmcnt(4)
	v_and_b32_e32 v5, 0x7f, v5
	v_and_b32_e32 v3, 0x3f80, v3
	v_lshlrev_b32_e32 v2, 7, v2
	v_or_b32_e32 v3, v3, v5
	s_waitcnt lgkmcnt(1)
	v_lshlrev_b32_e32 v5, 7, v8
	v_lshlrev_b32_e32 v6, 7, v6
	v_and_b32_e32 v2, 0x3f80, v2
	s_waitcnt lgkmcnt(0)
	v_and_b32_e32 v4, 0x7f, v9
	v_and_b32_e32 v7, 0x7f, v7
	v_and_b32_e32 v5, 0x3f80, v5
	v_and_b32_e32 v6, 0x3f80, v6
	v_or_b32_e32 v2, v2, v10
	v_or_b32_e32 v5, v5, v4
	v_or_b32_e32 v4, v6, v7
	global_store_dwordx4 v[22:23], v[2:5], off offset:48
	global_store_dwordx4 v[20:21], v[38:41], off
	global_store_dwordx4 v[22:23], v[32:35], off offset:16
	v_pk_mul_f32 v[4:5], v[16:17], v[18:19] op_sel_hi:[1,0]
	v_pk_mul_f32 v[2:3], v[12:13], v[18:19] op_sel_hi:[1,0]
	global_store_dwordx4 v[20:21], v[2:5], off offset:48
	s_branch .LBB0_21
.LBB0_26:
	v_readlane_b32 s0, v254, 58
	v_mov_b32_e32 v1, v133
	s_add_i32 s40, s42, s0
	s_waitcnt lgkmcnt(0)
	s_barrier
	v_readlane_b32 s0, v254, 27
	v_and_b32_e32 v55, 63, v1
	v_lshlrev_b32_e32 v154, 5, v55
	v_readlane_b32 s1, v254, 28
	s_ashr_i32 s41, s40, 31
	s_lshl_b64 s[38:39], s[40:41], 11
	v_lshl_add_u64 v[18:19], s[0:1], 0, v[154:155]
	s_mov_b64 s[98:99], s[0:1]
	v_add_u32_e32 v236, s38, v154
	s_lshr_b32 s32, s38, 2
	v_lshl_add_u32 v237, v55, 2, s32
	v_lshl_add_u64 v[8:9], v[18:19], 0, s[38:39]
	global_load_dwordx4 v[4:7], v[8:9], off offset:16
	s_nop 0
	global_load_dwordx4 v[8:11], v[8:9], off
	v_add_u32_e32 v16, s93, v154
	v_add_u32_e32 v1, 0x3000, v16
	v_cmp_ne_u32_e64 s[0:1], -1, v1
	v_readlane_b32 s10, v254, 10
	v_readlane_b32 s11, v254, 11
	v_cndmask_b32_e64 v2, 0, v1, s[0:1]
	v_add_u32_e32 v12, 0x3014, v16
	v_mov_b32_e32 v17, s11
	v_cndmask_b32_e64 v3, 0, v17, s[0:1]
	v_cmp_gt_u32_e64 s[14:15], 48, v55
	v_cmp_gt_u32_e64 s[12:13], 32, v55
	v_cmp_lt_u32_e32 vcc, 15, v55
	s_waitcnt vmcnt(1)
	v_lshlrev_b32_e32 v1, 16, v4
	s_waitcnt vmcnt(0)
	v_lshlrev_b32_e32 v47, 16, v8
	v_and_b32_e32 v48, 0xffff0000, v8
	v_and_b32_e32 v40, 0xffff0000, v4
	v_lshlrev_b32_e32 v49, 16, v9
	v_and_b32_e32 v50, 0xffff0000, v9
	v_max3_f32 v4, |v47|, 0, |v48|
	v_lshlrev_b32_e32 v51, 16, v10
	v_and_b32_e32 v52, 0xffff0000, v10
	v_max3_f32 v4, v4, |v49|, |v50|
	v_lshlrev_b32_e32 v53, 16, v11
	v_and_b32_e32 v54, 0xffff0000, v11
	v_max3_f32 v4, v4, |v51|, |v52|
	v_max3_f32 v4, v4, |v53|, |v54|
	v_lshlrev_b32_e32 v41, 16, v5
	v_and_b32_e32 v42, 0xffff0000, v5
	v_max3_f32 v4, v4, |v1|, |v40|
	v_lshlrev_b32_e32 v43, 16, v6
	v_and_b32_e32 v44, 0xffff0000, v6
	v_max3_f32 v4, v4, |v41|, |v42|
	v_lshlrev_b32_e32 v45, 16, v7
	v_and_b32_e32 v46, 0xffff0000, v7
	v_max3_f32 v4, v4, |v43|, |v44|
	v_max3_f32 v4, v4, |v45|, |v46|
	s_nop 1
	v_mov_b32_dpp v5, v4 quad_perm:[1,0,3,2] row_mask:0xf bank_mask:0xf bound_ctrl:1
	v_max_f32_e32 v5, v5, v5
	v_max_f32_e32 v4, v4, v5
	s_nop 1
	v_mov_b32_dpp v5, v4 quad_perm:[2,3,0,1] row_mask:0xf bank_mask:0xf bound_ctrl:1
	v_max_f32_e32 v5, v5, v5
	v_max_f32_e32 v4, v4, v5
	s_nop 1
	v_mov_b32_dpp v5, v4 row_half_mirror row_mask:0xf bank_mask:0xf bound_ctrl:1
	v_max_f32_e32 v5, v5, v5
	v_max_f32_e32 v4, v4, v5
	s_nop 1
	v_mov_b32_dpp v5, v4 row_mirror row_mask:0xf bank_mask:0xf bound_ctrl:1
	v_max_f32_e32 v5, v5, v5
	v_max_f32_e32 v4, v4, v5
	s_nop 0
	v_readlane_b32 s0, v4, 0
	s_nop 1
	v_writelane_b32 v254, s0, 38
	v_readlane_b32 s0, v4, 16
	s_nop 1
	v_writelane_b32 v254, s0, 42
	v_readlane_b32 s0, v4, 32
	s_nop 1
	v_writelane_b32 v254, s0, 36
	v_readlane_b32 s0, v4, 48
	s_nop 1
	v_writelane_b32 v254, s0, 40
	s_lshl_b64 s[0:1], s[40:41], 9
	v_lshl_or_b32 v4, v55, 2, s0
	v_mov_b32_e32 v5, s1
	v_lshl_add_u64 v[6:7], s[24:25], 0, v[4:5]
	global_load_dword v36, v[6:7], off
	v_or_b32_e32 v6, 0x100, v4
	v_mov_b32_e32 v7, s1
	v_lshl_add_u64 v[8:9], s[24:25], 0, v[6:7]
	global_load_dword v38, v[8:9], off
	v_lshl_add_u64 v[4:5], s[26:27], 0, v[4:5]
	global_load_dword v57, v[4:5], off
	v_lshl_add_u64 v[4:5], s[26:27], 0, v[6:7]
	global_load_dword v56, v[4:5], off
	v_add_u32_e32 v238, 0x800, v236
	global_load_dwordx4 v[200:203], v238, s[98:99] offset:16
	global_load_dwordx4 v[204:207], v238, s[98:99]
	v_add_u32_e32 v239, 0x200, v237
	global_load_dword v232, v239, s[24:25]
	global_load_dword v233, v239, s[24:25] offset:256
	global_load_dword v234, v239, s[26:27]
	global_load_dword v235, v239, s[26:27] offset:256
	v_mul_i32_i24_e32 v4, 0xffffffe4, v55
	v_add_u32_e32 v4, v16, v4
	v_add_u32_e32 v5, 0x3000, v4
	v_cmp_ne_u32_e64 s[0:1], -1, v5
	v_add_u32_e32 v6, 0x3008, v16
	v_add_u32_e32 v8, 0x300c, v16
	v_cndmask_b32_e64 v20, 0, v5, s[0:1]
	v_add_u32_e32 v5, 0x3100, v4
	v_cndmask_b32_e64 v21, 0, v17, s[0:1]
	v_cmp_ne_u32_e64 s[0:1], -1, v5
	ds_write_b32 v20, v155
	s_waitcnt vmcnt(6)
	v_cndmask_b32_e64 v22, 0, v5, s[0:1]
	v_add_u32_e32 v5, 0x3200, v4
	v_cndmask_b32_e64 v23, 0, v17, s[0:1]
	v_cmp_ne_u32_e64 s[0:1], -1, v5
	ds_write_b32 v22, v155
	v_cndmask_b32_e64 v24, 0, v5, s[0:1]
	v_add_u32_e32 v5, 0x3300, v4
	v_cndmask_b32_e64 v25, 0, v17, s[0:1]
	v_cmp_ne_u32_e64 s[0:1], -1, v5
	ds_write_b32 v24, v155
	v_cndmask_b32_e64 v26, 0, v5, s[0:1]
	v_add_u32_e32 v5, 0x3400, v4
	v_cndmask_b32_e64 v27, 0, v17, s[0:1]
	v_cmp_ne_u32_e64 s[0:1], -1, v5
	ds_write_b32 v26, v155
	v_cndmask_b32_e64 v28, 0, v5, s[0:1]
	v_add_u32_e32 v5, 0x3500, v4
	v_cndmask_b32_e64 v29, 0, v17, s[0:1]
	v_cmp_ne_u32_e64 s[0:1], -1, v5
	ds_write_b32 v28, v155
	v_cndmask_b32_e64 v30, 0, v5, s[0:1]
	v_add_u32_e32 v5, 0x3600, v4
	v_cndmask_b32_e64 v31, 0, v17, s[0:1]
	v_cmp_ne_u32_e64 s[0:1], -1, v5
	v_add_u32_e32 v4, 0x3700, v4
	ds_write_b32 v30, v155
	v_cndmask_b32_e64 v32, 0, v5, s[0:1]
	v_cndmask_b32_e64 v33, 0, v17, s[0:1]
	v_cmp_ne_u32_e64 s[0:1], -1, v4
	ds_write_b32 v32, v155
	v_cndmask_b32_e64 v34, 0, v4, s[0:1]
	v_cndmask_b32_e64 v35, 0, v17, s[0:1]
	ds_write_b32 v34, v155
	v_ashrrev_i32_e32 v4, 5, v36
	v_lshl_add_u32 v59, v4, 2, s93
	ds_add_rtn_u32 v39, v59, v208 offset:12288
	v_ashrrev_i32_e32 v4, 5, v38
	v_lshl_add_u32 v60, v4, 2, s93
	v_add_u32_e32 v4, 0x3004, v16
	v_cmp_ne_u32_e64 s[0:1], -1, v4
	ds_add_rtn_u32 v37, v60, v208 offset:12288
	s_waitcnt lgkmcnt(0)
	ds_read_b32 v58, v2
	v_cndmask_b32_e64 v4, 0, v4, s[0:1]
	v_cndmask_b32_e64 v5, 0, v17, s[0:1]
	v_cmp_ne_u32_e64 s[0:1], -1, v6
	ds_read_b32 v61, v4
	s_waitcnt lgkmcnt(0)
	v_add_u32_e32 v10, v61, v58
	v_cndmask_b32_e64 v6, 0, v6, s[0:1]
	v_cndmask_b32_e64 v7, 0, v17, s[0:1]
	v_cmp_ne_u32_e64 s[0:1], -1, v8
	ds_read_b32 v62, v6
	v_cndmask_b32_e64 v8, 0, v8, s[0:1]
	v_cndmask_b32_e64 v9, 0, v17, s[0:1]
	ds_read_b32 v63, v8
	s_waitcnt lgkmcnt(0)
	v_add3_u32 v14, v10, v62, v63
	v_add_u32_e32 v10, 0x3010, v16
	v_cmp_ne_u32_e64 s[0:1], -1, v10
	s_nop 1
	v_cndmask_b32_e64 v10, 0, v10, s[0:1]
	v_cndmask_b32_e64 v11, 0, v17, s[0:1]
	v_cmp_ne_u32_e64 s[0:1], -1, v12
	ds_read_b32 v64, v10
	v_cndmask_b32_e64 v12, 0, v12, s[0:1]
	v_cndmask_b32_e64 v13, 0, v17, s[0:1]
	ds_read_b32 v65, v12
	s_waitcnt lgkmcnt(0)
	v_add3_u32 v67, v14, v64, v65
	v_add_u32_e32 v14, 0x3018, v16
	v_cmp_ne_u32_e64 s[0:1], -1, v14
	v_add_u32_e32 v16, 0x301c, v16
	s_nop 0
	v_cndmask_b32_e64 v14, 0, v14, s[0:1]
	v_cndmask_b32_e64 v15, 0, v17, s[0:1]
	v_cmp_ne_u32_e64 s[0:1], -1, v16
	ds_read_b32 v66, v14
	v_cndmask_b32_e64 v16, 0, v16, s[0:1]
	v_cndmask_b32_e64 v17, 0, v17, s[0:1]
	ds_read_b32 v68, v16
	s_waitcnt lgkmcnt(0)
	v_add3_u32 v67, v67, v66, v68
	v_cvt_f32_u32_e32 v68, v67
	s_nop 1
	v_add_f32_dpp v68, v68, v68 row_shr:1 row_mask:0xf bank_mask:0xf bound_ctrl:1
	s_nop 1
	v_add_f32_dpp v68, v68, v68 row_shr:2 row_mask:0xf bank_mask:0xf bound_ctrl:1
	s_nop 1
	v_add_f32_dpp v68, v68, v68 row_shr:4 row_mask:0xf bank_mask:0xf bound_ctrl:1
	s_nop 1
	v_add_f32_dpp v68, v68, v68 row_shr:8 row_mask:0xf bank_mask:0xf bound_ctrl:1
	s_nop 0
	v_readlane_b32 s10, v68, 15
	v_readlane_b32 s16, v68, 31
	v_readlane_b32 s11, v68, 47
	s_and_saveexec_b64 s[0:1], s[14:15]
	s_xor_b64 s[0:1], exec, s[0:1]
	s_cbranch_execz .LBB0_32
	s_and_saveexec_b64 s[18:19], s[12:13]
	s_xor_b64 s[42:43], exec, s[18:19]
	v_mov_b32_e32 v69, s10
	v_cndmask_b32_e32 v69, 0, v69, vcc
	s_andn2_saveexec_b64 s[42:43], s[42:43]
	v_mov_b32_e32 v69, s16
	v_add_f32_e32 v69, s10, v69
	s_or_b64 exec, exec, s[42:43]
.LBB0_32:
	s_andn2_saveexec_b64 s[0:1], s[0:1]
	v_mov_b32_e32 v69, s16
	v_add_f32_e32 v69, s10, v69
	v_add_f32_e32 v69, s11, v69
	s_or_b64 exec, exec, s[0:1]
	v_add_u32_e32 v59, 0x3000, v59
	v_cmp_ne_u32_e64 s[0:1], -1, v59
	v_readlane_b32 s10, v254, 10
	v_readlane_b32 s11, v254, 11
	v_cndmask_b32_e64 v70, 0, v59, s[0:1]
	v_add_f32_e32 v59, v68, v69
	v_cvt_u32_f32_e32 v59, v59
	v_mov_b32_e32 v72, s11
	v_cndmask_b32_e64 v71, 0, v72, s[0:1]
	v_add_u32_e32 v60, 0x3000, v60
	v_sub_u32_e32 v59, v59, v67
	v_add_u32_e32 v58, v59, v58
	ds_write_b32 v2, v59
	ds_write_b32 v4, v58
	v_add_u32_e32 v58, v58, v61
	ds_write_b32 v6, v58
	v_add_u32_e32 v58, v58, v62
	ds_write_b32 v8, v58
	v_add_u32_e32 v58, v58, v63
	ds_write_b32 v10, v58
	v_add_u32_e32 v58, v58, v64
	ds_write_b32 v12, v58
	v_add_u32_e32 v58, v58, v65
	ds_write_b32 v14, v58
	v_add_u32_e32 v58, v58, v66
	ds_write_b32 v16, v58
	s_waitcnt lgkmcnt(0)
	ds_read_b32 v58, v70
	v_cmp_ne_u32_e64 s[0:1], -1, v60
	s_waitcnt lgkmcnt(0)
	v_add_u32_e32 v62, v58, v39
	v_cndmask_b32_e64 v73, 0, v72, s[0:1]
	v_cndmask_b32_e64 v72, 0, v60, s[0:1]
	ds_read_b32 v39, v72
	s_waitcnt lgkmcnt(0)
	s_or_b32 s0, s40, 1
	s_ashr_i32 s1, s0, 31
	s_lshl_b64 s[42:43], s[0:1], 11
	s_waitcnt lgkmcnt(0)
	v_add_u32_e32 v63, v39, v37
	v_ashrrev_i32_e32 v37, 31, v36
	v_lshl_add_u64 v[58:59], v[36:37], 3, s[28:29]
	v_ashrrev_i32_e32 v39, 31, v38
	global_load_dwordx2 v[58:59], v[58:59], off
	v_lshl_add_u64 v[60:61], v[38:39], 3, s[28:29]
	global_load_dwordx2 v[60:61], v[60:61], off
	v_lshl_add_u32 v37, v62, 2, s93
	s_waitcnt vmcnt(1)
	v_mul_f32_e32 v39, v57, v59
	ds_write2st64_b32 v37, v36, v39 offset1:2
	ds_write_b32 v37, v58 offset:1024
	v_lshl_add_u32 v36, v63, 2, s93
	s_waitcnt vmcnt(0)
	v_mul_f32_e32 v37, v56, v61
	ds_write2st64_b32 v36, v38, v37 offset1:2
	ds_write_b32 v36, v60 offset:1024
	v_lshl_add_u64 v[56:57], v[18:19], 0, s[42:43]
	v_mov_b32_e32 v36, v200
	v_mov_b32_e32 v37, v201
	v_mov_b32_e32 v38, v202
	v_mov_b32_e32 v39, v203
	v_mov_b32_e32 v60, v204
	v_mov_b32_e32 v61, v205
	v_mov_b32_e32 v62, v206
	v_mov_b32_e32 v63, v207
	v_lshlrev_b32_e32 v56, 16, v36
	v_lshlrev_b32_e32 v64, 16, v60
	v_and_b32_e32 v65, 0xffff0000, v60
	v_and_b32_e32 v57, 0xffff0000, v36
	v_lshlrev_b32_e32 v66, 16, v61
	v_and_b32_e32 v67, 0xffff0000, v61
	v_max3_f32 v36, |v64|, 0, |v65|
	v_lshlrev_b32_e32 v68, 16, v62
	v_and_b32_e32 v69, 0xffff0000, v62
	v_max3_f32 v36, v36, |v66|, |v67|
	v_lshlrev_b32_e32 v70, 16, v63
	v_and_b32_e32 v71, 0xffff0000, v63
	v_max3_f32 v36, v36, |v68|, |v69|
	v_max3_f32 v36, v36, |v70|, |v71|
	v_lshlrev_b32_e32 v58, 16, v37
	v_and_b32_e32 v59, 0xffff0000, v37
	v_max3_f32 v36, v36, |v56|, |v57|
	v_lshlrev_b32_e32 v60, 16, v38
	v_and_b32_e32 v61, 0xffff0000, v38
	v_max3_f32 v36, v36, |v58|, |v59|
	v_lshlrev_b32_e32 v62, 16, v39
	v_and_b32_e32 v63, 0xffff0000, v39
	v_max3_f32 v36, v36, |v60|, |v61|
	v_max3_f32 v36, v36, |v62|, |v63|
	s_nop 1
	v_mov_b32_dpp v37, v36 quad_perm:[1,0,3,2] row_mask:0xf bank_mask:0xf bound_ctrl:1
	v_max_f32_e32 v37, v37, v37
	v_max_f32_e32 v36, v36, v37
	s_nop 1
	v_mov_b32_dpp v37, v36 quad_perm:[2,3,0,1] row_mask:0xf bank_mask:0xf bound_ctrl:1
	v_max_f32_e32 v37, v37, v37
	v_max_f32_e32 v36, v36, v37
	s_nop 1
	v_mov_b32_dpp v37, v36 row_half_mirror row_mask:0xf bank_mask:0xf bound_ctrl:1
	v_max_f32_e32 v37, v37, v37
	v_max_f32_e32 v36, v36, v37
	s_nop 1
	v_mov_b32_dpp v37, v36 row_mirror row_mask:0xf bank_mask:0xf bound_ctrl:1
	v_max_f32_e32 v37, v37, v37
	v_max_f32_e32 v36, v36, v37
	s_nop 0
	v_readlane_b32 s10, v36, 32
	v_readlane_b32 s35, v36, 0
	v_readlane_b32 s37, v36, 16
	v_writelane_b32 v254, s10, 44
	v_writelane_b32 v254, s0, 46
	v_readlane_b32 s36, v36, 48
	s_nop 0
	v_writelane_b32 v254, s1, 47
	s_lshl_b64 s[0:1], s[0:1], 9
	v_lshl_or_b32 v72, v55, 2, s0
	v_mov_b32_e32 v73, s1
	v_lshl_add_u64 v[36:37], s[24:25], 0, v[72:73]
	v_or_b32_e32 v74, 0x100, v72
	v_mov_b32_e32 v75, s1
	v_mov_b32_e32 v36, v232
	v_lshl_add_u64 v[38:39], s[24:25], 0, v[74:75]
	v_mov_b32_e32 v38, v233
	v_lshl_add_u64 v[72:73], s[26:27], 0, v[72:73]
	v_mov_b32_e32 v72, v234
	v_lshl_add_u64 v[74:75], s[26:27], 0, v[74:75]
	v_mov_b32_e32 v73, v235
	v_add_u32_e32 v238, 0x1000, v236
	global_load_dwordx4 v[192:195], v238, s[98:99] offset:16
	global_load_dwordx4 v[196:199], v238, s[98:99]
	v_add_u32_e32 v239, 0x400, v237
	global_load_dword v228, v239, s[24:25]
	global_load_dword v229, v239, s[24:25] offset:256
	global_load_dword v230, v239, s[26:27]
	global_load_dword v231, v239, s[26:27] offset:256
	s_nop 0
	ds_write_b32 v20, v155
	ds_write_b32 v22, v155
	ds_write_b32 v24, v155
	ds_write_b32 v26, v155
	ds_write_b32 v28, v155
	ds_write_b32 v30, v155
	ds_write_b32 v32, v155
	ds_write_b32 v34, v155
	v_ashrrev_i32_e32 v37, 5, v36
	v_lshl_add_u32 v74, v37, 2, s93
	v_ashrrev_i32_e32 v39, 5, v38
	ds_add_rtn_u32 v37, v74, v208 offset:12288
	v_lshl_add_u32 v82, v39, 2, s93
	ds_add_rtn_u32 v39, v82, v208 offset:12288
	s_waitcnt lgkmcnt(0)
	ds_read_b32 v76, v2
	ds_read_b32 v75, v4
	ds_read_b32 v78, v6
	ds_read_b32 v77, v8
	s_waitcnt lgkmcnt(0)
	v_add_u32_e32 v79, v75, v76
	v_add3_u32 v81, v79, v78, v77
	ds_read_b32 v80, v10
	ds_read_b32 v79, v12
	s_waitcnt lgkmcnt(0)
	v_add3_u32 v83, v81, v80, v79
	ds_read_b32 v81, v14
	ds_read_b32 v84, v16
	s_waitcnt lgkmcnt(0)
	v_add3_u32 v83, v83, v81, v84
	v_cvt_f32_u32_e32 v84, v83
	s_nop 1
	v_add_f32_dpp v84, v84, v84 row_shr:1 row_mask:0xf bank_mask:0xf bound_ctrl:1
	s_nop 1
	v_add_f32_dpp v84, v84, v84 row_shr:2 row_mask:0xf bank_mask:0xf bound_ctrl:1
	s_nop 1
	v_add_f32_dpp v84, v84, v84 row_shr:4 row_mask:0xf bank_mask:0xf bound_ctrl:1
	s_nop 1
	v_add_f32_dpp v84, v84, v84 row_shr:8 row_mask:0xf bank_mask:0xf bound_ctrl:1
	s_nop 0
	v_readlane_b32 s10, v84, 15
	v_readlane_b32 s16, v84, 31
	v_readlane_b32 s11, v84, 47
	s_and_saveexec_b64 s[0:1], s[14:15]
	s_xor_b64 s[0:1], exec, s[0:1]
	s_cbranch_execz .LBB0_40
	s_and_saveexec_b64 s[18:19], s[12:13]
	s_xor_b64 s[46:47], exec, s[18:19]
	v_mov_b32_e32 v85, s10
	v_cndmask_b32_e32 v85, 0, v85, vcc
	s_andn2_saveexec_b64 s[46:47], s[46:47]
	v_mov_b32_e32 v85, s16
	v_add_f32_e32 v85, s10, v85
	s_or_b64 exec, exec, s[46:47]
.LBB0_40:
	s_andn2_saveexec_b64 s[0:1], s[0:1]
	v_mov_b32_e32 v85, s16
	v_add_f32_e32 v85, s10, v85
	v_add_f32_e32 v85, s11, v85
	s_or_b64 exec, exec, s[0:1]
	v_add_u32_e32 v74, 0x3000, v74
	v_cmp_ne_u32_e64 s[0:1], -1, v74
	v_readlane_b32 s10, v254, 10
	v_readlane_b32 s11, v254, 11
	v_cndmask_b32_e64 v86, 0, v74, s[0:1]
	v_add_f32_e32 v74, v84, v85
	v_cvt_u32_f32_e32 v74, v74
	v_mov_b32_e32 v88, s11
	v_cndmask_b32_e64 v87, 0, v88, s[0:1]
	v_add_u32_e32 v82, 0x3000, v82
	v_sub_u32_e32 v74, v74, v83
	ds_write_b32 v2, v74
	v_add_u32_e32 v74, v74, v76
	ds_write_b32 v4, v74
	v_add_u32_e32 v74, v74, v75
	ds_write_b32 v6, v74
	v_add_u32_e32 v74, v74, v78
	ds_write_b32 v8, v74
	v_add_u32_e32 v74, v74, v77
	ds_write_b32 v10, v74
	v_add_u32_e32 v74, v74, v80
	ds_write_b32 v12, v74
	v_add_u32_e32 v74, v74, v79
	ds_write_b32 v14, v74
	v_add_u32_e32 v74, v74, v81
	ds_write_b32 v16, v74
	s_waitcnt lgkmcnt(0)
	ds_read_b32 v74, v86
	v_cmp_ne_u32_e64 s[0:1], -1, v82
	s_waitcnt lgkmcnt(0)
	v_add_u32_e32 v78, v74, v37
	v_cndmask_b32_e64 v89, 0, v88, s[0:1]
	v_cndmask_b32_e64 v88, 0, v82, s[0:1]
	ds_read_b32 v37, v88
	s_waitcnt lgkmcnt(0)
	s_or_b32 s0, s40, 2
	s_ashr_i32 s1, s0, 31
	s_lshl_b64 s[46:47], s[0:1], 11
	v_writelane_b32 v254, s0, 48
	s_waitcnt lgkmcnt(0)
	v_add_u32_e32 v79, v37, v39
	v_ashrrev_i32_e32 v37, 31, v36
	v_lshl_add_u64 v[74:75], v[36:37], 3, s[28:29]
	v_ashrrev_i32_e32 v39, 31, v38
	global_load_dwordx2 v[74:75], v[74:75], off
	v_lshl_add_u64 v[76:77], v[38:39], 3, s[28:29]
	global_load_dwordx2 v[76:77], v[76:77], off
	v_lshl_add_u32 v37, v78, 2, s93
	v_writelane_b32 v254, s1, 49
	s_lshl_b64 s[0:1], s[0:1], 9
	v_lshl_or_b32 v88, v55, 2, s0
	v_mov_b32_e32 v89, s1
	v_or_b32_e32 v90, 0x100, v88
	v_mov_b32_e32 v91, s1
	s_waitcnt vmcnt(1)
	v_mul_f32_e32 v39, v72, v75
	ds_write2st64_b32 v37, v36, v39 offset0:6 offset1:8
	ds_write_b32 v37, v74 offset:2560
	v_lshl_add_u32 v36, v79, 2, s93
	s_waitcnt vmcnt(0)
	v_mul_f32_e32 v37, v73, v77
	ds_write2st64_b32 v36, v38, v37 offset0:6 offset1:8
	ds_write_b32 v36, v76 offset:2560
	v_lshl_add_u64 v[72:73], v[18:19], 0, s[46:47]
	v_mov_b32_e32 v36, v192
	v_mov_b32_e32 v37, v193
	v_mov_b32_e32 v38, v194
	v_mov_b32_e32 v39, v195
	v_mov_b32_e32 v76, v196
	v_mov_b32_e32 v77, v197
	v_mov_b32_e32 v78, v198
	v_mov_b32_e32 v79, v199
	v_lshlrev_b32_e32 v72, 16, v36
	v_lshlrev_b32_e32 v80, 16, v76
	v_and_b32_e32 v81, 0xffff0000, v76
	v_and_b32_e32 v73, 0xffff0000, v36
	v_lshlrev_b32_e32 v82, 16, v77
	v_and_b32_e32 v83, 0xffff0000, v77
	v_max3_f32 v36, |v80|, 0, |v81|
	v_lshlrev_b32_e32 v84, 16, v78
	v_and_b32_e32 v85, 0xffff0000, v78
	v_max3_f32 v36, v36, |v82|, |v83|
	v_lshlrev_b32_e32 v86, 16, v79
	v_and_b32_e32 v87, 0xffff0000, v79
	v_max3_f32 v36, v36, |v84|, |v85|
	v_max3_f32 v36, v36, |v86|, |v87|
	v_lshlrev_b32_e32 v74, 16, v37
	v_and_b32_e32 v75, 0xffff0000, v37
	v_max3_f32 v36, v36, |v72|, |v73|
	v_lshlrev_b32_e32 v76, 16, v38
	v_and_b32_e32 v77, 0xffff0000, v38
	v_max3_f32 v36, v36, |v74|, |v75|
	v_lshlrev_b32_e32 v78, 16, v39
	v_and_b32_e32 v79, 0xffff0000, v39
	v_max3_f32 v36, v36, |v76|, |v77|
	v_max3_f32 v36, v36, |v78|, |v79|
	v_lshl_add_u64 v[38:39], s[24:25], 0, v[90:91]
	v_mov_b32_e32 v38, v229
	v_mov_b32_dpp v37, v36 quad_perm:[1,0,3,2] row_mask:0xf bank_mask:0xf bound_ctrl:1
	v_max_f32_e32 v37, v37, v37
	v_max_f32_e32 v36, v36, v37
	v_lshl_add_u64 v[90:91], s[26:27], 0, v[90:91]
	s_nop 0
	v_mov_b32_dpp v37, v36 quad_perm:[2,3,0,1] row_mask:0xf bank_mask:0xf bound_ctrl:1
	v_max_f32_e32 v37, v37, v37
	v_max_f32_e32 v36, v36, v37
	s_nop 1
	v_mov_b32_dpp v37, v36 row_half_mirror row_mask:0xf bank_mask:0xf bound_ctrl:1
	v_max_f32_e32 v37, v37, v37
	v_max_f32_e32 v36, v36, v37
	s_nop 1
	v_mov_b32_dpp v37, v36 row_mirror row_mask:0xf bank_mask:0xf bound_ctrl:1
	v_max_f32_e32 v37, v37, v37
	v_max_f32_e32 v36, v36, v37
	s_nop 0
	v_readlane_b32 s74, v36, 0
	v_readlane_b32 s92, v36, 16
	v_readlane_b32 s90, v36, 32
	v_readlane_b32 s91, v36, 48
	v_lshl_add_u64 v[36:37], s[24:25], 0, v[88:89]
	v_mov_b32_e32 v36, v228
	v_lshl_add_u64 v[88:89], s[26:27], 0, v[88:89]
	v_mov_b32_e32 v88, v230
	s_waitcnt vmcnt(2)
	v_ashrrev_i32_e32 v39, 5, v38
	v_mov_b32_e32 v89, v231
	v_add_u32_e32 v238, 0x1800, v236
	global_load_dwordx4 v[200:203], v238, s[98:99] offset:16
	global_load_dwordx4 v[204:207], v238, s[98:99]
	v_add_u32_e32 v239, 0x600, v237
	global_load_dword v232, v239, s[24:25]
	global_load_dword v233, v239, s[24:25] offset:256
	global_load_dword v234, v239, s[26:27]
	global_load_dword v235, v239, s[26:27] offset:256
	s_nop 0
	ds_write_b32 v20, v155
	ds_write_b32 v22, v155
	ds_write_b32 v24, v155
	ds_write_b32 v26, v155
	ds_write_b32 v28, v155
	ds_write_b32 v30, v155
	ds_write_b32 v32, v155
	ds_write_b32 v34, v155
	v_lshl_add_u32 v98, v39, 2, s93
	v_ashrrev_i32_e32 v37, 5, v36
	v_lshl_add_u32 v90, v37, 2, s93
	ds_add_rtn_u32 v37, v90, v208 offset:12288
	ds_add_rtn_u32 v39, v98, v208 offset:12288
	s_waitcnt lgkmcnt(0)
	ds_read_b32 v92, v2
	ds_read_b32 v91, v4
	ds_read_b32 v94, v6
	ds_read_b32 v93, v8
	s_waitcnt lgkmcnt(0)
	v_add_u32_e32 v95, v91, v92
	v_add3_u32 v97, v95, v94, v93
	ds_read_b32 v96, v10
	ds_read_b32 v95, v12
	s_waitcnt lgkmcnt(0)
	v_add3_u32 v99, v97, v96, v95
	ds_read_b32 v97, v14
	ds_read_b32 v100, v16
	s_waitcnt lgkmcnt(0)
	v_add3_u32 v99, v99, v97, v100
	v_cvt_f32_u32_e32 v100, v99
	s_nop 1
	v_add_f32_dpp v100, v100, v100 row_shr:1 row_mask:0xf bank_mask:0xf bound_ctrl:1
	s_nop 1
	v_add_f32_dpp v100, v100, v100 row_shr:2 row_mask:0xf bank_mask:0xf bound_ctrl:1
	s_nop 1
	v_add_f32_dpp v100, v100, v100 row_shr:4 row_mask:0xf bank_mask:0xf bound_ctrl:1
	s_nop 1
	v_add_f32_dpp v100, v100, v100 row_shr:8 row_mask:0xf bank_mask:0xf bound_ctrl:1
	s_nop 0
	v_readlane_b32 s10, v100, 15
	v_readlane_b32 s16, v100, 31
	v_readlane_b32 s11, v100, 47
	s_and_saveexec_b64 s[0:1], s[14:15]
	s_xor_b64 s[0:1], exec, s[0:1]
	s_cbranch_execz .LBB0_48
	s_and_saveexec_b64 s[18:19], s[12:13]
	s_xor_b64 s[50:51], exec, s[18:19]
	v_mov_b32_e32 v101, s10
	v_cndmask_b32_e32 v101, 0, v101, vcc
	s_andn2_saveexec_b64 s[50:51], s[50:51]
	v_mov_b32_e32 v101, s16
	v_add_f32_e32 v101, s10, v101
	s_or_b64 exec, exec, s[50:51]
.LBB0_48:
	s_andn2_saveexec_b64 s[0:1], s[0:1]
	v_mov_b32_e32 v101, s16
	v_add_f32_e32 v101, s10, v101
	v_add_f32_e32 v101, s11, v101
	s_or_b64 exec, exec, s[0:1]
	v_add_u32_e32 v90, 0x3000, v90
	v_cmp_ne_u32_e64 s[0:1], -1, v90
	v_readlane_b32 s10, v254, 10
	v_readlane_b32 s11, v254, 11
	v_cndmask_b32_e64 v102, 0, v90, s[0:1]
	v_add_f32_e32 v90, v100, v101
	v_cvt_u32_f32_e32 v90, v90
	v_mov_b32_e32 v104, s11
	v_cndmask_b32_e64 v103, 0, v104, s[0:1]
	v_add_u32_e32 v98, 0x3000, v98
	v_sub_u32_e32 v90, v90, v99
	ds_write_b32 v2, v90
	v_add_u32_e32 v90, v90, v92
	ds_write_b32 v4, v90
	v_add_u32_e32 v90, v90, v91
	ds_write_b32 v6, v90
	v_add_u32_e32 v90, v90, v94
	ds_write_b32 v8, v90
	v_add_u32_e32 v90, v90, v93
	ds_write_b32 v10, v90
	v_add_u32_e32 v90, v90, v96
	ds_write_b32 v12, v90
	v_add_u32_e32 v90, v90, v95
	ds_write_b32 v14, v90
	v_add_u32_e32 v90, v90, v97
	ds_write_b32 v16, v90
	s_waitcnt lgkmcnt(0)
	ds_read_b32 v90, v102
	v_cmp_ne_u32_e64 s[0:1], -1, v98
	s_waitcnt lgkmcnt(0)
	v_add_u32_e32 v94, v90, v37
	v_cndmask_b32_e64 v105, 0, v104, s[0:1]
	v_cndmask_b32_e64 v104, 0, v98, s[0:1]
	ds_read_b32 v37, v104
	s_waitcnt lgkmcnt(0)
	s_or_b32 s0, s40, 3
	s_ashr_i32 s1, s0, 31
	s_lshl_b64 s[50:51], s[0:1], 11
	v_writelane_b32 v254, s0, 50
	s_waitcnt lgkmcnt(0)
	v_add_u32_e32 v95, v37, v39
	v_ashrrev_i32_e32 v37, 31, v36
	v_lshl_add_u64 v[90:91], v[36:37], 3, s[28:29]
	v_ashrrev_i32_e32 v39, 31, v38
	global_load_dwordx2 v[90:91], v[90:91], off
	v_lshl_add_u64 v[92:93], v[38:39], 3, s[28:29]
	global_load_dwordx2 v[92:93], v[92:93], off
	v_lshl_add_u32 v37, v94, 2, s93
	v_writelane_b32 v254, s1, 51
	s_lshl_b64 s[0:1], s[0:1], 9
	v_lshl_or_b32 v94, v55, 2, s0
	v_or_b32_e32 v96, 0x100, v94
	v_mov_b32_e32 v97, s1
	s_waitcnt vmcnt(1)
	v_mul_f32_e32 v39, v88, v91
	ds_write2st64_b32 v37, v36, v39 offset0:12 offset1:14
	ds_write_b32 v37, v90 offset:4096
	v_lshl_add_u32 v36, v95, 2, s93
	s_waitcnt vmcnt(0)
	v_mul_f32_e32 v37, v89, v93
	ds_write2st64_b32 v36, v38, v37 offset0:12 offset1:14
	ds_write_b32 v36, v92 offset:4096
	v_lshl_add_u64 v[88:89], v[18:19], 0, s[50:51]
	v_mov_b32_e32 v36, v200
	v_mov_b32_e32 v37, v201
	v_mov_b32_e32 v38, v202
	v_mov_b32_e32 v39, v203
	v_mov_b32_e32 v90, v204
	v_mov_b32_e32 v91, v205
	v_mov_b32_e32 v92, v206
	v_mov_b32_e32 v93, v207
	v_mov_b32_e32 v95, s1
	v_lshlrev_b32_e32 v112, 16, v36
	v_lshlrev_b32_e32 v110, 16, v90
	v_and_b32_e32 v119, 0xffff0000, v90
	v_and_b32_e32 v113, 0xffff0000, v36
	v_lshlrev_b32_e32 v111, 16, v91
	v_and_b32_e32 v114, 0xffff0000, v91
	v_max3_f32 v36, |v110|, 0, |v119|
	v_lshlrev_b32_e32 v115, 16, v92
	v_and_b32_e32 v116, 0xffff0000, v92
	v_max3_f32 v36, v36, |v111|, |v114|
	v_lshlrev_b32_e32 v117, 16, v93
	v_and_b32_e32 v118, 0xffff0000, v93
	v_max3_f32 v36, v36, |v115|, |v116|
	v_max3_f32 v36, v36, |v117|, |v118|
	v_lshlrev_b32_e32 v88, 16, v37
	v_and_b32_e32 v89, 0xffff0000, v37
	v_max3_f32 v36, v36, |v112|, |v113|
	v_lshlrev_b32_e32 v90, 16, v38
	v_and_b32_e32 v91, 0xffff0000, v38
	v_max3_f32 v36, v36, |v88|, |v89|
	v_lshlrev_b32_e32 v92, 16, v39
	v_and_b32_e32 v93, 0xffff0000, v39
	v_max3_f32 v36, v36, |v90|, |v91|
	v_max3_f32 v36, v36, |v92|, |v93|
	v_lshl_add_u64 v[38:39], s[24:25], 0, v[96:97]
	v_mov_b32_e32 v38, v233
	v_mov_b32_dpp v37, v36 quad_perm:[1,0,3,2] row_mask:0xf bank_mask:0xf bound_ctrl:1
	v_max_f32_e32 v37, v37, v37
	v_max_f32_e32 v36, v36, v37
	v_lshl_add_u64 v[96:97], s[26:27], 0, v[96:97]
	s_nop 0
	v_mov_b32_dpp v37, v36 quad_perm:[2,3,0,1] row_mask:0xf bank_mask:0xf bound_ctrl:1
	v_max_f32_e32 v37, v37, v37
	v_max_f32_e32 v36, v36, v37
	s_nop 1
	v_mov_b32_dpp v37, v36 row_half_mirror row_mask:0xf bank_mask:0xf bound_ctrl:1
	v_max_f32_e32 v37, v37, v37
	v_max_f32_e32 v36, v36, v37
	s_nop 1
	v_mov_b32_dpp v37, v36 row_mirror row_mask:0xf bank_mask:0xf bound_ctrl:1
	v_max_f32_e32 v37, v37, v37
	v_max_f32_e32 v36, v36, v37
	s_nop 0
	v_readlane_b32 s20, v36, 0
	v_readlane_b32 s30, v36, 16
	v_readlane_b32 s97, v36, 32
	v_readlane_b32 s21, v36, 48
	v_lshl_add_u64 v[36:37], s[24:25], 0, v[94:95]
	v_mov_b32_e32 v36, v232
	v_lshl_add_u64 v[94:95], s[26:27], 0, v[94:95]
	v_mov_b32_e32 v94, v234
	s_waitcnt vmcnt(2)
	v_ashrrev_i32_e32 v39, 5, v38
	v_mov_b32_e32 v95, v235
	v_add_u32_e32 v238, 0x2000, v236
	global_load_dwordx4 v[192:195], v238, s[98:99] offset:16
	global_load_dwordx4 v[196:199], v238, s[98:99]
	v_add_u32_e32 v239, 0x800, v237
	global_load_dword v228, v239, s[24:25]
	global_load_dword v229, v239, s[24:25] offset:256
	global_load_dword v230, v239, s[26:27]
	global_load_dword v231, v239, s[26:27] offset:256
	s_nop 0
	ds_write_b32 v20, v155
	ds_write_b32 v22, v155
	ds_write_b32 v24, v155
	ds_write_b32 v26, v155
	ds_write_b32 v28, v155
	ds_write_b32 v30, v155
	ds_write_b32 v32, v155
	ds_write_b32 v34, v155
	v_lshl_add_u32 v104, v39, 2, s93
	v_ashrrev_i32_e32 v37, 5, v36
	v_lshl_add_u32 v96, v37, 2, s93
	ds_add_rtn_u32 v37, v96, v208 offset:12288
	ds_add_rtn_u32 v39, v104, v208 offset:12288
	s_waitcnt lgkmcnt(0)
	ds_read_b32 v98, v2
	ds_read_b32 v97, v4
	ds_read_b32 v100, v6
	ds_read_b32 v99, v8
	s_waitcnt lgkmcnt(0)
	v_add_u32_e32 v101, v97, v98
	v_add3_u32 v103, v101, v100, v99
	ds_read_b32 v102, v10
	ds_read_b32 v101, v12
	s_waitcnt lgkmcnt(0)
	v_add3_u32 v105, v103, v102, v101
	ds_read_b32 v103, v14
	ds_read_b32 v106, v16
	s_waitcnt lgkmcnt(0)
	v_add3_u32 v105, v105, v103, v106
	v_cvt_f32_u32_e32 v106, v105
	s_nop 1
	v_add_f32_dpp v106, v106, v106 row_shr:1 row_mask:0xf bank_mask:0xf bound_ctrl:1
	s_nop 1
	v_add_f32_dpp v106, v106, v106 row_shr:2 row_mask:0xf bank_mask:0xf bound_ctrl:1
	s_nop 1
	v_add_f32_dpp v106, v106, v106 row_shr:4 row_mask:0xf bank_mask:0xf bound_ctrl:1
	s_nop 1
	v_add_f32_dpp v106, v106, v106 row_shr:8 row_mask:0xf bank_mask:0xf bound_ctrl:1
	s_nop 0
	v_readlane_b32 s10, v106, 15
	v_readlane_b32 s16, v106, 31
	v_readlane_b32 s11, v106, 47
	s_and_saveexec_b64 s[0:1], s[14:15]
	s_xor_b64 s[0:1], exec, s[0:1]
	s_cbranch_execz .LBB0_56
	s_and_saveexec_b64 s[18:19], s[12:13]
	s_xor_b64 s[54:55], exec, s[18:19]
	v_mov_b32_e32 v107, s10
	v_cndmask_b32_e32 v107, 0, v107, vcc
	s_andn2_saveexec_b64 s[54:55], s[54:55]
	v_mov_b32_e32 v107, s16
	v_add_f32_e32 v107, s10, v107
	s_or_b64 exec, exec, s[54:55]
.LBB0_56:
	s_andn2_saveexec_b64 s[0:1], s[0:1]
	v_mov_b32_e32 v107, s16
	v_add_f32_e32 v107, s10, v107
	v_add_f32_e32 v107, s11, v107
	s_or_b64 exec, exec, s[0:1]
	v_add_u32_e32 v96, 0x3000, v96
	v_cmp_ne_u32_e64 s[0:1], -1, v96
	v_readlane_b32 s10, v254, 10
	v_readlane_b32 s11, v254, 11
	v_cndmask_b32_e64 v108, 0, v96, s[0:1]
	v_add_f32_e32 v96, v106, v107
	v_cvt_u32_f32_e32 v96, v96
	v_mov_b32_e32 v120, s11
	v_cndmask_b32_e64 v109, 0, v120, s[0:1]
	v_add_u32_e32 v104, 0x3000, v104
	v_sub_u32_e32 v96, v96, v105
	ds_write_b32 v2, v96
	v_add_u32_e32 v96, v96, v98
	ds_write_b32 v4, v96
	v_add_u32_e32 v96, v96, v97
	ds_write_b32 v6, v96
	v_add_u32_e32 v96, v96, v100
	ds_write_b32 v8, v96
	v_add_u32_e32 v96, v96, v99
	ds_write_b32 v10, v96
	v_add_u32_e32 v96, v96, v102
	ds_write_b32 v12, v96
	v_add_u32_e32 v96, v96, v101
	ds_write_b32 v14, v96
	v_add_u32_e32 v96, v96, v103
	ds_write_b32 v16, v96
	s_waitcnt lgkmcnt(0)
	ds_read_b32 v96, v108
	v_cmp_ne_u32_e64 s[0:1], -1, v104
	s_waitcnt lgkmcnt(0)
	v_add_u32_e32 v100, v96, v37
	v_cndmask_b32_e64 v121, 0, v120, s[0:1]
	v_cndmask_b32_e64 v120, 0, v104, s[0:1]
	ds_read_b32 v37, v120
	s_waitcnt lgkmcnt(0)
	s_or_b32 s0, s40, 4
	s_ashr_i32 s1, s0, 31
	s_lshl_b64 s[54:55], s[0:1], 11
	v_writelane_b32 v254, s0, 52
	s_waitcnt lgkmcnt(0)
	v_add_u32_e32 v101, v37, v39
	v_ashrrev_i32_e32 v37, 31, v36
	v_lshl_add_u64 v[96:97], v[36:37], 3, s[28:29]
	v_ashrrev_i32_e32 v39, 31, v38
	global_load_dwordx2 v[96:97], v[96:97], off
	v_lshl_add_u64 v[98:99], v[38:39], 3, s[28:29]
	global_load_dwordx2 v[98:99], v[98:99], off
	v_lshl_add_u32 v37, v100, 2, s93
	v_writelane_b32 v254, s1, 53
	s_lshl_b64 s[0:1], s[0:1], 9
	s_waitcnt vmcnt(1)
	v_mul_f32_e32 v39, v94, v97
	ds_write2st64_b32 v37, v36, v39 offset0:18 offset1:20
	ds_write_b32 v37, v96 offset:5632
	v_lshl_add_u32 v36, v101, 2, s93
	s_waitcnt vmcnt(0)
	v_mul_f32_e32 v37, v95, v99
	ds_write2st64_b32 v36, v38, v37 offset0:18 offset1:20
	ds_write_b32 v36, v98 offset:5632
	v_lshl_add_u64 v[94:95], v[18:19], 0, s[54:55]
	v_mov_b32_e32 v36, v192
	v_mov_b32_e32 v37, v193
	v_mov_b32_e32 v38, v194
	v_mov_b32_e32 v39, v195
	s_nop 0
	v_mov_b32_e32 v94, v196
	v_mov_b32_e32 v95, v197
	v_mov_b32_e32 v96, v198
	v_mov_b32_e32 v97, v199
	v_lshlrev_b32_e32 v108, 16, v36
	v_lshlrev_b32_e32 v106, 16, v94
	v_and_b32_e32 v141, 0xffff0000, v94
	v_and_b32_e32 v125, 0xffff0000, v36
	v_lshlrev_b32_e32 v107, 16, v95
	v_and_b32_e32 v126, 0xffff0000, v95
	v_max3_f32 v36, |v106|, 0, |v141|
	v_lshlrev_b32_e32 v127, 16, v96
	v_and_b32_e32 v138, 0xffff0000, v96
	v_max3_f32 v36, v36, |v107|, |v126|
	v_lshlrev_b32_e32 v139, 16, v97
	v_and_b32_e32 v140, 0xffff0000, v97
	v_max3_f32 v36, v36, |v127|, |v138|
	v_max3_f32 v36, v36, |v139|, |v140|
	v_lshlrev_b32_e32 v109, 16, v37
	v_and_b32_e32 v120, 0xffff0000, v37
	v_max3_f32 v36, v36, |v108|, |v125|
	v_lshlrev_b32_e32 v121, 16, v38
	v_and_b32_e32 v122, 0xffff0000, v38
	v_max3_f32 v36, v36, |v109|, |v120|
	v_lshlrev_b32_e32 v123, 16, v39
	v_and_b32_e32 v124, 0xffff0000, v39
	v_max3_f32 v36, v36, |v121|, |v122|
	v_max3_f32 v36, v36, |v123|, |v124|
	v_lshl_or_b32 v94, v55, 2, s0
	v_mov_b32_e32 v95, s1
	v_mov_b32_dpp v37, v36 quad_perm:[1,0,3,2] row_mask:0xf bank_mask:0xf bound_ctrl:1
	v_max_f32_e32 v37, v37, v37
	v_max_f32_e32 v36, v36, v37
	v_or_b32_e32 v96, 0x100, v94
	v_mov_b32_e32 v97, s1
	v_mov_b32_dpp v37, v36 quad_perm:[2,3,0,1] row_mask:0xf bank_mask:0xf bound_ctrl:1
	v_max_f32_e32 v37, v37, v37
	v_max_f32_e32 v36, v36, v37
	v_lshl_add_u64 v[38:39], s[24:25], 0, v[96:97]
	v_mov_b32_e32 v38, v229
	v_mov_b32_dpp v37, v36 row_half_mirror row_mask:0xf bank_mask:0xf bound_ctrl:1
	v_max_f32_e32 v37, v37, v37
	v_max_f32_e32 v36, v36, v37
	v_lshl_add_u64 v[96:97], s[26:27], 0, v[96:97]
	s_nop 0
	v_mov_b32_dpp v37, v36 row_mirror row_mask:0xf bank_mask:0xf bound_ctrl:1
	v_max_f32_e32 v37, v37, v37
	v_max_f32_e32 v36, v36, v37
	s_nop 0
	v_readlane_b32 s10, v36, 0
	v_readlane_b32 s16, v36, 16
	v_readlane_b32 s31, v36, 32
	v_readlane_b32 s11, v36, 48
	v_lshl_add_u64 v[36:37], s[24:25], 0, v[94:95]
	v_mov_b32_e32 v36, v228
	v_lshl_add_u64 v[94:95], s[26:27], 0, v[94:95]
	v_mov_b32_e32 v94, v230
	s_waitcnt vmcnt(2)
	v_ashrrev_i32_e32 v39, 5, v38
	v_mov_b32_e32 v95, v231
	v_add_u32_e32 v238, 0x2800, v236
	global_load_dwordx4 v[200:203], v238, s[98:99] offset:16
	global_load_dwordx4 v[204:207], v238, s[98:99]
	v_add_u32_e32 v239, 0xa00, v237
	global_load_dword v232, v239, s[24:25]
	global_load_dword v233, v239, s[24:25] offset:256
	global_load_dword v234, v239, s[26:27]
	global_load_dword v235, v239, s[26:27] offset:256
	s_nop 0
	ds_write_b32 v20, v155
	ds_write_b32 v22, v155
	ds_write_b32 v24, v155
	ds_write_b32 v26, v155
	ds_write_b32 v28, v155
	ds_write_b32 v30, v155
	ds_write_b32 v32, v155
	ds_write_b32 v34, v155
	v_lshl_add_u32 v104, v39, 2, s93
	v_ashrrev_i32_e32 v37, 5, v36
	v_lshl_add_u32 v96, v37, 2, s93
	ds_add_rtn_u32 v37, v96, v208 offset:12288
	ds_add_rtn_u32 v39, v104, v208 offset:12288
	s_waitcnt lgkmcnt(0)
	ds_read_b32 v98, v2
	ds_read_b32 v97, v4
	ds_read_b32 v100, v6
	ds_read_b32 v99, v8
	s_waitcnt lgkmcnt(0)
	v_add_u32_e32 v101, v97, v98
	v_add3_u32 v103, v101, v100, v99
	ds_read_b32 v102, v10
	ds_read_b32 v101, v12
	s_waitcnt lgkmcnt(0)
	v_add3_u32 v105, v103, v102, v101
	ds_read_b32 v103, v14
	ds_read_b32 v128, v16
	s_waitcnt lgkmcnt(0)
	v_add3_u32 v105, v105, v103, v128
	v_cvt_f32_u32_e32 v128, v105
	s_nop 1
	v_add_f32_dpp v128, v128, v128 row_shr:1 row_mask:0xf bank_mask:0xf bound_ctrl:1
	s_nop 1
	v_add_f32_dpp v128, v128, v128 row_shr:2 row_mask:0xf bank_mask:0xf bound_ctrl:1
	s_nop 1
	v_add_f32_dpp v128, v128, v128 row_shr:4 row_mask:0xf bank_mask:0xf bound_ctrl:1
	s_nop 1
	v_add_f32_dpp v128, v128, v128 row_shr:8 row_mask:0xf bank_mask:0xf bound_ctrl:1
	s_nop 0
	v_readlane_b32 s17, v128, 15
	v_readlane_b32 s19, v128, 31
	v_readlane_b32 s18, v128, 47
	s_and_saveexec_b64 s[0:1], s[14:15]
	s_xor_b64 s[0:1], exec, s[0:1]
	s_cbranch_execz .LBB0_64
	s_and_saveexec_b64 s[44:45], s[12:13]
	s_xor_b64 s[58:59], exec, s[44:45]
	v_mov_b32_e32 v129, s17
	v_cndmask_b32_e32 v129, 0, v129, vcc
	s_andn2_saveexec_b64 s[58:59], s[58:59]
	v_mov_b32_e32 v129, s19
	v_add_f32_e32 v129, s17, v129
	s_or_b64 exec, exec, s[58:59]
.LBB0_64:
	s_andn2_saveexec_b64 s[0:1], s[0:1]
	v_mov_b32_e32 v129, s19
	v_add_f32_e32 v129, s17, v129
	v_add_f32_e32 v129, s18, v129
	s_or_b64 exec, exec, s[0:1]
	v_add_u32_e32 v96, 0x3000, v96
	v_cmp_ne_u32_e64 s[0:1], -1, v96
	v_readlane_b32 s18, v254, 10
	v_readlane_b32 s19, v254, 11
	v_cndmask_b32_e64 v136, 0, v96, s[0:1]
	v_add_f32_e32 v96, v128, v129
	v_cvt_u32_f32_e32 v96, v96
	v_mov_b32_e32 v142, s19
	v_cndmask_b32_e64 v137, 0, v142, s[0:1]
	v_add_u32_e32 v104, 0x3000, v104
	v_sub_u32_e32 v96, v96, v105
	ds_write_b32 v2, v96
	v_add_u32_e32 v96, v96, v98
	ds_write_b32 v4, v96
	v_add_u32_e32 v96, v96, v97
	ds_write_b32 v6, v96
	v_add_u32_e32 v96, v96, v100
	ds_write_b32 v8, v96
	v_add_u32_e32 v96, v96, v99
	ds_write_b32 v10, v96
	v_add_u32_e32 v96, v96, v102
	ds_write_b32 v12, v96
	v_add_u32_e32 v96, v96, v101
	ds_write_b32 v14, v96
	v_add_u32_e32 v96, v96, v103
	ds_write_b32 v16, v96
	s_waitcnt lgkmcnt(0)
	ds_read_b32 v96, v136
	v_cmp_ne_u32_e64 s[0:1], -1, v104
	s_or_b32 s62, s40, 5
	s_ashr_i32 s63, s62, 31
	v_cndmask_b32_e64 v143, 0, v142, s[0:1]
	v_cndmask_b32_e64 v142, 0, v104, s[0:1]
	s_lshl_b64 s[58:59], s[62:63], 11
	s_lshl_b64 s[0:1], s[62:63], 9
	s_waitcnt lgkmcnt(0)
	v_add_u32_e32 v100, v96, v37
	ds_read_b32 v37, v142
	s_waitcnt lgkmcnt(0)
	s_waitcnt lgkmcnt(0)
	v_add_u32_e32 v101, v37, v39
	v_ashrrev_i32_e32 v37, 31, v36
	v_lshl_add_u64 v[96:97], v[36:37], 3, s[28:29]
	v_ashrrev_i32_e32 v39, 31, v38
	global_load_dwordx2 v[96:97], v[96:97], off
	v_lshl_add_u64 v[98:99], v[38:39], 3, s[28:29]
	global_load_dwordx2 v[98:99], v[98:99], off
	v_lshl_add_u32 v37, v100, 2, s93
	s_waitcnt vmcnt(1)
	v_mul_f32_e32 v39, v94, v97
	ds_write2st64_b32 v37, v36, v39 offset0:24 offset1:26
	ds_write_b32 v37, v96 offset:7168
	v_lshl_add_u32 v36, v101, 2, s93
	s_waitcnt vmcnt(0)
	v_mul_f32_e32 v37, v95, v99
	ds_write2st64_b32 v36, v38, v37 offset0:24 offset1:26
	ds_write_b32 v36, v98 offset:7168
	v_lshl_add_u64 v[94:95], v[18:19], 0, s[58:59]
	v_mov_b32_e32 v36, v200
	v_mov_b32_e32 v37, v201
	v_mov_b32_e32 v38, v202
	v_mov_b32_e32 v39, v203
	s_nop 0
	v_mov_b32_e32 v94, v204
	v_mov_b32_e32 v95, v205
	v_mov_b32_e32 v96, v206
	v_mov_b32_e32 v97, v207
	v_lshlrev_b32_e32 v104, 16, v36
	v_lshlrev_b32_e32 v102, 16, v94
	v_and_b32_e32 v152, 0xffff0000, v94
	v_and_b32_e32 v146, 0xffff0000, v36
	v_lshlrev_b32_e32 v103, 16, v95
	v_and_b32_e32 v147, 0xffff0000, v95
	v_max3_f32 v36, |v102|, 0, |v152|
	v_lshlrev_b32_e32 v148, 16, v96
	v_and_b32_e32 v149, 0xffff0000, v96
	v_max3_f32 v36, v36, |v103|, |v147|
	v_lshlrev_b32_e32 v150, 16, v97
	v_and_b32_e32 v151, 0xffff0000, v97
	v_max3_f32 v36, v36, |v148|, |v149|
	v_max3_f32 v36, v36, |v150|, |v151|
	v_lshlrev_b32_e32 v105, 16, v37
	v_and_b32_e32 v137, 0xffff0000, v37
	v_max3_f32 v36, v36, |v104|, |v146|
	v_lshlrev_b32_e32 v142, 16, v38
	v_and_b32_e32 v143, 0xffff0000, v38
	v_max3_f32 v36, v36, |v105|, |v137|
	v_lshlrev_b32_e32 v144, 16, v39
	v_and_b32_e32 v145, 0xffff0000, v39
	v_max3_f32 v36, v36, |v142|, |v143|
	v_max3_f32 v36, v36, |v144|, |v145|
	v_lshl_or_b32 v94, v55, 2, s0
	v_mov_b32_e32 v95, s1
	v_mov_b32_dpp v37, v36 quad_perm:[1,0,3,2] row_mask:0xf bank_mask:0xf bound_ctrl:1
	v_max_f32_e32 v37, v37, v37
	v_max_f32_e32 v36, v36, v37
	v_or_b32_e32 v96, 0x100, v94
	v_mov_b32_e32 v97, s1
	v_mov_b32_dpp v37, v36 quad_perm:[2,3,0,1] row_mask:0xf bank_mask:0xf bound_ctrl:1
	v_max_f32_e32 v37, v37, v37
	v_max_f32_e32 v36, v36, v37
	v_lshl_add_u64 v[38:39], s[24:25], 0, v[96:97]
	v_mov_b32_e32 v38, v233
	v_mov_b32_dpp v37, v36 row_half_mirror row_mask:0xf bank_mask:0xf bound_ctrl:1
	v_max_f32_e32 v37, v37, v37
	v_max_f32_e32 v36, v36, v37
	v_lshl_add_u64 v[96:97], s[26:27], 0, v[96:97]
	s_nop 0
	v_mov_b32_dpp v37, v36 row_mirror row_mask:0xf bank_mask:0xf bound_ctrl:1
	v_max_f32_e32 v37, v37, v37
	v_max_f32_e32 v36, v36, v37
	s_nop 0
	v_readlane_b32 s75, v36, 0
	v_readlane_b32 s19, v36, 16
	v_readlane_b32 s17, v36, 32
	v_readlane_b32 s18, v36, 48
	v_lshl_add_u64 v[36:37], s[24:25], 0, v[94:95]
	v_mov_b32_e32 v36, v232
	v_lshl_add_u64 v[94:95], s[26:27], 0, v[94:95]
	v_mov_b32_e32 v94, v234
	s_waitcnt vmcnt(2)
	v_ashrrev_i32_e32 v39, 5, v38
	v_mov_b32_e32 v95, v235
	v_add_u32_e32 v238, 0x3000, v236
	global_load_dwordx4 v[192:195], v238, s[98:99] offset:16
	global_load_dwordx4 v[196:199], v238, s[98:99]
	v_add_u32_e32 v239, 0xc00, v237
	global_load_dword v228, v239, s[24:25]
	global_load_dword v229, v239, s[24:25] offset:256
	global_load_dword v230, v239, s[26:27]
	global_load_dword v231, v239, s[26:27] offset:256
	s_nop 0
	ds_write_b32 v20, v155
	ds_write_b32 v22, v155
	ds_write_b32 v24, v155
	ds_write_b32 v26, v155
	ds_write_b32 v28, v155
	ds_write_b32 v30, v155
	ds_write_b32 v32, v155
	ds_write_b32 v34, v155
	v_lshl_add_u32 v136, v39, 2, s93
	v_ashrrev_i32_e32 v37, 5, v36
	v_lshl_add_u32 v96, v37, 2, s93
	ds_add_rtn_u32 v37, v96, v208 offset:12288
	ds_add_rtn_u32 v39, v136, v208 offset:12288
	s_waitcnt lgkmcnt(0)
	ds_read_b32 v98, v2
	ds_read_b32 v97, v4
	ds_read_b32 v100, v6
	ds_read_b32 v99, v8
	s_waitcnt lgkmcnt(0)
	v_add_u32_e32 v101, v97, v98
	v_add3_u32 v129, v101, v100, v99
	ds_read_b32 v128, v10
	ds_read_b32 v101, v12
	s_waitcnt lgkmcnt(0)
	v_add3_u32 v153, v129, v128, v101
	ds_read_b32 v129, v14
	ds_read_b32 v154, v16
	s_waitcnt lgkmcnt(0)
	v_add3_u32 v153, v153, v129, v154
	v_cvt_f32_u32_e32 v154, v153
	s_nop 1
	v_add_f32_dpp v154, v154, v154 row_shr:1 row_mask:0xf bank_mask:0xf bound_ctrl:1
	s_nop 1
	v_add_f32_dpp v154, v154, v154 row_shr:2 row_mask:0xf bank_mask:0xf bound_ctrl:1
	s_nop 1
	v_add_f32_dpp v154, v154, v154 row_shr:4 row_mask:0xf bank_mask:0xf bound_ctrl:1
	s_nop 1
	v_add_f32_dpp v154, v154, v154 row_shr:8 row_mask:0xf bank_mask:0xf bound_ctrl:1
	s_nop 0
	v_readlane_b32 s44, v154, 15
	v_readlane_b32 s48, v154, 31
	v_readlane_b32 s45, v154, 47
	s_and_saveexec_b64 s[0:1], s[14:15]
	s_xor_b64 s[0:1], exec, s[0:1]
	s_cbranch_execz .LBB0_72
	s_and_saveexec_b64 s[52:53], s[12:13]
	s_xor_b64 s[64:65], exec, s[52:53]
	v_mov_b32_e32 v160, s44
	v_cndmask_b32_e32 v160, 0, v160, vcc
	s_andn2_saveexec_b64 s[64:65], s[64:65]
	v_mov_b32_e32 v160, s48
	v_add_f32_e32 v160, s44, v160
	s_or_b64 exec, exec, s[64:65]
.LBB0_72:
	s_andn2_saveexec_b64 s[0:1], s[0:1]
	v_mov_b32_e32 v160, s48
	v_add_f32_e32 v160, s44, v160
	v_add_f32_e32 v160, s45, v160
	s_or_b64 exec, exec, s[0:1]
	v_add_u32_e32 v96, 0x3000, v96
	v_cmp_ne_u32_e64 s[0:1], -1, v96
	v_readlane_b32 s44, v254, 10
	v_readlane_b32 s45, v254, 11
	v_cndmask_b32_e64 v162, 0, v96, s[0:1]
	v_add_f32_e32 v96, v154, v160
	v_cvt_u32_f32_e32 v96, v96
	v_mov_b32_e32 v161, s45
	v_cndmask_b32_e64 v163, 0, v161, s[0:1]
	v_add_u32_e32 v136, 0x3000, v136
	v_sub_u32_e32 v96, v96, v153
	ds_write_b32 v2, v96
	v_add_u32_e32 v96, v96, v98
	ds_write_b32 v4, v96
	v_add_u32_e32 v96, v96, v97
	ds_write_b32 v6, v96
	v_add_u32_e32 v96, v96, v100
	ds_write_b32 v8, v96
	v_add_u32_e32 v96, v96, v99
	ds_write_b32 v10, v96
	v_add_u32_e32 v96, v96, v128
	ds_write_b32 v12, v96
	v_add_u32_e32 v96, v96, v101
	ds_write_b32 v14, v96
	v_add_u32_e32 v96, v96, v129
	ds_write_b32 v16, v96
	s_waitcnt lgkmcnt(0)
	ds_read_b32 v96, v162
	v_cmp_ne_u32_e64 s[0:1], -1, v136
	s_or_b32 s66, s40, 6
	s_ashr_i32 s67, s66, 31
	v_cndmask_b32_e64 v165, 0, v161, s[0:1]
	v_cndmask_b32_e64 v164, 0, v136, s[0:1]
	s_lshl_b64 s[64:65], s[66:67], 11
	s_lshl_b64 s[0:1], s[66:67], 9
	s_waitcnt lgkmcnt(0)
	v_add_u32_e32 v100, v96, v37
	ds_read_b32 v37, v164
	s_waitcnt lgkmcnt(0)
	s_waitcnt lgkmcnt(0)
	v_add_u32_e32 v101, v37, v39
	v_ashrrev_i32_e32 v37, 31, v36
	v_lshl_add_u64 v[96:97], v[36:37], 3, s[28:29]
	v_ashrrev_i32_e32 v39, 31, v38
	global_load_dwordx2 v[96:97], v[96:97], off
	v_lshl_add_u64 v[98:99], v[38:39], 3, s[28:29]
	global_load_dwordx2 v[98:99], v[98:99], off
	v_lshl_add_u32 v37, v100, 2, s93
	s_waitcnt vmcnt(1)
	v_mul_f32_e32 v39, v94, v97
	ds_write2st64_b32 v37, v36, v39 offset0:30 offset1:32
	ds_write_b32 v37, v96 offset:8704
	v_lshl_add_u32 v36, v101, 2, s93
	s_waitcnt vmcnt(0)
	v_mul_f32_e32 v37, v95, v99
	ds_write2st64_b32 v36, v38, v37 offset0:30 offset1:32
	ds_write_b32 v36, v98 offset:8704
	v_lshl_add_u64 v[94:95], v[18:19], 0, s[64:65]
	v_mov_b32_e32 v36, v192
	v_mov_b32_e32 v37, v193
	v_mov_b32_e32 v38, v194
	v_mov_b32_e32 v39, v195
	s_nop 0
	v_mov_b32_e32 v94, v196
	v_mov_b32_e32 v95, v197
	v_mov_b32_e32 v96, v198
	v_mov_b32_e32 v97, v199
	v_lshlrev_b32_e32 v100, 16, v36
	v_lshlrev_b32_e32 v98, 16, v94
	v_and_b32_e32 v168, 0xffff0000, v94
	v_and_b32_e32 v162, 0xffff0000, v36
	v_lshlrev_b32_e32 v99, 16, v95
	v_and_b32_e32 v163, 0xffff0000, v95
	v_max3_f32 v36, |v98|, 0, |v168|
	v_lshlrev_b32_e32 v164, 16, v96
	v_and_b32_e32 v165, 0xffff0000, v96
	v_max3_f32 v36, v36, |v99|, |v163|
	v_lshlrev_b32_e32 v166, 16, v97
	v_and_b32_e32 v167, 0xffff0000, v97
	v_max3_f32 v36, v36, |v164|, |v165|
	v_max3_f32 v36, v36, |v166|, |v167|
	v_lshlrev_b32_e32 v101, 16, v37
	v_and_b32_e32 v136, 0xffff0000, v37
	v_max3_f32 v36, v36, |v100|, |v162|
	v_lshlrev_b32_e32 v153, 16, v38
	v_and_b32_e32 v154, 0xffff0000, v38
	v_max3_f32 v36, v36, |v101|, |v136|
	v_lshlrev_b32_e32 v160, 16, v39
	v_and_b32_e32 v161, 0xffff0000, v39
	v_max3_f32 v36, v36, |v153|, |v154|
	v_max3_f32 v36, v36, |v160|, |v161|
	v_lshl_or_b32 v94, v55, 2, s0
	v_mov_b32_e32 v95, s1
	v_mov_b32_dpp v37, v36 quad_perm:[1,0,3,2] row_mask:0xf bank_mask:0xf bound_ctrl:1
	v_max_f32_e32 v37, v37, v37
	v_max_f32_e32 v36, v36, v37
	v_or_b32_e32 v96, 0x100, v94
	v_mov_b32_e32 v97, s1
	v_mov_b32_dpp v37, v36 quad_perm:[2,3,0,1] row_mask:0xf bank_mask:0xf bound_ctrl:1
	v_max_f32_e32 v37, v37, v37
	v_max_f32_e32 v36, v36, v37
	v_lshl_add_u64 v[38:39], s[24:25], 0, v[96:97]
	v_mov_b32_e32 v38, v229
	v_mov_b32_dpp v37, v36 row_half_mirror row_mask:0xf bank_mask:0xf bound_ctrl:1
	v_max_f32_e32 v37, v37, v37
	v_max_f32_e32 v36, v36, v37
	v_lshl_add_u64 v[96:97], s[26:27], 0, v[96:97]
	s_nop 0
	v_mov_b32_dpp v37, v36 row_mirror row_mask:0xf bank_mask:0xf bound_ctrl:1
	v_max_f32_e32 v37, v37, v37
	v_max_f32_e32 v36, v36, v37
	s_nop 0
	v_readlane_b32 s72, v36, 0
	v_readlane_b32 s94, v36, 16
	v_readlane_b32 s60, v36, 32
	v_readlane_b32 s73, v36, 48
	v_lshl_add_u64 v[36:37], s[24:25], 0, v[94:95]
	v_mov_b32_e32 v36, v228
	v_lshl_add_u64 v[94:95], s[26:27], 0, v[94:95]
	v_mov_b32_e32 v94, v230
	s_waitcnt vmcnt(2)
	v_ashrrev_i32_e32 v39, 5, v38
	v_mov_b32_e32 v95, v231
	v_add_u32_e32 v238, 0x3800, v236
	global_load_dwordx4 v[200:203], v238, s[98:99] offset:16
	global_load_dwordx4 v[204:207], v238, s[98:99]
	v_add_u32_e32 v239, 0xe00, v237
	global_load_dword v232, v239, s[24:25]
	global_load_dword v233, v239, s[24:25] offset:256
	global_load_dword v234, v239, s[26:27]
	global_load_dword v235, v239, s[26:27] offset:256
	s_nop 0
	ds_write_b32 v20, v155
	ds_write_b32 v22, v155
	ds_write_b32 v24, v155
	ds_write_b32 v26, v155
	ds_write_b32 v28, v155
	ds_write_b32 v30, v155
	ds_write_b32 v32, v155
	ds_write_b32 v34, v155
	v_lshl_add_u32 v173, v39, 2, s93
	v_ashrrev_i32_e32 v37, 5, v36
	v_lshl_add_u32 v96, v37, 2, s93
	ds_add_rtn_u32 v37, v96, v208 offset:12288
	ds_add_rtn_u32 v39, v173, v208 offset:12288
	s_waitcnt lgkmcnt(0)
	ds_read_b32 v128, v2
	ds_read_b32 v97, v4
	ds_read_b32 v169, v6
	ds_read_b32 v129, v8
	s_waitcnt lgkmcnt(0)
	v_add_u32_e32 v170, v97, v128
	v_add3_u32 v172, v170, v169, v129
	ds_read_b32 v171, v10
	ds_read_b32 v170, v12
	s_waitcnt lgkmcnt(0)
	v_add3_u32 v174, v172, v171, v170
	ds_read_b32 v172, v14
	ds_read_b32 v175, v16
	s_waitcnt lgkmcnt(0)
	v_add3_u32 v174, v174, v172, v175
	v_cvt_f32_u32_e32 v175, v174
	s_nop 1
	v_add_f32_dpp v175, v175, v175 row_shr:1 row_mask:0xf bank_mask:0xf bound_ctrl:1
	s_nop 1
	v_add_f32_dpp v175, v175, v175 row_shr:2 row_mask:0xf bank_mask:0xf bound_ctrl:1
	s_nop 1
	v_add_f32_dpp v175, v175, v175 row_shr:4 row_mask:0xf bank_mask:0xf bound_ctrl:1
	s_nop 1
	v_add_f32_dpp v175, v175, v175 row_shr:8 row_mask:0xf bank_mask:0xf bound_ctrl:1
	s_nop 0
	v_readlane_b32 s44, v175, 15
	v_readlane_b32 s48, v175, 31
	v_readlane_b32 s45, v175, 47
	s_and_saveexec_b64 s[0:1], s[14:15]
	s_xor_b64 s[0:1], exec, s[0:1]
	s_cbranch_execz .LBB0_80
	s_and_saveexec_b64 s[52:53], s[12:13]
	s_xor_b64 s[68:69], exec, s[52:53]
	v_mov_b32_e32 v184, s44
	v_cndmask_b32_e32 v184, 0, v184, vcc
	s_andn2_saveexec_b64 s[68:69], s[68:69]
	v_mov_b32_e32 v184, s48
	v_add_f32_e32 v184, s44, v184
	s_or_b64 exec, exec, s[68:69]
.LBB0_80:
	s_andn2_saveexec_b64 s[0:1], s[0:1]
	v_mov_b32_e32 v184, s48
	v_add_f32_e32 v184, s44, v184
	v_add_f32_e32 v184, s45, v184
	s_or_b64 exec, exec, s[0:1]
	v_add_u32_e32 v96, 0x3000, v96
	v_cmp_ne_u32_e64 s[0:1], -1, v96
	v_readlane_b32 s44, v254, 10
	v_readlane_b32 s45, v254, 11
	v_cndmask_b32_e64 v186, 0, v96, s[0:1]
	v_add_f32_e32 v96, v175, v184
	v_cvt_u32_f32_e32 v96, v96
	v_mov_b32_e32 v185, s45
	v_cndmask_b32_e64 v187, 0, v185, s[0:1]
	v_add_u32_e32 v173, 0x3000, v173
	v_sub_u32_e32 v96, v96, v174
	ds_write_b32 v2, v96
	v_add_u32_e32 v96, v96, v128
	ds_write_b32 v4, v96
	v_add_u32_e32 v96, v96, v97
	ds_write_b32 v6, v96
	v_add_u32_e32 v96, v96, v169
	ds_write_b32 v8, v96
	v_add_u32_e32 v96, v96, v129
	ds_write_b32 v10, v96
	v_add_u32_e32 v96, v96, v171
	ds_write_b32 v12, v96
	v_add_u32_e32 v96, v96, v170
	ds_write_b32 v14, v96
	v_add_u32_e32 v96, v96, v172
	ds_write_b32 v16, v96
	s_waitcnt lgkmcnt(0)
	ds_read_b32 v96, v186
	v_cmp_ne_u32_e64 s[0:1], -1, v173
	s_or_b32 s70, s40, 7
	s_ashr_i32 s71, s70, 31
	v_cndmask_b32_e64 v189, 0, v185, s[0:1]
	v_cndmask_b32_e64 v188, 0, v173, s[0:1]
	s_lshl_b64 s[68:69], s[70:71], 11
	v_lshl_add_u64 v[18:19], v[18:19], 0, s[68:69]
	s_lshl_b64 s[0:1], s[70:71], 9
	s_waitcnt lgkmcnt(0)
	v_add_u32_e32 v169, v96, v37
	ds_read_b32 v37, v188
	s_waitcnt lgkmcnt(0)
	s_waitcnt lgkmcnt(0)
	v_add_u32_e32 v170, v37, v39
	v_ashrrev_i32_e32 v37, 31, v36
	v_lshl_add_u64 v[96:97], v[36:37], 3, s[28:29]
	v_ashrrev_i32_e32 v39, 31, v38
	global_load_dwordx2 v[96:97], v[96:97], off
	v_lshl_add_u64 v[128:129], v[38:39], 3, s[28:29]
	global_load_dwordx2 v[128:129], v[128:129], off
	v_lshl_add_u32 v37, v169, 2, s93
	s_waitcnt vmcnt(1)
	v_mul_f32_e32 v39, v94, v97
	ds_write2st64_b32 v37, v36, v39 offset0:36 offset1:38
	ds_write_b32 v37, v96 offset:10240
	v_lshl_add_u32 v36, v170, 2, s93
	s_waitcnt vmcnt(0)
	v_mul_f32_e32 v37, v95, v129
	ds_write2st64_b32 v36, v38, v37 offset0:36 offset1:38
	ds_write_b32 v36, v128 offset:10240
	v_mov_b32_e32 v36, v200
	v_mov_b32_e32 v37, v201
	v_mov_b32_e32 v38, v202
	v_mov_b32_e32 v39, v203
	v_mov_b32_e32 v186, v204
	v_mov_b32_e32 v187, v205
	v_mov_b32_e32 v188, v206
	v_mov_b32_e32 v189, v207
	v_lshlrev_b32_e32 v96, 16, v36
	v_lshlrev_b32_e32 v94, 16, v186
	v_and_b32_e32 v186, 0xffff0000, v186
	v_lshlrev_b32_e32 v184, 16, v187
	v_and_b32_e32 v185, 0xffff0000, v187
	v_max3_f32 v18, |v94|, 0, |v186|
	v_lshlrev_b32_e32 v95, 16, v188
	v_and_b32_e32 v175, 0xffff0000, v188
	v_max3_f32 v18, v18, |v184|, |v185|
	v_lshlrev_b32_e32 v173, 16, v189
	v_and_b32_e32 v174, 0xffff0000, v189
	v_max3_f32 v18, v18, |v95|, |v175|
	v_and_b32_e32 v170, 0xffff0000, v36
	v_max3_f32 v18, v18, |v173|, |v174|
	v_lshlrev_b32_e32 v171, 16, v37
	v_and_b32_e32 v172, 0xffff0000, v37
	v_max3_f32 v18, v18, |v96|, |v170|
	v_lshlrev_b32_e32 v97, 16, v38
	v_and_b32_e32 v169, 0xffff0000, v38
	v_max3_f32 v18, v18, |v171|, |v172|
	v_lshlrev_b32_e32 v37, 16, v39
	v_and_b32_e32 v129, 0xffff0000, v39
	v_max3_f32 v18, v18, |v97|, |v169|
	v_max3_f32 v18, v18, |v37|, |v129|
	v_lshl_or_b32 v38, v55, 2, s0
	v_mov_b32_e32 v39, s1
	v_mov_b32_dpp v19, v18 quad_perm:[1,0,3,2] row_mask:0xf bank_mask:0xf bound_ctrl:1
	v_max_f32_e32 v19, v19, v19
	v_max_f32_e32 v18, v18, v19
	v_or_b32_e32 v188, 0x100, v38
	v_mov_b32_e32 v189, s1
	v_mov_b32_dpp v19, v18 quad_perm:[2,3,0,1] row_mask:0xf bank_mask:0xf bound_ctrl:1
	v_max_f32_e32 v19, v19, v19
	v_max_f32_e32 v18, v18, v19
	v_lshl_add_u64 v[190:191], s[24:25], 0, v[188:189]
	v_mov_b32_e32 v36, v233
	v_mov_b32_dpp v19, v18 row_half_mirror row_mask:0xf bank_mask:0xf bound_ctrl:1
	v_max_f32_e32 v19, v19, v19
	v_max_f32_e32 v18, v18, v19
	v_lshl_add_u64 v[188:189], s[26:27], 0, v[188:189]
	s_nop 0
	v_mov_b32_dpp v19, v18 row_mirror row_mask:0xf bank_mask:0xf bound_ctrl:1
	v_max_f32_e32 v19, v19, v19
	v_max_f32_e32 v18, v18, v19
	s_nop 0
	v_readlane_b32 s44, v18, 0
	v_readlane_b32 s48, v18, 16
	v_readlane_b32 s95, v18, 32
	v_readlane_b32 s45, v18, 48
	v_lshl_add_u64 v[18:19], s[24:25], 0, v[38:39]
	v_mov_b32_e32 v18, v232
	v_lshl_add_u64 v[38:39], s[26:27], 0, v[38:39]
	v_mov_b32_e32 v38, v234
	s_waitcnt vmcnt(1)
	v_ashrrev_i32_e32 v19, 5, v18
	v_mov_b32_e32 v39, v235
	s_nop 0
	ds_write_b32 v20, v155
	s_waitcnt vmcnt(0)
	ds_write_b32 v22, v155
	ds_write_b32 v24, v155
	ds_write_b32 v26, v155
	ds_write_b32 v28, v155
	ds_write_b32 v30, v155
	ds_write_b32 v32, v155
	ds_write_b32 v34, v155
	v_lshl_add_u32 v20, v19, 2, s93
	v_ashrrev_i32_e32 v21, 5, v36
	ds_add_rtn_u32 v19, v20, v208 offset:12288
	v_lshl_add_u32 v21, v21, 2, s93
	ds_add_rtn_u32 v24, v21, v208 offset:12288
	s_waitcnt lgkmcnt(0)
	ds_read_b32 v26, v2
	ds_read_b32 v25, v4
	ds_read_b32 v28, v6
	ds_read_b32 v27, v8
	ds_read_b32 v30, v10
	ds_read_b32 v29, v12
	ds_read_b32 v31, v14
	ds_read_b32 v23, v16
	s_waitcnt lgkmcnt(0)
	v_add_u32_e32 v22, v25, v26
	v_add3_u32 v22, v22, v28, v27
	v_add3_u32 v22, v22, v30, v29
	v_add3_u32 v32, v22, v31, v23
	v_cvt_f32_u32_e32 v22, v32
	s_nop 1
	v_add_f32_dpp v22, v22, v22 row_shr:1 row_mask:0xf bank_mask:0xf bound_ctrl:1
	s_nop 1
	v_add_f32_dpp v22, v22, v22 row_shr:2 row_mask:0xf bank_mask:0xf bound_ctrl:1
	s_nop 1
	v_add_f32_dpp v22, v22, v22 row_shr:4 row_mask:0xf bank_mask:0xf bound_ctrl:1
	s_nop 1
	v_add_f32_dpp v33, v22, v22 row_shr:8 row_mask:0xf bank_mask:0xf bound_ctrl:1
	s_nop 0
	v_readlane_b32 s49, v33, 15
	v_readlane_b32 s53, v33, 31
	v_readlane_b32 s52, v33, 47
	s_and_saveexec_b64 s[0:1], s[14:15]
	s_xor_b64 s[0:1], exec, s[0:1]
	s_cbranch_execz .LBB0_88
	s_mov_b32 s34, s57
	s_and_saveexec_b64 s[14:15], s[12:13]
	s_xor_b64 s[12:13], exec, s[14:15]
	v_mov_b32_e32 v22, s49
	v_cndmask_b32_e32 v34, 0, v22, vcc
	s_andn2_saveexec_b64 s[12:13], s[12:13]
	v_mov_b32_e32 v22, s53
	v_add_f32_e32 v34, s49, v22
	s_or_b64 exec, exec, s[12:13]
	s_mov_b32 s56, 0xf800000
	s_mov_b32 s57, s34
.LBB0_88:
	s_andn2_saveexec_b64 s[0:1], s[0:1]
	v_mov_b32_e32 v22, s53
	v_add_f32_e32 v22, s49, v22
	v_add_f32_e32 v34, s52, v22
	s_or_b64 exec, exec, s[0:1]
	v_add_u32_e32 v35, 0x3000, v21
	v_max_f32_e64 v21, s48, s48
	v_max_f32_e64 v22, s44, s44
	v_max_f32_e32 v21, v22, v21
	v_max_f32_e64 v22, s45, s45
	v_max_f32_e64 v23, s95, s95
	v_max_f32_e32 v22, v23, v22
	s_mov_b32 s12, 0x1e3ce508
	v_max3_f32 v21, v21, v22, s12
	s_mov_b32 s13, 0x43700000
	v_div_scale_f32 v22, s[0:1], v21, v21, s13
	v_rcp_f32_e32 v23, v22
	v_readlane_b32 s0, v254, 10
	v_add_u32_e32 v20, 0x3000, v20
	v_readlane_b32 s1, v254, 11
	v_fma_f32 v55, -v22, v23, 1.0
	v_fmac_f32_e32 v23, v55, v23
	v_div_scale_f32 v55, vcc, s13, v21, s13
	v_mul_f32_e32 v128, v55, v23
	v_fma_f32 v187, -v22, v128, v55
	v_fmac_f32_e32 v128, v187, v23
	v_fma_f32 v22, -v22, v128, v55
	v_div_fmas_f32 v22, v22, v23, v128
	v_div_fixup_f32 v22, v22, v21, s13
	v_mul_f32_e32 v128, 0x3b888889, v21
	v_mul_f32_e32 v21, v22, v94
	v_mul_f32_e32 v23, v22, v186
	v_mov_b32_e32 v94, v155
	v_cvt_pk_fp8_f32 v94, v21, v23
	v_mul_f32_e32 v21, v22, v184
	v_mul_f32_e32 v23, v22, v185
	v_cmp_ne_u32_e32 vcc, -1, v20
	v_cvt_pk_fp8_f32 v94, v21, v23 op_sel:[0,0,1]
	v_mul_f32_e32 v21, v22, v95
	v_mul_f32_e32 v23, v22, v175
	v_mov_b32_e32 v95, v155
	v_cvt_pk_fp8_f32 v95, v21, v23
	v_mul_f32_e32 v21, v22, v173
	v_mul_f32_e32 v23, v22, v174
	v_max_f32_e64 v55, s60, s60
	v_cvt_pk_fp8_f32 v95, v21, v23 op_sel:[0,0,1]
	v_mul_f32_e32 v21, v22, v96
	v_mul_f32_e32 v23, v22, v170
	v_mov_b32_e32 v96, v155
	v_cvt_pk_fp8_f32 v96, v21, v23
	v_mul_f32_e32 v21, v22, v171
	v_mul_f32_e32 v23, v22, v172
	s_mov_b32 s95, 0
	v_cvt_pk_fp8_f32 v96, v21, v23 op_sel:[0,0,1]
	v_mul_f32_e32 v21, v22, v97
	v_mul_f32_e32 v23, v22, v169
	v_mov_b32_e32 v97, v155
	v_cvt_pk_fp8_f32 v97, v21, v23
	v_mul_f32_e32 v21, v22, v37
	v_mul_f32_e32 v22, v22, v129
	v_max_f32_e64 v37, s72, s72
	v_cvt_pk_fp8_f32 v97, v21, v22 op_sel:[0,0,1]
	v_mov_b32_e32 v21, s1
	v_cndmask_b32_e32 v23, 0, v21, vcc
	v_cndmask_b32_e32 v22, 0, v20, vcc
	v_cmp_ne_u32_e32 vcc, -1, v35
	s_nop 1
	v_cndmask_b32_e32 v20, 0, v35, vcc
	v_max_f32_e64 v35, s94, s94
	v_max_f32_e32 v35, v37, v35
	v_max_f32_e64 v37, s73, s73
	v_max_f32_e32 v37, v55, v37
	v_max3_f32 v35, v35, v37, s12
	v_div_scale_f32 v37, s[0:1], v35, v35, s13
	v_rcp_f32_e32 v55, v37
	v_cndmask_b32_e32 v21, 0, v21, vcc
	v_fma_f32 v129, -v37, v55, 1.0
	v_fmac_f32_e32 v55, v129, v55
	v_div_scale_f32 v129, vcc, s13, v35, s13
	v_mul_f32_e32 v169, v129, v55
	v_fma_f32 v170, -v37, v169, v129
	v_fmac_f32_e32 v169, v170, v55
	v_fma_f32 v37, -v37, v169, v129
	v_div_fmas_f32 v37, v37, v55, v169
	v_div_fixup_f32 v37, v37, v35, s13
	v_mul_f32_e32 v129, 0x3b888889, v35
	v_mul_f32_e32 v35, v37, v98
	v_mul_f32_e32 v55, v37, v168
	v_mov_b32_e32 v98, v155
	v_cvt_pk_fp8_f32 v98, v35, v55
	v_mul_f32_e32 v35, v37, v99
	v_mul_f32_e32 v55, v37, v163
	v_mov_b32_e32 v99, v155
	v_cvt_pk_fp8_f32 v98, v35, v55 op_sel:[0,0,1]
	v_mul_f32_e32 v35, v37, v164
	v_mul_f32_e32 v55, v37, v165
	v_cvt_pk_fp8_f32 v99, v35, v55
	v_mul_f32_e32 v35, v37, v166
	v_mul_f32_e32 v55, v37, v167
	v_cvt_pk_fp8_f32 v99, v35, v55 op_sel:[0,0,1]
	v_mul_f32_e32 v35, v37, v100
	v_mul_f32_e32 v55, v37, v162
	v_mov_b32_e32 v100, v155
	v_cvt_pk_fp8_f32 v100, v35, v55
	v_mul_f32_e32 v35, v37, v101
	v_mul_f32_e32 v55, v37, v136
	v_mov_b32_e32 v101, v155
	v_cvt_pk_fp8_f32 v100, v35, v55 op_sel:[0,0,1]
	v_mul_f32_e32 v35, v37, v153
	v_mul_f32_e32 v55, v37, v154
	v_cvt_pk_fp8_f32 v101, v35, v55
	v_mul_f32_e32 v35, v37, v160
	v_mul_f32_e32 v37, v37, v161
	v_max_f32_e64 v55, s17, s17
	v_cvt_pk_fp8_f32 v101, v35, v37 op_sel:[0,0,1]
	v_max_f32_e64 v35, s19, s19
	v_max_f32_e64 v37, s75, s75
	v_max_f32_e32 v35, v37, v35
	v_max_f32_e64 v37, s18, s18
	v_max_f32_e32 v37, v55, v37
	v_max3_f32 v35, v35, v37, s12
	v_div_scale_f32 v37, s[0:1], v35, v35, s13
	v_rcp_f32_e32 v55, v37
	s_nop 0
	v_fma_f32 v136, -v37, v55, 1.0
	v_fmac_f32_e32 v55, v136, v55
	v_div_scale_f32 v136, vcc, s13, v35, s13
	v_mul_f32_e32 v153, v136, v55
	v_fma_f32 v154, -v37, v153, v136
	v_fmac_f32_e32 v153, v154, v55
	v_fma_f32 v37, -v37, v153, v136
	v_div_fmas_f32 v37, v37, v55, v153
	v_div_fixup_f32 v37, v37, v35, s13
	v_mul_f32_e32 v136, 0x3b888889, v35
	v_mul_f32_e32 v35, v37, v102
	v_mul_f32_e32 v55, v37, v152
	v_mov_b32_e32 v102, v155
	v_cvt_pk_fp8_f32 v102, v35, v55
	v_mul_f32_e32 v35, v37, v103
	v_mul_f32_e32 v55, v37, v147
	v_mov_b32_e32 v103, v155
	v_cvt_pk_fp8_f32 v102, v35, v55 op_sel:[0,0,1]
	v_mul_f32_e32 v35, v37, v148
	v_mul_f32_e32 v55, v37, v149
	v_cvt_pk_fp8_f32 v103, v35, v55
	v_mul_f32_e32 v35, v37, v150
	v_mul_f32_e32 v55, v37, v151
	v_cvt_pk_fp8_f32 v103, v35, v55 op_sel:[0,0,1]
	v_mul_f32_e32 v35, v37, v104
	v_mul_f32_e32 v55, v37, v146
	v_mov_b32_e32 v104, v155
	v_cvt_pk_fp8_f32 v104, v35, v55
	v_mul_f32_e32 v35, v37, v105
	v_mul_f32_e32 v55, v37, v137
	v_mov_b32_e32 v105, v155
	v_cvt_pk_fp8_f32 v104, v35, v55 op_sel:[0,0,1]
	v_mul_f32_e32 v35, v37, v142
	v_mul_f32_e32 v55, v37, v143
	v_cvt_pk_fp8_f32 v105, v35, v55
	v_mul_f32_e32 v35, v37, v144
	v_mul_f32_e32 v37, v37, v145
	v_max_f32_e64 v55, s31, s31
	v_cvt_pk_fp8_f32 v105, v35, v37 op_sel:[0,0,1]
	v_max_f32_e64 v35, s16, s16
	v_max_f32_e64 v37, s10, s10
	v_max_f32_e32 v35, v37, v35
	v_max_f32_e64 v37, s11, s11
	v_max_f32_e32 v37, v55, v37
	v_max3_f32 v35, v35, v37, s12
	v_div_scale_f32 v37, s[0:1], v35, v35, s13
	v_rcp_f32_e32 v55, v37
	s_bfe_i32 s10, s96, 0x10000
	v_fma_f32 v137, -v37, v55, 1.0
	v_fmac_f32_e32 v55, v137, v55
	v_div_scale_f32 v137, vcc, s13, v35, s13
	v_mul_f32_e32 v142, v137, v55
	v_fma_f32 v143, -v37, v142, v137
	v_fmac_f32_e32 v142, v143, v55
	v_fma_f32 v37, -v37, v142, v137
	v_div_fmas_f32 v37, v37, v55, v142
	v_div_fixup_f32 v37, v37, v35, s13
	v_mul_f32_e32 v137, 0x3b888889, v35
	v_mul_f32_e32 v35, v37, v106
	v_mul_f32_e32 v55, v37, v141
	v_mov_b32_e32 v106, v155
	v_cvt_pk_fp8_f32 v106, v35, v55
	v_mul_f32_e32 v35, v37, v107
	v_mul_f32_e32 v55, v37, v126
	v_mov_b32_e32 v107, v155
	v_cvt_pk_fp8_f32 v106, v35, v55 op_sel:[0,0,1]
	v_mul_f32_e32 v35, v37, v127
	v_mul_f32_e32 v55, v37, v138
	v_cvt_pk_fp8_f32 v107, v35, v55
	v_mul_f32_e32 v35, v37, v139
	v_mul_f32_e32 v55, v37, v140
	v_cvt_pk_fp8_f32 v107, v35, v55 op_sel:[0,0,1]
	v_mul_f32_e32 v35, v37, v108
	v_mul_f32_e32 v55, v37, v125
	v_mov_b32_e32 v108, v155
	v_cvt_pk_fp8_f32 v108, v35, v55
	v_mul_f32_e32 v35, v37, v109
	v_mul_f32_e32 v55, v37, v120
	v_mov_b32_e32 v109, v155
	v_cvt_pk_fp8_f32 v108, v35, v55 op_sel:[0,0,1]
	v_mul_f32_e32 v35, v37, v121
	v_mul_f32_e32 v55, v37, v122
	v_cvt_pk_fp8_f32 v109, v35, v55
	v_mul_f32_e32 v35, v37, v123
	v_mul_f32_e32 v37, v37, v124
	v_max_f32_e64 v55, s97, s97
	v_cvt_pk_fp8_f32 v109, v35, v37 op_sel:[0,0,1]
	v_max_f32_e64 v35, s30, s30
	v_max_f32_e64 v37, s20, s20
	v_max_f32_e32 v35, v37, v35
	v_max_f32_e64 v37, s21, s21
	v_max_f32_e32 v37, v55, v37
	v_max3_f32 v35, v35, v37, s12
	v_div_scale_f32 v37, s[0:1], v35, v35, s13
	v_rcp_f32_e32 v55, v37
	v_mul_f32_e32 v138, 0x3b888889, v35
	v_mov_b32_e32 v123, v155
	v_mov_b32_e32 v124, v155
	v_fma_f32 v120, -v37, v55, 1.0
	v_fmac_f32_e32 v55, v120, v55
	v_div_scale_f32 v120, vcc, s13, v35, s13
	v_mul_f32_e32 v121, v120, v55
	v_fma_f32 v122, -v37, v121, v120
	v_fmac_f32_e32 v121, v122, v55
	v_fma_f32 v37, -v37, v121, v120
	v_div_fmas_f32 v37, v37, v55, v121
	v_div_fixup_f32 v37, v37, v35, s13
	v_mul_f32_e32 v35, v37, v110
	v_mul_f32_e32 v55, v37, v119
	v_mov_b32_e32 v110, v155
	v_cvt_pk_fp8_f32 v110, v35, v55
	v_mul_f32_e32 v35, v37, v111
	v_mul_f32_e32 v55, v37, v114
	v_mov_b32_e32 v111, v155
	v_cvt_pk_fp8_f32 v110, v35, v55 op_sel:[0,0,1]
	v_mul_f32_e32 v35, v37, v115
	v_mul_f32_e32 v55, v37, v116
	v_cvt_pk_fp8_f32 v111, v35, v55
	v_mul_f32_e32 v35, v37, v117
	v_mul_f32_e32 v55, v37, v118
	v_mov_b32_e32 v114, v155
	v_cvt_pk_fp8_f32 v111, v35, v55 op_sel:[0,0,1]
	v_mul_f32_e32 v35, v37, v112
	v_mul_f32_e32 v55, v37, v113
	v_mov_b32_e32 v112, v155
	v_cvt_pk_fp8_f32 v112, v35, v55
	v_mul_f32_e32 v35, v37, v88
	v_mul_f32_e32 v55, v37, v89
	v_mov_b32_e32 v113, v155
	v_cvt_pk_fp8_f32 v112, v35, v55 op_sel:[0,0,1]
	v_mul_f32_e32 v35, v37, v90
	v_mul_f32_e32 v55, v37, v91
	v_cvt_pk_fp8_f32 v113, v35, v55
	v_mul_f32_e32 v35, v37, v92
	v_mul_f32_e32 v37, v37, v93
	v_max_f32_e64 v55, s90, s90
	v_cvt_pk_fp8_f32 v113, v35, v37 op_sel:[0,0,1]
	v_max_f32_e64 v35, s92, s92
	v_max_f32_e64 v37, s74, s74
	v_max_f32_e32 v35, v37, v35
	v_max_f32_e64 v37, s91, s91
	v_max_f32_e32 v37, v55, v37
	v_max3_f32 v35, v35, v37, s12
	v_div_scale_f32 v37, s[0:1], v35, v35, s13
	v_rcp_f32_e32 v55, v37
	v_mul_f32_e32 v139, 0x3b888889, v35
	v_mov_b32_e32 v115, v155
	v_mov_b32_e32 v116, v155
	v_fma_f32 v88, -v37, v55, 1.0
	v_fmac_f32_e32 v55, v88, v55
	v_div_scale_f32 v88, vcc, s13, v35, s13
	v_mul_f32_e32 v89, v88, v55
	v_fma_f32 v90, -v37, v89, v88
	v_fmac_f32_e32 v89, v90, v55
	v_fma_f32 v37, -v37, v89, v88
	v_div_fmas_f32 v37, v37, v55, v89
	v_div_fixup_f32 v37, v37, v35, s13
	v_mul_f32_e32 v35, v37, v80
	v_mul_f32_e32 v55, v37, v81
	v_cvt_pk_fp8_f32 v114, v35, v55
	v_mul_f32_e32 v35, v37, v82
	v_mul_f32_e32 v55, v37, v83
	v_mov_b32_e32 v117, v155
	v_cvt_pk_fp8_f32 v114, v35, v55 op_sel:[0,0,1]
	v_mul_f32_e32 v35, v37, v84
	v_mul_f32_e32 v55, v37, v85
	v_cvt_pk_fp8_f32 v115, v35, v55
	v_mul_f32_e32 v35, v37, v86
	v_mul_f32_e32 v55, v37, v87
	v_readlane_b32 s0, v254, 44
	v_cvt_pk_fp8_f32 v115, v35, v55 op_sel:[0,0,1]
	v_mul_f32_e32 v35, v37, v72
	v_mul_f32_e32 v55, v37, v73
	v_cvt_pk_fp8_f32 v116, v35, v55
	v_mul_f32_e32 v35, v37, v74
	v_mul_f32_e32 v55, v37, v75
	v_mov_b32_e32 v118, v155
	v_cvt_pk_fp8_f32 v116, v35, v55 op_sel:[0,0,1]
	v_mul_f32_e32 v35, v37, v76
	v_mul_f32_e32 v55, v37, v77
	v_cvt_pk_fp8_f32 v117, v35, v55
	v_mul_f32_e32 v35, v37, v78
	v_mul_f32_e32 v37, v37, v79
	v_max_f32_e64 v55, s0, s0
	v_cvt_pk_fp8_f32 v117, v35, v37 op_sel:[0,0,1]
	v_max_f32_e64 v35, s37, s37
	v_max_f32_e64 v37, s35, s35
	v_max_f32_e32 v35, v37, v35
	v_max_f32_e64 v37, s36, s36
	v_max_f32_e32 v37, v55, v37
	v_max3_f32 v35, v35, v37, s12
	v_div_scale_f32 v37, s[0:1], v35, v35, s13
	v_rcp_f32_e32 v55, v37
	v_mul_f32_e32 v140, 0x3b888889, v35
	v_mov_b32_e32 v119, v155
	v_mov_b32_e32 v120, v155
	v_fma_f32 v72, -v37, v55, 1.0
	v_fmac_f32_e32 v55, v72, v55
	v_div_scale_f32 v72, vcc, s13, v35, s13
	v_mul_f32_e32 v73, v72, v55
	v_fma_f32 v74, -v37, v73, v72
	v_fmac_f32_e32 v73, v74, v55
	v_fma_f32 v37, -v37, v73, v72
	v_div_fmas_f32 v37, v37, v55, v73
	v_div_fixup_f32 v37, v37, v35, s13
	v_mul_f32_e32 v35, v37, v64
	v_mul_f32_e32 v55, v37, v65
	v_cvt_pk_fp8_f32 v118, v35, v55
	v_mul_f32_e32 v35, v37, v66
	v_mul_f32_e32 v55, v37, v67
	v_mov_b32_e32 v121, v155
	v_cvt_pk_fp8_f32 v118, v35, v55 op_sel:[0,0,1]
	v_mul_f32_e32 v35, v37, v68
	v_mul_f32_e32 v55, v37, v69
	v_cvt_pk_fp8_f32 v119, v35, v55
	v_mul_f32_e32 v35, v37, v70
	v_mul_f32_e32 v55, v37, v71
	v_readlane_b32 s0, v254, 42
	v_cvt_pk_fp8_f32 v119, v35, v55 op_sel:[0,0,1]
	v_mul_f32_e32 v35, v37, v56
	v_mul_f32_e32 v55, v37, v57
	v_cvt_pk_fp8_f32 v120, v35, v55
	v_mul_f32_e32 v35, v37, v58
	v_mul_f32_e32 v55, v37, v59
	v_mov_b32_e32 v122, v155
	v_cvt_pk_fp8_f32 v120, v35, v55 op_sel:[0,0,1]
	v_mul_f32_e32 v35, v37, v60
	v_mul_f32_e32 v55, v37, v61
	v_cvt_pk_fp8_f32 v121, v35, v55
	v_mul_f32_e32 v35, v37, v62
	v_mul_f32_e32 v37, v37, v63
	v_mov_b32_e32 v125, v155
	v_cvt_pk_fp8_f32 v121, v35, v37 op_sel:[0,0,1]
	v_max_f32_e64 v35, s0, s0
	v_readlane_b32 s0, v254, 38
	s_mov_b32 s36, 30
	s_nop 0
	v_max_f32_e64 v37, s0, s0
	v_readlane_b32 s0, v254, 40
	v_max_f32_e32 v35, v37, v35
	s_nop 0
	v_max_f32_e64 v37, s0, s0
	v_readlane_b32 s0, v254, 36
	s_nop 1
	v_max_f32_e64 v55, s0, s0
	v_max_f32_e32 v37, v55, v37
	v_max3_f32 v35, v35, v37, s12
	v_div_scale_f32 v37, s[0:1], v35, v35, s13
	v_rcp_f32_e32 v55, v37
	v_mul_f32_e32 v141, 0x3b888889, v35
	s_and_b32 s0, s96, 1
	s_cmp_eq_u32 s0, 0
	v_fma_f32 v56, -v37, v55, 1.0
	v_fmac_f32_e32 v55, v56, v55
	v_div_scale_f32 v56, vcc, s13, v35, s13
	v_mul_f32_e32 v57, v56, v55
	v_fma_f32 v58, -v37, v57, v56
	v_fmac_f32_e32 v57, v58, v55
	v_fma_f32 v37, -v37, v57, v56
	v_div_fmas_f32 v37, v37, v55, v57
	v_div_fixup_f32 v37, v37, v35, s13
	v_mul_f32_e32 v35, v37, v47
	v_mul_f32_e32 v47, v37, v48
	v_cvt_pk_fp8_f32 v122, v35, v47
	v_mul_f32_e32 v35, v37, v49
	v_mul_f32_e32 v47, v37, v50
	v_mul_f32_e32 v1, v37, v1
	v_cvt_pk_fp8_f32 v122, v35, v47 op_sel:[0,0,1]
	v_mul_f32_e32 v35, v37, v51
	v_mul_f32_e32 v47, v37, v52
	v_cvt_pk_fp8_f32 v123, v35, v47
	v_mul_f32_e32 v35, v37, v53
	v_mul_f32_e32 v47, v37, v54
	s_cselect_b64 s[0:1], -1, 0
	v_cvt_pk_fp8_f32 v123, v35, v47 op_sel:[0,0,1]
	v_mul_f32_e32 v35, v37, v40
	v_cvt_pk_fp8_f32 v124, v1, v35
	v_mul_f32_e32 v1, v37, v41
	v_mul_f32_e32 v35, v37, v42
	s_and_b32 s34, s10, 31
	v_cvt_pk_fp8_f32 v124, v1, v35 op_sel:[0,0,1]
	v_mul_f32_e32 v1, v37, v43
	v_mul_f32_e32 v35, v37, v44
	v_cvt_pk_fp8_f32 v125, v1, v35
	v_mul_f32_e32 v1, v37, v45
	v_mul_f32_e32 v35, v37, v46
	v_ashrrev_i32_e32 v37, 31, v36
	v_cvt_pk_fp8_f32 v125, v1, v35 op_sel:[0,0,1]
	v_add_f32_e32 v1, v33, v34
	v_cvt_u32_f32_e32 v1, v1
	s_lshl_b32 s35, s34, 4
	s_add_i32 s10, s93, s35
	v_mov_b32_e32 v62, s10
	v_sub_u32_e32 v1, v1, v32
	ds_write_b32 v2, v1
	v_add_u32_e32 v1, v1, v26
	ds_write_b32 v4, v1
	v_add_u32_e32 v1, v1, v25
	ds_write_b32 v6, v1
	v_add_u32_e32 v1, v1, v28
	ds_write_b32 v8, v1
	v_add_u32_e32 v1, v1, v27
	ds_write_b32 v10, v1
	v_add_u32_e32 v1, v1, v30
	ds_write_b32 v12, v1
	v_add_u32_e32 v1, v1, v29
	ds_write_b32 v14, v1
	v_add_u32_e32 v1, v1, v31
	ds_write_b32 v16, v1
	s_waitcnt lgkmcnt(0)
	ds_read_b32 v1, v22
	ds_read_b32 v2, v20
	s_waitcnt lgkmcnt(0)
	v_lshl_add_u64 v[4:5], v[36:37], 3, s[28:29]
	global_load_dwordx2 v[4:5], v[4:5], off
	s_waitcnt lgkmcnt(0)
	v_add_u32_e32 v1, v1, v19
	v_ashrrev_i32_e32 v19, 31, v18
	v_add_u32_e32 v6, v2, v24
	v_lshl_add_u64 v[2:3], v[18:19], 3, s[28:29]
	global_load_dwordx2 v[2:3], v[2:3], off
	v_lshl_add_u32 v1, v1, 2, s93
	s_waitcnt vmcnt(0)
	v_mul_f32_e32 v3, v38, v3
	ds_write2st64_b32 v1, v18, v3 offset0:42 offset1:44
	ds_write_b32 v1, v2 offset:11776
	v_lshl_add_u32 v1, v6, 2, s93
	v_mul_f32_e32 v2, v39, v5
	ds_write2st64_b32 v1, v36, v2 offset0:42 offset1:44
	ds_write_b32 v1, v4 offset:11776
	s_waitcnt lgkmcnt(0)
	v_readfirstlane_b32 s98, v130
	v_readfirstlane_b32 s99, v131
	v_lshlrev_b32_e32 v92, 4, v176
	s_mov_b32 s95, 0
	s_cmp_lg_u64 s[0:1], 0
	s_cselect_b32 s34, 0, 31
	s_lshl_b32 s36, s34, 4
	v_add_u32_e32 v89, s36, v181
	s_add_i32 s10, s93, s36
	v_mov_b32_e32 v91, s10
	ds_read_b128 v[66:69], v91 offset:0
	ds_read_b128 v[70:73], v91 offset:1536
	ds_read_b128 v[74:77], v91 offset:3072
	ds_read_b128 v[78:81], v91 offset:4608
	s_waitcnt lgkmcnt(3)
	v_lshl_add_u32 v145, v66, 10, v92
	global_load_dwordx4 v[2:5], v145, s[98:99]
	v_lshl_add_u32 v147, v67, 10, v92
	global_load_dwordx4 v[6:9], v147, s[98:99]
	v_lshl_add_u32 v145, v68, 10, v92
	global_load_dwordx4 v[10:13], v145, s[98:99]
	v_lshl_add_u32 v147, v69, 10, v92
	global_load_dwordx4 v[14:17], v147, s[98:99]
	ds_read_b32 v82, v89 offset:1024
	s_waitcnt lgkmcnt(3)
	v_lshl_add_u32 v145, v70, 10, v92
	global_load_dwordx4 v[18:21], v145, s[98:99]
	v_lshl_add_u32 v147, v71, 10, v92
	global_load_dwordx4 v[22:25], v147, s[98:99]
	v_lshl_add_u32 v145, v72, 10, v92
	global_load_dwordx4 v[26:29], v145, s[98:99]
	v_lshl_add_u32 v147, v73, 10, v92
	global_load_dwordx4 v[30:33], v147, s[98:99]
	ds_read_b32 v83, v89 offset:2560
	s_waitcnt lgkmcnt(3)
	v_lshl_add_u32 v145, v74, 10, v92
	global_load_dwordx4 v[34:37], v145, s[98:99]
	v_lshl_add_u32 v147, v75, 10, v92
	global_load_dwordx4 v[38:41], v147, s[98:99]
	v_lshl_add_u32 v145, v76, 10, v92
	global_load_dwordx4 v[42:45], v145, s[98:99]
	v_lshl_add_u32 v147, v77, 10, v92
	global_load_dwordx4 v[46:49], v147, s[98:99]
	ds_read_b32 v84, v89 offset:4096
	s_waitcnt lgkmcnt(3)
	v_lshl_add_u32 v145, v78, 10, v92
	global_load_dwordx4 v[50:53], v145, s[98:99]
	v_lshl_add_u32 v147, v79, 10, v92
	global_load_dwordx4 v[54:57], v147, s[98:99]
	v_lshl_add_u32 v145, v80, 10, v92
	global_load_dwordx4 v[58:61], v145, s[98:99]
	v_lshl_add_u32 v147, v81, 10, v92
	global_load_dwordx4 v[62:65], v147, s[98:99]
	ds_read_b32 v85, v89 offset:5632
	ds_read_b128 v[66:69], v91 offset:6144
	ds_read_b128 v[70:73], v91 offset:7680
	ds_read_b128 v[74:77], v91 offset:9216
	ds_read_b128 v[78:81], v91 offset:10752
	s_add_i32 s10, s34, 1
	s_min_u32 s10, s10, 31
	s_sub_i32 s11, s34, 1
	s_max_i32 s11, s11, 0
	s_cmp_lg_u64 s[0:1], 0
	s_cselect_b32 s35, s10, s11
	s_lshl_b32 s36, s35, 4
	v_add_u32_e32 v90, s36, v181
	s_add_i32 s10, s93, s36
	s_waitcnt vmcnt(12) lgkmcnt(0)
	v_mov_b32_e32 v91, s10
	v_mul_f32_e32 v88, v141, v82
	v_mfma_f32_16x16x32_fp8_fp8 v[184:187], v[2:3], v[122:123], 0
	v_mfma_f32_16x16x32_fp8_fp8 v[188:191], v[6:7], v[122:123], 0
	v_mfma_f32_16x16x32_fp8_fp8 v[192:195], v[10:11], v[122:123], 0
	v_mfma_f32_16x16x32_fp8_fp8 v[196:199], v[14:15], v[122:123], 0
	v_mfma_f32_16x16x32_fp8_fp8 v[184:187], v[4:5], v[124:125], v[184:187]
	v_mfma_f32_16x16x32_fp8_fp8 v[188:191], v[8:9], v[124:125], v[188:191]
	v_mfma_f32_16x16x32_fp8_fp8 v[192:195], v[12:13], v[124:125], v[192:195]
	v_mfma_f32_16x16x32_fp8_fp8 v[196:199], v[16:17], v[124:125], v[196:199]
	v_lshl_add_u32 v145, v66, 10, v92
	global_load_dwordx4 v[2:5], v145, s[98:99]
	v_lshl_add_u32 v147, v67, 10, v92
	global_load_dwordx4 v[6:9], v147, s[98:99]
	v_lshl_add_u32 v145, v68, 10, v92
	global_load_dwordx4 v[10:13], v145, s[98:99]
	v_lshl_add_u32 v147, v69, 10, v92
	global_load_dwordx4 v[14:17], v147, s[98:99]
	ds_read_b32 v82, v89 offset:7168
	ds_read_b128 v[66:69], v91 offset:0

.LBB0_110:
	v_bfe_u32 v154, v160, v182, 8
	s_waitcnt lgkmcnt(7)
	v_mov_b32_e32 v196, v137
	v_mov_b32_e32 v198, v136
	v_lshlrev_b64 v[136:137], v132, v[154:155]
	s_barrier
	s_add_i32 s14, s14, 2
	s_waitcnt vmcnt(11)
	v_mfma_f32_16x16x32_fp8_fp8 v[122:125], v[136:137], v[42:43], v[122:125]
	v_lshlrev_b32_e32 v42, 10, v198
	v_and_b32_e32 v154, 0x3fffc00, v42
	v_lshl_add_u64 v[42:43], v[140:141], 0, v[154:155]
	v_mfma_f32_16x16x32_fp8_fp8 v[126:129], v[136:137], v[44:45], v[126:129]
	global_load_dwordx4 v[42:45], v[42:43], off
	s_min_u32 s15, s14, 27
	s_add_i32 s18, s15, 4
	s_sub_i32 s15, 27, s15
	s_and_b64 s[16:17], s[12:13], exec
	s_cselect_b32 s15, s15, s18
	s_waitcnt lgkmcnt(4)
	v_mov_b32_e32 v184, v167
	v_lshl_add_u32 v167, s15, 4, v183
	ds_read_b32 v136, v167 offset:512
	s_waitcnt lgkmcnt(1)
	v_mov_b32_e32 v1, v175
	v_mov_b32_e32 v185, v174
	v_mov_b32_e32 v186, v166
	v_mov_b32_e32 v187, v173
	v_mov_b32_e32 v188, v165
	v_mov_b32_e32 v189, v172
	v_mov_b32_e32 v190, v164
	v_mov_b32_e32 v191, v171
	v_mov_b32_e32 v192, v163
	v_mov_b32_e32 v193, v170
	v_mov_b32_e32 v194, v162
	v_mov_b32_e32 v195, v169
	v_mov_b32_e32 v197, v168
	v_bfe_u32 v154, v161, v182, 8
	v_lshlrev_b64 v[160:161], v132, v[154:155]
	ds_read_b32 v137, v167 offset:2048
	s_waitcnt vmcnt(11)
	v_mfma_f32_16x16x32_fp8_fp8 v[114:117], v[160:161], v[46:47], v[114:117]
	v_lshlrev_b32_e32 v46, 10, v196
	v_and_b32_e32 v154, 0x3fffc00, v46
	v_lshl_add_u64 v[46:47], v[140:141], 0, v[154:155]
	v_mfma_f32_16x16x32_fp8_fp8 v[118:121], v[160:161], v[48:49], v[118:121]
	global_load_dwordx4 v[46:49], v[46:47], off
	v_bfe_u32 v154, v152, v182, 8
	v_lshlrev_b64 v[160:161], v132, v[154:155]
	ds_read_b32 v162, v167 offset:3584
	s_waitcnt vmcnt(11)
	v_mfma_f32_16x16x32_fp8_fp8 v[82:85], v[160:161], v[50:51], v[82:85]
	v_lshlrev_b32_e32 v50, 10, v194
	v_and_b32_e32 v154, 0x3fffc00, v50
	v_lshl_add_u64 v[50:51], v[140:141], 0, v[154:155]
	v_mfma_f32_16x16x32_fp8_fp8 v[86:89], v[160:161], v[52:53], v[86:89]
	global_load_dwordx4 v[50:53], v[50:51], off
	v_bfe_u32 v154, v153, v182, 8
	v_lshlrev_b64 v[152:153], v132, v[154:155]
	ds_read_b32 v163, v167 offset:5120
	s_waitcnt vmcnt(11)
	v_mfma_f32_16x16x32_fp8_fp8 v[34:37], v[152:153], v[54:55], v[34:37]
	v_lshlrev_b32_e32 v54, 10, v192
	v_and_b32_e32 v154, 0x3fffc00, v54
	v_lshl_add_u64 v[54:55], v[140:141], 0, v[154:155]
	v_mfma_f32_16x16x32_fp8_fp8 v[38:41], v[152:153], v[56:57], v[38:41]
	global_load_dwordx4 v[54:57], v[54:55], off
	v_bfe_u32 v154, v150, v182, 8
	v_lshlrev_b64 v[152:153], v132, v[154:155]
	ds_read_b32 v164, v167 offset:6656
	s_waitcnt vmcnt(11)
	v_mfma_f32_16x16x32_fp8_fp8 v[26:29], v[152:153], v[58:59], v[26:29]
	v_lshlrev_b32_e32 v58, 10, v190
	v_and_b32_e32 v154, 0x3fffc00, v58
	v_lshl_add_u64 v[58:59], v[140:141], 0, v[154:155]
	v_mfma_f32_16x16x32_fp8_fp8 v[30:33], v[152:153], v[60:61], v[30:33]
	global_load_dwordx4 v[58:61], v[58:59], off
	v_bfe_u32 v154, v151, v182, 8
	v_lshlrev_b64 v[150:151], v132, v[154:155]
	ds_read_b32 v165, v167 offset:8192
	s_waitcnt vmcnt(11)
	v_mfma_f32_16x16x32_fp8_fp8 v[18:21], v[150:151], v[62:63], v[18:21]
	v_lshlrev_b32_e32 v62, 10, v188
	v_and_b32_e32 v154, 0x3fffc00, v62
	v_lshl_add_u64 v[62:63], v[140:141], 0, v[154:155]
	v_mfma_f32_16x16x32_fp8_fp8 v[22:25], v[150:151], v[64:65], v[22:25]
	global_load_dwordx4 v[62:65], v[62:63], off
	v_bfe_u32 v154, v148, v182, 8
	v_lshlrev_b64 v[150:151], v132, v[154:155]
	ds_read_b32 v166, v167 offset:9728
	s_waitcnt vmcnt(11)
	v_mfma_f32_16x16x32_fp8_fp8 v[10:13], v[150:151], v[66:67], v[10:13]
	v_lshlrev_b32_e32 v66, 10, v186
	v_and_b32_e32 v154, 0x3fffc00, v66
	v_lshl_add_u64 v[66:67], v[140:141], 0, v[154:155]
	v_mfma_f32_16x16x32_fp8_fp8 v[14:17], v[150:151], v[68:69], v[14:17]
	global_load_dwordx4 v[66:69], v[66:67], off
	v_bfe_u32 v154, v149, v182, 8
	v_lshlrev_b64 v[148:149], v132, v[154:155]
	ds_read_b32 v167, v167 offset:11264
	s_waitcnt vmcnt(11)
	v_mfma_f32_16x16x32_fp8_fp8 v[2:5], v[148:149], v[70:71], v[2:5]
	v_lshlrev_b32_e32 v70, 10, v184
	v_and_b32_e32 v154, 0x3fffc00, v70
	v_lshl_add_u64 v[70:71], v[140:141], 0, v[154:155]
	v_mfma_f32_16x16x32_fp8_fp8 v[6:9], v[148:149], v[72:73], v[6:9]
	global_load_dwordx4 v[70:73], v[70:71], off
	v_bfe_u32 v154, v146, v182, 8
	v_lshlrev_b64 v[148:149], v132, v[154:155]
	s_min_u32 s15, s14, 26
	s_add_i32 s18, s15, 5
	s_sub_i32 s15, 26, s15
	s_and_b64 s[16:17], s[12:13], exec
	s_waitcnt vmcnt(11)
	v_mfma_f32_16x16x32_fp8_fp8 v[122:125], v[148:149], v[74:75], v[122:125]
	v_lshlrev_b32_e32 v74, 10, v197
	v_and_b32_e32 v154, 0x3fffc00, v74
	v_lshl_add_u64 v[74:75], v[140:141], 0, v[154:155]
	v_mfma_f32_16x16x32_fp8_fp8 v[126:129], v[148:149], v[76:77], v[126:129]
	global_load_dwordx4 v[74:77], v[74:75], off
	s_cselect_b32 s15, s15, s18
	v_lshl_add_u32 v148, s15, 4, v183
	ds_read_b32 v168, v148 offset:512
	v_bfe_u32 v154, v147, v182, 8
	v_lshlrev_b64 v[146:147], v132, v[154:155]
	ds_read_b32 v169, v148 offset:2048
	s_waitcnt vmcnt(11)
	v_mfma_f32_16x16x32_fp8_fp8 v[114:117], v[146:147], v[78:79], v[114:117]
	v_lshlrev_b32_e32 v78, 10, v195
	v_and_b32_e32 v154, 0x3fffc00, v78
	v_lshl_add_u64 v[78:79], v[140:141], 0, v[154:155]
	v_mfma_f32_16x16x32_fp8_fp8 v[118:121], v[146:147], v[80:81], v[118:121]
	global_load_dwordx4 v[78:81], v[78:79], off
	v_bfe_u32 v154, v144, v182, 8
	v_lshlrev_b64 v[146:147], v132, v[154:155]
	ds_read_b32 v170, v148 offset:3584
	s_waitcnt vmcnt(11)
	v_mfma_f32_16x16x32_fp8_fp8 v[82:85], v[146:147], v[90:91], v[82:85]
	v_lshlrev_b32_e32 v90, 10, v193
	v_and_b32_e32 v154, 0x3fffc00, v90
	v_lshl_add_u64 v[90:91], v[140:141], 0, v[154:155]
	v_mfma_f32_16x16x32_fp8_fp8 v[86:89], v[146:147], v[92:93], v[86:89]
	global_load_dwordx4 v[90:93], v[90:91], off
	v_bfe_u32 v154, v145, v182, 8
	v_lshlrev_b64 v[144:145], v132, v[154:155]
	ds_read_b32 v171, v148 offset:5120
	s_waitcnt vmcnt(11)
	v_mfma_f32_16x16x32_fp8_fp8 v[34:37], v[144:145], v[94:95], v[34:37]
	v_lshlrev_b32_e32 v94, 10, v191
	v_and_b32_e32 v154, 0x3fffc00, v94
	v_lshl_add_u64 v[94:95], v[140:141], 0, v[154:155]
	v_mfma_f32_16x16x32_fp8_fp8 v[38:41], v[144:145], v[96:97], v[38:41]
	global_load_dwordx4 v[94:97], v[94:95], off
	v_bfe_u32 v154, v142, v182, 8
	v_lshlrev_b64 v[144:145], v132, v[154:155]
	ds_read_b32 v172, v148 offset:6656
	s_waitcnt vmcnt(11)
	v_mfma_f32_16x16x32_fp8_fp8 v[26:29], v[144:145], v[98:99], v[26:29]
	v_lshlrev_b32_e32 v98, 10, v189
	v_and_b32_e32 v154, 0x3fffc00, v98
	v_lshl_add_u64 v[98:99], v[140:141], 0, v[154:155]
	v_mfma_f32_16x16x32_fp8_fp8 v[30:33], v[144:145], v[100:101], v[30:33]
	global_load_dwordx4 v[98:101], v[98:99], off
	v_bfe_u32 v154, v143, v182, 8
	v_lshlrev_b64 v[142:143], v132, v[154:155]
	ds_read_b32 v173, v148 offset:8192
	s_waitcnt vmcnt(11)
	v_mfma_f32_16x16x32_fp8_fp8 v[18:21], v[142:143], v[102:103], v[18:21]
	v_lshlrev_b32_e32 v102, 10, v187
	v_and_b32_e32 v154, 0x3fffc00, v102
	v_lshl_add_u64 v[102:103], v[140:141], 0, v[154:155]
	v_mfma_f32_16x16x32_fp8_fp8 v[22:25], v[142:143], v[104:105], v[22:25]
	global_load_dwordx4 v[102:105], v[102:103], off
	v_bfe_u32 v154, v138, v182, 8
	v_lshlrev_b64 v[142:143], v132, v[154:155]
	ds_read_b32 v174, v148 offset:9728
	s_waitcnt vmcnt(11)
	v_mfma_f32_16x16x32_fp8_fp8 v[10:13], v[142:143], v[106:107], v[10:13]
	v_lshlrev_b32_e32 v106, 10, v185
	v_and_b32_e32 v154, 0x3fffc00, v106
	v_lshl_add_u64 v[106:107], v[140:141], 0, v[154:155]
	v_mfma_f32_16x16x32_fp8_fp8 v[14:17], v[142:143], v[108:109], v[14:17]
	global_load_dwordx4 v[106:109], v[106:107], off
	v_bfe_u32 v154, v139, v182, 8
	v_lshlrev_b64 v[138:139], v132, v[154:155]
	ds_read_b32 v175, v148 offset:11264
	s_waitcnt vmcnt(11)
	v_mfma_f32_16x16x32_fp8_fp8 v[2:5], v[138:139], v[110:111], v[2:5]
	v_lshlrev_b32_e32 v110, 10, v1
	v_and_b32_e32 v154, 0x3fffc00, v110
	v_lshl_add_u64 v[110:111], v[140:141], 0, v[154:155]
	v_mfma_f32_16x16x32_fp8_fp8 v[6:9], v[138:139], v[112:113], v[6:9]
	global_load_dwordx4 v[110:113], v[110:111], off
	s_cmp_gt_u32 s14, 29
	v_mov_b32_e32 v160, v198
	v_mov_b32_e32 v146, v197
	v_mov_b32_e32 v161, v196
	v_mov_b32_e32 v147, v195
	v_mov_b32_e32 v152, v194
	v_mov_b32_e32 v144, v193
	v_mov_b32_e32 v153, v192
	v_mov_b32_e32 v145, v191
	v_mov_b32_e32 v150, v190
	v_mov_b32_e32 v142, v189
	v_mov_b32_e32 v151, v188
	v_mov_b32_e32 v143, v187
	v_mov_b32_e32 v148, v186
	v_mov_b32_e32 v138, v185
	v_mov_b32_e32 v149, v184
	v_mov_b32_e32 v139, v1
	s_cbranch_scc0 .LBB0_110
	v_mov_b32_e32 v1, v176
	s_add_i32 s10, s10, 1
	s_waitcnt vmcnt(15)
	v_lshlrev_b32_e32 v42, 4, v1
	v_ashrrev_i32_e32 v43, 2, v1
	v_and_b32_e32 v42, 0xf0, v42
	v_and_b32_e32 v43, -8, v43
	v_add_u32_e32 v42, v42, v43
	v_lshrrev_b32_e32 v1, 2, v1
	s_waitcnt vmcnt(14)
	v_and_or_b32 v46, v1, 4, v42
	v_ashrrev_i32_e32 v47, 31, v46
	v_lshl_add_u64 v[42:43], v[46:47], 2, s[0:1]
	v_lshl_add_u64 v[42:43], s[60:61], 2, v[42:43]
	v_lshl_add_u64 v[46:47], v[46:47], 1, s[22:23]
	s_lshl_b32 s60, s60, 1
	v_lshl_add_u64 v[46:47], v[46:47], 0, s[60:61]
	s_waitcnt vmcnt(7)
	v_lshl_add_u64 v[74:75], v[46:47], 0, s[38:39]
	global_load_dwordx2 v[76:77], v[74:75], off
	v_lshl_add_u64 v[70:71], v[46:47], 0, s[42:43]
	global_load_dwordx4 v[42:45], v[42:43], off
	v_lshl_add_u64 v[66:67], v[46:47], 0, s[46:47]
	global_load_dwordx2 v[72:73], v[70:71], off
	global_load_dwordx2 v[68:69], v[66:67], off
	v_lshl_add_u64 v[62:63], v[46:47], 0, s[50:51]
	global_load_dwordx2 v[64:65], v[62:63], off
	v_lshl_add_u64 v[58:59], v[46:47], 0, s[54:55]
	global_load_dwordx2 v[60:61], v[58:59], off
	v_lshl_add_u64 v[54:55], v[46:47], 0, s[58:59]
	global_load_dwordx2 v[56:57], v[54:55], off
	v_lshl_add_u64 v[50:51], v[46:47], 0, s[64:65]
	global_load_dwordx2 v[52:53], v[50:51], off
	v_lshl_add_u64 v[46:47], v[46:47], 0, s[68:69]
	global_load_dwordx2 v[48:49], v[46:47], off
	v_mov_b32_e32 v1, s93
	s_waitcnt vmcnt(15)
	ds_read_b32 v78, v1 offset:14336
	s_nop 1
	v_permlane32_swap_b32 v122, v126
	s_nop 1
	v_permlane32_swap_b32 v123, v127
	s_nop 1
	v_permlane32_swap_b32 v124, v128
	s_nop 1
	v_permlane32_swap_b32 v125, v129
	s_cmp_eq_u32 s10, 4
	v_pk_add_f32 v[80:81], v[122:123], v[126:127]
	s_waitcnt vmcnt(14)
	v_pk_add_f32 v[90:91], v[124:125], v[128:129]
	s_waitcnt lgkmcnt(0)
	v_pk_mul_f32 v[80:81], v[78:79], v[80:81] op_sel_hi:[0,1]
	v_pk_mul_f32 v[78:79], v[78:79], v[90:91] op_sel_hi:[0,1]
	s_waitcnt vmcnt(8)
	v_lshlrev_b32_e32 v90, 16, v76
	v_and_b32_e32 v91, 0xffff0000, v76
	v_lshlrev_b32_e32 v76, 16, v77
	v_and_b32_e32 v77, 0xffff0000, v77
	s_waitcnt vmcnt(7)
	v_pk_fma_f32 v[76:77], v[44:45], v[78:79], v[76:77]
	v_pk_fma_f32 v[78:79], v[42:43], v[80:81], v[90:91]
	s_nop 0
	v_cvt_pk_bf16_f32 v78, v78, v79
	v_cvt_pk_bf16_f32 v79, v76, v77
	global_store_dwordx2 v[74:75], v[78:79], off
	ds_read_b32 v74, v1 offset:14340
	s_nop 1
	v_permlane32_swap_b32 v114, v118
	s_nop 1
	v_permlane32_swap_b32 v115, v119
	s_nop 1
	v_permlane32_swap_b32 v116, v120
	s_nop 1
	v_permlane32_swap_b32 v117, v121
	s_nop 0
	v_pk_add_f32 v[76:77], v[114:115], v[118:119]
	v_pk_add_f32 v[78:79], v[116:117], v[120:121]
	s_waitcnt lgkmcnt(0)
	v_pk_mul_f32 v[76:77], v[74:75], v[76:77] op_sel_hi:[0,1]
	v_pk_mul_f32 v[74:75], v[74:75], v[78:79] op_sel_hi:[0,1]
	s_waitcnt vmcnt(7)
	v_lshlrev_b32_e32 v78, 16, v72
	v_and_b32_e32 v79, 0xffff0000, v72
	v_lshlrev_b32_e32 v72, 16, v73
	v_and_b32_e32 v73, 0xffff0000, v73
	v_pk_fma_f32 v[72:73], v[44:45], v[74:75], v[72:73]
	v_pk_fma_f32 v[74:75], v[42:43], v[76:77], v[78:79]
	s_nop 0
	v_cvt_pk_bf16_f32 v74, v74, v75
	v_cvt_pk_bf16_f32 v75, v72, v73
	global_store_dwordx2 v[70:71], v[74:75], off
	ds_read_b32 v70, v1 offset:14344
	s_nop 1
	v_permlane32_swap_b32 v82, v86
	s_nop 1
	v_permlane32_swap_b32 v83, v87
	s_nop 1
	v_permlane32_swap_b32 v84, v88
	s_nop 1
	v_permlane32_swap_b32 v85, v89
	s_nop 0
	v_pk_add_f32 v[72:73], v[82:83], v[86:87]
	v_pk_add_f32 v[74:75], v[84:85], v[88:89]
	s_waitcnt lgkmcnt(0)
	v_pk_mul_f32 v[72:73], v[70:71], v[72:73] op_sel_hi:[0,1]
	v_pk_mul_f32 v[70:71], v[70:71], v[74:75] op_sel_hi:[0,1]
	s_waitcnt vmcnt(7)
	v_lshlrev_b32_e32 v74, 16, v68
	v_and_b32_e32 v75, 0xffff0000, v68
	v_lshlrev_b32_e32 v68, 16, v69
	v_and_b32_e32 v69, 0xffff0000, v69
	v_pk_fma_f32 v[68:69], v[44:45], v[70:71], v[68:69]
	v_pk_fma_f32 v[70:71], v[42:43], v[72:73], v[74:75]
	s_nop 0
	v_cvt_pk_bf16_f32 v70, v70, v71
	v_cvt_pk_bf16_f32 v71, v68, v69
	global_store_dwordx2 v[66:67], v[70:71], off
	ds_read_b32 v66, v1 offset:14348
	s_nop 1
	v_permlane32_swap_b32 v34, v38
	s_nop 1
	v_permlane32_swap_b32 v35, v39
	s_nop 1
	v_permlane32_swap_b32 v36, v40
	s_nop 1
	v_permlane32_swap_b32 v37, v41
	s_nop 0
	v_pk_add_f32 v[34:35], v[34:35], v[38:39]
	s_waitcnt vmcnt(7)
	v_lshlrev_b32_e32 v38, 16, v64
	s_waitcnt lgkmcnt(0)
	v_pk_mul_f32 v[34:35], v[66:67], v[34:35] op_sel_hi:[0,1]
	v_and_b32_e32 v39, 0xffff0000, v64
	v_pk_add_f32 v[36:37], v[36:37], v[40:41]
	v_pk_fma_f32 v[34:35], v[42:43], v[34:35], v[38:39]
	v_pk_mul_f32 v[36:37], v[66:67], v[36:37] op_sel_hi:[0,1]
	v_lshlrev_b32_e32 v40, 16, v65
	v_and_b32_e32 v41, 0xffff0000, v65
	v_cvt_pk_bf16_f32 v34, v34, v35
	v_pk_fma_f32 v[36:37], v[44:45], v[36:37], v[40:41]
	s_nop 0
	v_cvt_pk_bf16_f32 v35, v36, v37
	global_store_dwordx2 v[62:63], v[34:35], off
	ds_read_b32 v34, v1 offset:14352
	s_nop 1
	v_permlane32_swap_b32 v26, v30
	s_nop 1
	v_permlane32_swap_b32 v27, v31
	s_nop 1
	v_permlane32_swap_b32 v28, v32
	s_nop 1
	v_permlane32_swap_b32 v29, v33
	s_nop 0
	v_pk_add_f32 v[26:27], v[26:27], v[30:31]
	s_waitcnt vmcnt(7)
	v_lshlrev_b32_e32 v30, 16, v60
	s_waitcnt lgkmcnt(0)
	v_pk_mul_f32 v[26:27], v[34:35], v[26:27] op_sel_hi:[0,1]
	v_and_b32_e32 v31, 0xffff0000, v60
	v_pk_add_f32 v[28:29], v[28:29], v[32:33]
	v_pk_fma_f32 v[26:27], v[42:43], v[26:27], v[30:31]
	v_pk_mul_f32 v[28:29], v[34:35], v[28:29] op_sel_hi:[0,1]
	v_lshlrev_b32_e32 v32, 16, v61
	v_and_b32_e32 v33, 0xffff0000, v61
	v_cvt_pk_bf16_f32 v26, v26, v27
	v_pk_fma_f32 v[28:29], v[44:45], v[28:29], v[32:33]
	s_nop 0
	v_cvt_pk_bf16_f32 v27, v28, v29
	global_store_dwordx2 v[58:59], v[26:27], off
	ds_read_b32 v26, v1 offset:14356
	s_nop 1
	v_permlane32_swap_b32 v18, v22
	s_nop 1
	v_permlane32_swap_b32 v19, v23
	s_nop 1
	v_permlane32_swap_b32 v20, v24
	s_nop 1
	v_permlane32_swap_b32 v21, v25
	s_nop 0
	v_pk_add_f32 v[18:19], v[18:19], v[22:23]
	s_waitcnt vmcnt(7)
	v_lshlrev_b32_e32 v22, 16, v56
	s_waitcnt lgkmcnt(0)
	v_pk_mul_f32 v[18:19], v[26:27], v[18:19] op_sel_hi:[0,1]
	v_and_b32_e32 v23, 0xffff0000, v56
	v_pk_add_f32 v[20:21], v[20:21], v[24:25]
	v_pk_fma_f32 v[18:19], v[42:43], v[18:19], v[22:23]
	v_pk_mul_f32 v[20:21], v[26:27], v[20:21] op_sel_hi:[0,1]
	v_lshlrev_b32_e32 v24, 16, v57
	v_and_b32_e32 v25, 0xffff0000, v57
	v_cvt_pk_bf16_f32 v18, v18, v19
	v_pk_fma_f32 v[20:21], v[44:45], v[20:21], v[24:25]
	s_nop 0
	v_cvt_pk_bf16_f32 v19, v20, v21
	global_store_dwordx2 v[54:55], v[18:19], off
	ds_read_b32 v18, v1 offset:14360
	s_nop 1
	v_permlane32_swap_b32 v10, v14
	s_nop 1
	v_permlane32_swap_b32 v11, v15
	s_nop 1
	v_permlane32_swap_b32 v12, v16
	s_nop 1
	v_permlane32_swap_b32 v13, v17
	s_nop 0
	v_pk_add_f32 v[10:11], v[10:11], v[14:15]
	s_waitcnt vmcnt(7)
	v_lshlrev_b32_e32 v14, 16, v52
	s_waitcnt lgkmcnt(0)
	v_pk_mul_f32 v[10:11], v[18:19], v[10:11] op_sel_hi:[0,1]
	v_and_b32_e32 v15, 0xffff0000, v52
	v_pk_add_f32 v[12:13], v[12:13], v[16:17]
	v_pk_fma_f32 v[10:11], v[42:43], v[10:11], v[14:15]
	v_pk_mul_f32 v[12:13], v[18:19], v[12:13] op_sel_hi:[0,1]
	v_lshlrev_b32_e32 v16, 16, v53
	v_and_b32_e32 v17, 0xffff0000, v53
	v_cvt_pk_bf16_f32 v10, v10, v11
	v_pk_fma_f32 v[12:13], v[44:45], v[12:13], v[16:17]
	s_nop 0
	v_cvt_pk_bf16_f32 v11, v12, v13
	global_store_dwordx2 v[50:51], v[10:11], off
	ds_read_b32 v10, v1 offset:14364
	s_nop 1
	v_permlane32_swap_b32 v2, v6
	s_nop 1
	v_permlane32_swap_b32 v3, v7
	s_nop 1
	v_permlane32_swap_b32 v4, v8
	s_nop 1
	v_permlane32_swap_b32 v5, v9
	s_nop 0
	v_pk_add_f32 v[2:3], v[2:3], v[6:7]
	v_pk_add_f32 v[4:5], v[4:5], v[8:9]
	s_waitcnt lgkmcnt(0)
	v_pk_mul_f32 v[2:3], v[10:11], v[2:3] op_sel_hi:[0,1]
	s_waitcnt vmcnt(7)
	v_lshlrev_b32_e32 v6, 16, v48
	v_and_b32_e32 v7, 0xffff0000, v48
	v_pk_mul_f32 v[4:5], v[10:11], v[4:5] op_sel_hi:[0,1]
	v_lshlrev_b32_e32 v8, 16, v49
	v_and_b32_e32 v9, 0xffff0000, v49
	v_pk_fma_f32 v[2:3], v[42:43], v[2:3], v[6:7]
	v_pk_fma_f32 v[4:5], v[44:45], v[4:5], v[8:9]
	v_cvt_pk_bf16_f32 v2, v2, v3
	s_nop 0
	v_cvt_pk_bf16_f32 v3, v4, v5
	global_store_dwordx2 v[46:47], v[2:3], off
	s_cbranch_scc0 .LBB0_109
	v_mov_b32_e32 v1, v176
	s_add_i32 s0, s11, 3
	s_waitcnt vmcnt(0)
	s_mul_hi_u32 s1, s0, 0x6000
	v_lshlrev_b32_e32 v2, 4, v1
	v_ashrrev_i32_e32 v3, 2, v1
	s_mulk_i32 s0, 0x6000
	v_readlane_b32 s10, v254, 29
	v_and_b32_e32 v2, 0xf0, v2
	v_and_b32_e32 v3, -8, v3
	s_add_u32 s0, s10, s0
	v_readlane_b32 s10, v254, 30
	v_add_u32_e32 v2, v2, v3
	v_lshrrev_b32_e32 v1, 2, v1
	s_addc_u32 s1, s10, s1
	v_readlane_b32 s10, v254, 25
	v_and_or_b32 v34, v1, 4, v2
	v_readlane_b32 s11, v254, 26
	v_ashrrev_i32_e32 v35, 31, v34
	s_mov_b64 s[12:13], -1
	s_and_b64 vcc, exec, s[10:11]
	s_cbranch_vccz .LBB0_114
	v_mov_b32_e32 v1, 0xd0
	v_readlane_b32 s12, v254, 23
	v_add_u32_e32 v1, 0, v1
	v_add_u32_e32 v1, 0x20200, v1
	ds_read_b32 v2, v1
	ds_read_b32 v1, v1 offset:4
	v_readlane_b32 s13, v254, 24
	s_add_u32 s12, s12, 0
	s_waitcnt lgkmcnt(1)
	v_readfirstlane_b32 s10, v2
	s_waitcnt lgkmcnt(0)
	v_readfirstlane_b32 s11, v1
	s_addc_u32 s11, s13, s11
	s_add_u32 s10, s12, s10
	s_addc_u32 s11, s11, 0
	v_lshl_add_u64 v[2:3], v[34:35], 2, s[10:11]
	global_load_dwordx4 v[2:5], v[2:3], off
	s_mov_b64 s[12:13], 0
